# GEMM K-loops: incoming half issues its first 4 MFMAs before the hand-over barrier
# speedup vs baseline: 1.0030x; 1.0030x over previous
.LBB0_93:
	ds_read_b128 v[152:155], v146
	ds_read_b128 v[156:159], v146 offset:1024
	ds_read_b128 v[160:163], v146 offset:2048
	ds_read_b128 v[164:167], v146 offset:3072
	ds_read_b128 v[172:175], v147
	ds_read_b128 v[176:179], v147 offset:1024
	ds_read_b128 v[180:183], v147 offset:2048
	ds_read_b128 v[184:187], v147 offset:3072
	s_add_u32 s16, s12, s14
	s_addc_u32 s17, s13, s15
	s_add_u32 s16, s16, 0x9800100
	s_addc_u32 s17, s17, 0
	s_add_u32 s48, s26, s14
	s_addc_u32 s49, s27, s15
	s_cmpk_eq_i32 s14, 0x300
	s_cselect_b32 s17, s7, s17
	s_cselect_b32 s16, s6, s16
	s_cselect_b32 s49, s5, s49
	s_cselect_b32 s48, s4, s48
	s_mov_b32 m0, s29
	v_lshl_add_u64 v[168:169], v[140:141], 0, s[14:15]
	ds_read_b128 v[188:191], v148
	ds_read_b128 v[192:195], v148 offset:1024
	ds_read_b128 v[196:199], v148 offset:2048
	ds_read_b128 v[200:203], v148 offset:3072
	ds_read_b128 v[204:207], v148 offset:4096
	ds_read_b128 v[208:211], v148 offset:5120
	ds_read_b128 v[212:215], v148 offset:6144
	ds_read_b128 v[216:219], v148 offset:7168
	global_load_lds_dwordx4 v[168:169], off
	v_lshl_add_u64 v[168:169], v[142:143], 0, s[14:15]
	s_mov_b32 m0, s30
	s_nop 0
	global_load_lds_dwordx4 v[168:169], off
	s_waitcnt vmcnt(8)
	s_waitcnt lgkmcnt(0)
	v_mfma_f32_16x16x32_f16 v[124:127], v[152:155], v[188:191], v[124:127]
	v_mfma_f32_16x16x32_f16 v[120:123], v[160:163], v[188:191], v[120:123]
	v_mfma_f32_16x16x32_f16 v[112:115], v[152:155], v[196:199], v[112:115]
	v_mfma_f32_16x16x32_f16 v[104:107], v[160:163], v[196:199], v[104:107]
	s_barrier
	s_setprio 1
	s_waitcnt lgkmcnt(0)
	v_mfma_f32_16x16x32_f16 v[96:99], v[152:155], v[204:207], v[96:99]
	v_mfma_f32_16x16x32_f16 v[88:91], v[160:163], v[204:207], v[88:91]
	v_mfma_f32_16x16x32_f16 v[80:83], v[152:155], v[212:215], v[80:83]
	v_mfma_f32_16x16x32_f16 v[72:75], v[160:163], v[212:215], v[72:75]
	v_mfma_f32_16x16x32_f16 v[124:127], v[156:159], v[192:195], v[124:127]
	v_mfma_f32_16x16x32_f16 v[120:123], v[164:167], v[192:195], v[120:123]
	v_mfma_f32_16x16x32_f16 v[112:115], v[156:159], v[200:203], v[112:115]
	v_mfma_f32_16x16x32_f16 v[104:107], v[164:167], v[200:203], v[104:107]
	v_mfma_f32_16x16x32_f16 v[96:99], v[156:159], v[208:211], v[96:99]
	v_mfma_f32_16x16x32_f16 v[88:91], v[164:167], v[208:211], v[88:91]
	v_mfma_f32_16x16x32_f16 v[80:83], v[156:159], v[216:219], v[80:83]
	v_mfma_f32_16x16x32_f16 v[72:75], v[164:167], v[216:219], v[72:75]
	s_setprio 0
	s_setprio 1
	v_mfma_f32_16x16x32_f16 v[116:119], v[172:175], v[188:191], v[116:119]
	v_mfma_f32_16x16x32_f16 v[108:111], v[180:183], v[188:191], v[108:111]
	v_mfma_f32_16x16x32_f16 v[100:103], v[172:175], v[196:199], v[100:103]
	v_mfma_f32_16x16x32_f16 v[92:95], v[180:183], v[196:199], v[92:95]
	v_mfma_f32_16x16x32_f16 v[84:87], v[172:175], v[204:207], v[84:87]
	v_mfma_f32_16x16x32_f16 v[76:79], v[180:183], v[204:207], v[76:79]
	v_mfma_f32_16x16x32_f16 v[68:71], v[172:175], v[212:215], v[68:71]
	v_mfma_f32_16x16x32_f16 v[64:67], v[180:183], v[212:215], v[64:67]
	v_mfma_f32_16x16x32_f16 v[116:119], v[176:179], v[192:195], v[116:119]
	v_mfma_f32_16x16x32_f16 v[108:111], v[184:187], v[192:195], v[108:111]
	v_mfma_f32_16x16x32_f16 v[100:103], v[176:179], v[200:203], v[100:103]
	v_mfma_f32_16x16x32_f16 v[92:95], v[184:187], v[200:203], v[92:95]
	v_mfma_f32_16x16x32_f16 v[84:87], v[176:179], v[208:211], v[84:87]
	v_mfma_f32_16x16x32_f16 v[76:79], v[184:187], v[208:211], v[76:79]
	v_mfma_f32_16x16x32_f16 v[68:71], v[176:179], v[216:219], v[68:71]
	v_mfma_f32_16x16x32_f16 v[64:67], v[184:187], v[216:219], v[64:67]
	s_setprio 0
	s_barrier
	s_mov_b32 m0, s31
	v_lshl_add_u64 v[168:169], s[48:49], 0, v[134:135]
	ds_read_b128 v[188:191], v148 offset:16384
	ds_read_b128 v[192:195], v148 offset:17408
	ds_read_b128 v[196:199], v148 offset:18432
	ds_read_b128 v[200:203], v148 offset:19456
	ds_read_b128 v[204:207], v148 offset:20480
	ds_read_b128 v[208:211], v148 offset:21504
	ds_read_b128 v[212:215], v148 offset:22528
	ds_read_b128 v[216:219], v148 offset:23552
	global_load_lds_dwordx4 v[168:169], off
	v_lshl_add_u64 v[220:221], s[48:49], 0, v[128:129]
	s_mov_b32 m0, s33
	v_lshl_add_u64 v[222:223], s[48:49], 0, v[136:137]
	global_load_lds_dwordx4 v[220:221], off
	s_mov_b32 m0, s34
	v_lshl_add_u64 v[224:225], s[48:49], 0, v[130:131]
	global_load_lds_dwordx4 v[222:223], off
	s_mov_b32 m0, s35
	v_lshl_add_u64 v[226:227], s[16:17], 0, v[138:139]
	global_load_lds_dwordx4 v[224:225], off
	s_mov_b32 m0, s1
	v_lshl_add_u64 v[228:229], s[16:17], 0, v[132:133]
	global_load_lds_dwordx4 v[226:227], off
	s_mov_b32 m0, s3
	s_nop 0
	global_load_lds_dwordx4 v[228:229], off
	s_waitcnt vmcnt(8)
	s_waitcnt lgkmcnt(0)
	v_mfma_f32_16x16x32_f16 v[60:63], v[152:155], v[188:191], v[60:63]
	v_mfma_f32_16x16x32_f16 v[56:59], v[160:163], v[188:191], v[56:59]
	v_mfma_f32_16x16x32_f16 v[52:55], v[152:155], v[196:199], v[52:55]
	v_mfma_f32_16x16x32_f16 v[44:47], v[160:163], v[196:199], v[44:47]
	s_barrier
	s_setprio 1
	s_waitcnt lgkmcnt(0)
	v_mfma_f32_16x16x32_f16 v[36:39], v[152:155], v[204:207], v[36:39]
	v_mfma_f32_16x16x32_f16 v[28:31], v[160:163], v[204:207], v[28:31]
	v_mfma_f32_16x16x32_f16 v[20:23], v[152:155], v[212:215], v[20:23]
	v_mfma_f32_16x16x32_f16 v[12:15], v[160:163], v[212:215], v[12:15]
	v_mfma_f32_16x16x32_f16 v[60:63], v[156:159], v[192:195], v[60:63]
	v_mfma_f32_16x16x32_f16 v[56:59], v[164:167], v[192:195], v[56:59]
	v_mfma_f32_16x16x32_f16 v[52:55], v[156:159], v[200:203], v[52:55]
	v_mfma_f32_16x16x32_f16 v[44:47], v[164:167], v[200:203], v[44:47]
	v_mfma_f32_16x16x32_f16 v[36:39], v[156:159], v[208:211], v[36:39]
	v_mfma_f32_16x16x32_f16 v[28:31], v[164:167], v[208:211], v[28:31]
	v_mfma_f32_16x16x32_f16 v[20:23], v[156:159], v[216:219], v[20:23]
	v_mfma_f32_16x16x32_f16 v[12:15], v[164:167], v[216:219], v[12:15]
	s_setprio 0
	s_setprio 1
	v_mfma_f32_16x16x32_f16 v[48:51], v[172:175], v[188:191], v[48:51]
	v_mfma_f32_16x16x32_f16 v[40:43], v[180:183], v[188:191], v[40:43]
	v_mfma_f32_16x16x32_f16 v[32:35], v[172:175], v[196:199], v[32:35]
	v_mfma_f32_16x16x32_f16 v[24:27], v[180:183], v[196:199], v[24:27]
	v_mfma_f32_16x16x32_f16 v[16:19], v[172:175], v[204:207], v[16:19]
	v_mfma_f32_16x16x32_f16 v[8:11], v[180:183], v[204:207], v[8:11]
	v_mfma_f32_16x16x32_f16 v[4:7], v[172:175], v[212:215], v[4:7]
	v_mfma_f32_16x16x32_f16 v[0:3], v[180:183], v[212:215], v[0:3]
	v_mfma_f32_16x16x32_f16 v[48:51], v[176:179], v[192:195], v[48:51]
	v_mfma_f32_16x16x32_f16 v[40:43], v[184:187], v[192:195], v[40:43]
	v_mfma_f32_16x16x32_f16 v[32:35], v[176:179], v[200:203], v[32:35]
	v_mfma_f32_16x16x32_f16 v[24:27], v[184:187], v[200:203], v[24:27]
	v_mfma_f32_16x16x32_f16 v[16:19], v[176:179], v[208:211], v[16:19]
	v_mfma_f32_16x16x32_f16 v[8:11], v[184:187], v[208:211], v[8:11]
	v_mfma_f32_16x16x32_f16 v[4:7], v[176:179], v[216:219], v[4:7]
	v_mfma_f32_16x16x32_f16 v[0:3], v[184:187], v[216:219], v[0:3]
	s_setprio 0
	s_barrier
	ds_read_b128 v[152:155], v149
	ds_read_b128 v[156:159], v149 offset:1024
	ds_read_b128 v[160:163], v149 offset:2048
	ds_read_b128 v[164:167], v149 offset:3072
	ds_read_b128 v[172:175], v150
	ds_read_b128 v[176:179], v150 offset:1024
	ds_read_b128 v[180:183], v150 offset:2048
	ds_read_b128 v[184:187], v150 offset:3072
	s_add_u32 s16, s16, 0x20000
	s_addc_u32 s17, s17, 0
	s_mov_b32 m0, s21
	v_lshl_add_u64 v[230:231], s[16:17], 0, v[138:139]
	ds_read_b128 v[188:191], v148 offset:32768
	ds_read_b128 v[192:195], v148 offset:33792
	ds_read_b128 v[196:199], v148 offset:34816
	ds_read_b128 v[200:203], v148 offset:35840
	ds_read_b128 v[204:207], v148 offset:36864
	ds_read_b128 v[208:211], v148 offset:37888
	ds_read_b128 v[212:215], v148 offset:38912
	ds_read_b128 v[216:219], v148 offset:39936
	global_load_lds_dwordx4 v[230:231], off
	v_lshl_add_u64 v[230:231], s[16:17], 0, v[132:133]
	s_mov_b32 m0, s22
	s_nop 0
	global_load_lds_dwordx4 v[230:231], off
	s_waitcnt vmcnt(8)
	s_waitcnt lgkmcnt(0)
	v_mfma_f32_16x16x32_f16 v[124:127], v[152:155], v[188:191], v[124:127]
	v_mfma_f32_16x16x32_f16 v[120:123], v[160:163], v[188:191], v[120:123]
	v_mfma_f32_16x16x32_f16 v[112:115], v[152:155], v[196:199], v[112:115]
	v_mfma_f32_16x16x32_f16 v[104:107], v[160:163], v[196:199], v[104:107]
	s_barrier
	s_setprio 1
	s_waitcnt lgkmcnt(0)
	v_mfma_f32_16x16x32_f16 v[96:99], v[152:155], v[204:207], v[96:99]
	v_mfma_f32_16x16x32_f16 v[88:91], v[160:163], v[204:207], v[88:91]
	v_mfma_f32_16x16x32_f16 v[80:83], v[152:155], v[212:215], v[80:83]
	v_mfma_f32_16x16x32_f16 v[72:75], v[160:163], v[212:215], v[72:75]
	v_mfma_f32_16x16x32_f16 v[124:127], v[156:159], v[192:195], v[124:127]
	v_mfma_f32_16x16x32_f16 v[120:123], v[164:167], v[192:195], v[120:123]
	v_mfma_f32_16x16x32_f16 v[112:115], v[156:159], v[200:203], v[112:115]
	v_mfma_f32_16x16x32_f16 v[104:107], v[164:167], v[200:203], v[104:107]
	v_mfma_f32_16x16x32_f16 v[96:99], v[156:159], v[208:211], v[96:99]
	v_mfma_f32_16x16x32_f16 v[88:91], v[164:167], v[208:211], v[88:91]
	v_mfma_f32_16x16x32_f16 v[80:83], v[156:159], v[216:219], v[80:83]
	v_mfma_f32_16x16x32_f16 v[72:75], v[164:167], v[216:219], v[72:75]
	s_setprio 0
	s_setprio 1
	v_mfma_f32_16x16x32_f16 v[116:119], v[172:175], v[188:191], v[116:119]
	v_mfma_f32_16x16x32_f16 v[108:111], v[180:183], v[188:191], v[108:111]
	v_mfma_f32_16x16x32_f16 v[100:103], v[172:175], v[196:199], v[100:103]
	v_mfma_f32_16x16x32_f16 v[92:95], v[180:183], v[196:199], v[92:95]
	v_mfma_f32_16x16x32_f16 v[84:87], v[172:175], v[204:207], v[84:87]
	v_mfma_f32_16x16x32_f16 v[76:79], v[180:183], v[204:207], v[76:79]
	v_mfma_f32_16x16x32_f16 v[68:71], v[172:175], v[212:215], v[68:71]
	v_mfma_f32_16x16x32_f16 v[64:67], v[180:183], v[212:215], v[64:67]
	v_mfma_f32_16x16x32_f16 v[116:119], v[176:179], v[192:195], v[116:119]
	v_mfma_f32_16x16x32_f16 v[108:111], v[184:187], v[192:195], v[108:111]
	v_mfma_f32_16x16x32_f16 v[100:103], v[176:179], v[200:203], v[100:103]
	v_mfma_f32_16x16x32_f16 v[92:95], v[184:187], v[200:203], v[92:95]
	v_mfma_f32_16x16x32_f16 v[84:87], v[176:179], v[208:211], v[84:87]
	v_mfma_f32_16x16x32_f16 v[76:79], v[184:187], v[208:211], v[76:79]
	v_mfma_f32_16x16x32_f16 v[68:71], v[176:179], v[216:219], v[68:71]
	v_mfma_f32_16x16x32_f16 v[64:67], v[184:187], v[216:219], v[64:67]
	s_setprio 0
	s_barrier
	s_mov_b32 m0, s44
	v_lshl_add_u64 v[168:169], v[168:169], 0, s[8:9]
	ds_read_b128 v[188:191], v148 offset:49152
	ds_read_b128 v[192:195], v148 offset:50176
	ds_read_b128 v[196:199], v148 offset:51200
	ds_read_b128 v[200:203], v148 offset:52224
	ds_read_b128 v[204:207], v148 offset:53248
	ds_read_b128 v[208:211], v148 offset:54272
	ds_read_b128 v[212:215], v148 offset:55296
	ds_read_b128 v[216:219], v148 offset:56320
	global_load_lds_dwordx4 v[168:169], off
	v_lshl_add_u64 v[168:169], v[220:221], 0, s[8:9]
	s_mov_b32 m0, s45
	s_nop 0
	global_load_lds_dwordx4 v[168:169], off
	v_lshl_add_u64 v[168:169], v[222:223], 0, s[8:9]
	s_mov_b32 m0, s46
	s_nop 0
	global_load_lds_dwordx4 v[168:169], off
	v_lshl_add_u64 v[168:169], v[224:225], 0, s[8:9]
	s_mov_b32 m0, s47
	s_nop 0
	global_load_lds_dwordx4 v[168:169], off
	v_lshl_add_u64 v[168:169], v[226:227], 0, s[8:9]
	s_mov_b32 m0, s24
	s_nop 0
	global_load_lds_dwordx4 v[168:169], off
	v_lshl_add_u64 v[168:169], v[228:229], 0, s[8:9]
	s_mov_b32 m0, s25
	s_nop 0
	global_load_lds_dwordx4 v[168:169], off
	s_waitcnt vmcnt(8)
	s_waitcnt lgkmcnt(0)
	v_mfma_f32_16x16x32_f16 v[60:63], v[152:155], v[188:191], v[60:63]
	v_mfma_f32_16x16x32_f16 v[56:59], v[160:163], v[188:191], v[56:59]
	v_mfma_f32_16x16x32_f16 v[52:55], v[152:155], v[196:199], v[52:55]
	v_mfma_f32_16x16x32_f16 v[44:47], v[160:163], v[196:199], v[44:47]
	s_barrier
	s_setprio 1
	s_waitcnt lgkmcnt(0)
	v_mfma_f32_16x16x32_f16 v[36:39], v[152:155], v[204:207], v[36:39]
	v_mfma_f32_16x16x32_f16 v[28:31], v[160:163], v[204:207], v[28:31]
	v_mfma_f32_16x16x32_f16 v[20:23], v[152:155], v[212:215], v[20:23]
	v_mfma_f32_16x16x32_f16 v[12:15], v[160:163], v[212:215], v[12:15]
	v_mfma_f32_16x16x32_f16 v[60:63], v[156:159], v[192:195], v[60:63]
	v_mfma_f32_16x16x32_f16 v[56:59], v[164:167], v[192:195], v[56:59]
	v_mfma_f32_16x16x32_f16 v[52:55], v[156:159], v[200:203], v[52:55]
	v_mfma_f32_16x16x32_f16 v[44:47], v[164:167], v[200:203], v[44:47]
	v_mfma_f32_16x16x32_f16 v[36:39], v[156:159], v[208:211], v[36:39]
	v_mfma_f32_16x16x32_f16 v[28:31], v[164:167], v[208:211], v[28:31]
	v_mfma_f32_16x16x32_f16 v[20:23], v[156:159], v[216:219], v[20:23]
	v_mfma_f32_16x16x32_f16 v[12:15], v[164:167], v[216:219], v[12:15]
	s_setprio 0
	s_setprio 1
	v_mfma_f32_16x16x32_f16 v[48:51], v[172:175], v[188:191], v[48:51]
	v_mfma_f32_16x16x32_f16 v[40:43], v[180:183], v[188:191], v[40:43]
	v_mfma_f32_16x16x32_f16 v[32:35], v[172:175], v[196:199], v[32:35]
	v_mfma_f32_16x16x32_f16 v[24:27], v[180:183], v[196:199], v[24:27]
	v_mfma_f32_16x16x32_f16 v[16:19], v[172:175], v[204:207], v[16:19]
	v_mfma_f32_16x16x32_f16 v[8:11], v[180:183], v[204:207], v[8:11]
	v_mfma_f32_16x16x32_f16 v[4:7], v[172:175], v[212:215], v[4:7]
	v_mfma_f32_16x16x32_f16 v[0:3], v[180:183], v[212:215], v[0:3]
	v_mfma_f32_16x16x32_f16 v[48:51], v[176:179], v[192:195], v[48:51]
	v_mfma_f32_16x16x32_f16 v[40:43], v[184:187], v[192:195], v[40:43]
	v_mfma_f32_16x16x32_f16 v[32:35], v[176:179], v[200:203], v[32:35]
	v_mfma_f32_16x16x32_f16 v[24:27], v[184:187], v[200:203], v[24:27]
	v_mfma_f32_16x16x32_f16 v[16:19], v[176:179], v[208:211], v[16:19]
	v_mfma_f32_16x16x32_f16 v[8:11], v[184:187], v[208:211], v[8:11]
	v_mfma_f32_16x16x32_f16 v[4:7], v[176:179], v[216:219], v[4:7]
	v_mfma_f32_16x16x32_f16 v[0:3], v[184:187], v[216:219], v[0:3]
	s_setprio 0
	s_barrier
	s_add_i32 s28, s28, 2
	s_add_u32 s14, s14, 0x100
	s_addc_u32 s15, s15, 0
	s_cmp_gt_u32 s28, 5
	s_cbranch_scc0 .LBB0_93
	s_cmpk_lt_u32 s20, 0x100
	s_cbranch_scc0 .LBB0_96
	s_barrier

.LBB0_202:
	s_add_u32 s2, s6, 0xfffc0080
	s_addc_u32 s3, s7, -1
	s_add_i32 s66, 0, 0x10000
	s_cmp_eq_u32 s89, 12
	s_cselect_b32 s57, s20, s3
	s_cselect_b32 s56, s21, s2
	v_add_u32_e32 v148, s66, v151
	s_cselect_b32 s91, s49, s88
	s_cselect_b32 s90, s51, s62
	s_add_i32 s2, 0, 0x14000
	ds_read_b128 v[144:147], v148
	ds_read_b128 v[164:167], v148 offset:1024
	ds_read_b128 v[176:179], v148 offset:2048
	ds_read_b128 v[180:183], v148 offset:3072
	v_add_u32_e32 v148, s2, v151
	ds_read_b128 v[184:187], v148
	ds_read_b128 v[188:191], v148 offset:1024
	ds_read_b128 v[192:195], v148 offset:2048
	ds_read_b128 v[196:199], v148 offset:3072
	v_lshl_add_u64 v[148:149], s[6:7], 0, v[140:141]
	s_add_i32 m0, s17, 0xc000
	ds_read_b128 v[200:203], v153
	ds_read_b128 v[204:207], v153 offset:1024
	ds_read_b128 v[208:211], v153 offset:2048
	ds_read_b128 v[212:215], v153 offset:3072
	ds_read_b128 v[216:219], v153 offset:4096
	ds_read_b128 v[220:223], v153 offset:5120
	ds_read_b128 v[224:227], v153 offset:6144
	ds_read_b128 v[228:231], v153 offset:7168
	global_load_lds_dwordx4 v[148:149], off
	v_lshl_add_u64 v[148:149], s[6:7], 0, v[142:143]
	s_add_i32 m0, s17, 0xe000
	s_nop 0
	global_load_lds_dwordx4 v[148:149], off
	s_waitcnt vmcnt(8)
	s_waitcnt lgkmcnt(0)
	v_mfma_f32_16x16x32_f16 v[128:131], v[144:147], v[200:203], v[128:131]
	v_mfma_f32_16x16x32_f16 v[124:127], v[176:179], v[200:203], v[124:127]
	v_mfma_f32_16x16x32_f16 v[112:115], v[144:147], v[208:211], v[112:115]
	v_mfma_f32_16x16x32_f16 v[108:111], v[176:179], v[208:211], v[108:111]
	s_barrier
	s_setprio 1
	s_waitcnt lgkmcnt(0)
	v_mfma_f32_16x16x32_f16 v[96:99], v[144:147], v[216:219], v[96:99]
	v_mfma_f32_16x16x32_f16 v[92:95], v[176:179], v[216:219], v[92:95]
	v_mfma_f32_16x16x32_f16 v[80:83], v[144:147], v[224:227], v[80:83]
	v_mfma_f32_16x16x32_f16 v[76:79], v[176:179], v[224:227], v[76:79]
	v_mfma_f32_16x16x32_f16 v[128:131], v[164:167], v[204:207], v[128:131]
	v_mfma_f32_16x16x32_f16 v[124:127], v[180:183], v[204:207], v[124:127]
	v_mfma_f32_16x16x32_f16 v[112:115], v[164:167], v[212:215], v[112:115]
	v_mfma_f32_16x16x32_f16 v[108:111], v[180:183], v[212:215], v[108:111]
	v_mfma_f32_16x16x32_f16 v[96:99], v[164:167], v[220:223], v[96:99]
	v_mfma_f32_16x16x32_f16 v[92:95], v[180:183], v[220:223], v[92:95]
	v_mfma_f32_16x16x32_f16 v[80:83], v[164:167], v[228:231], v[80:83]
	v_mfma_f32_16x16x32_f16 v[76:79], v[180:183], v[228:231], v[76:79]
	s_setprio 0
	s_setprio 1
	v_mfma_f32_16x16x32_f16 v[120:123], v[184:187], v[200:203], v[120:123]
	v_mfma_f32_16x16x32_f16 v[116:119], v[192:195], v[200:203], v[116:119]
	v_mfma_f32_16x16x32_f16 v[104:107], v[184:187], v[208:211], v[104:107]
	v_mfma_f32_16x16x32_f16 v[100:103], v[192:195], v[208:211], v[100:103]
	v_mfma_f32_16x16x32_f16 v[88:91], v[184:187], v[216:219], v[88:91]
	v_mfma_f32_16x16x32_f16 v[84:87], v[192:195], v[216:219], v[84:87]
	v_mfma_f32_16x16x32_f16 v[72:75], v[184:187], v[224:227], v[72:75]
	v_mfma_f32_16x16x32_f16 v[68:71], v[192:195], v[224:227], v[68:71]
	v_mfma_f32_16x16x32_f16 v[120:123], v[188:191], v[204:207], v[120:123]
	v_mfma_f32_16x16x32_f16 v[116:119], v[196:199], v[204:207], v[116:119]
	v_mfma_f32_16x16x32_f16 v[104:107], v[188:191], v[212:215], v[104:107]
	v_mfma_f32_16x16x32_f16 v[100:103], v[196:199], v[212:215], v[100:103]
	v_mfma_f32_16x16x32_f16 v[88:91], v[188:191], v[220:223], v[88:91]
	v_mfma_f32_16x16x32_f16 v[84:87], v[196:199], v[220:223], v[84:87]
	v_mfma_f32_16x16x32_f16 v[72:75], v[188:191], v[228:231], v[72:75]
	v_mfma_f32_16x16x32_f16 v[68:71], v[196:199], v[228:231], v[68:71]
	s_setprio 0
	s_barrier
	s_add_i32 s3, s66, s16
	v_lshl_add_u64 v[148:149], s[90:91], 0, v[2:3]
	s_mov_b32 m0, s3
	ds_read_b128 v[200:203], v153 offset:16384
	ds_read_b128 v[204:207], v153 offset:17408
	ds_read_b128 v[208:211], v153 offset:18432
	ds_read_b128 v[212:215], v153 offset:19456
	ds_read_b128 v[216:219], v153 offset:20480
	ds_read_b128 v[220:223], v153 offset:21504
	ds_read_b128 v[224:227], v153 offset:22528
	ds_read_b128 v[228:231], v153 offset:23552
	global_load_lds_dwordx4 v[148:149], off
	v_lshl_add_u64 v[154:155], s[90:91], 0, v[0:1]
	s_add_i32 m0, s3, 0x2000
	s_add_i32 s2, s2, s16
	global_load_lds_dwordx4 v[154:155], off
	v_lshl_add_u64 v[232:233], s[90:91], 0, v[136:137]
	s_mov_b32 m0, s2
	v_lshl_add_u64 v[234:235], s[90:91], 0, v[132:133]
	global_load_lds_dwordx4 v[232:233], off
	s_add_i32 m0, s2, 0x2000
	v_lshl_add_u64 v[236:237], s[56:57], 0, v[138:139]
	global_load_lds_dwordx4 v[234:235], off
	s_mov_b32 m0, s17
	v_lshl_add_u64 v[238:239], s[56:57], 0, v[134:135]
	global_load_lds_dwordx4 v[236:237], off
	s_mov_b32 m0, s28
	s_nop 0
	global_load_lds_dwordx4 v[238:239], off
	s_waitcnt vmcnt(8)
	s_waitcnt lgkmcnt(0)
	v_mfma_f32_16x16x32_f16 v[64:67], v[144:147], v[200:203], v[64:67]
	v_mfma_f32_16x16x32_f16 v[60:63], v[176:179], v[200:203], v[60:63]
	v_mfma_f32_16x16x32_f16 v[48:51], v[144:147], v[208:211], v[48:51]
	v_mfma_f32_16x16x32_f16 v[44:47], v[176:179], v[208:211], v[44:47]
	s_barrier
	s_setprio 1
	s_waitcnt lgkmcnt(0)
	v_mfma_f32_16x16x32_f16 v[32:35], v[144:147], v[216:219], v[32:35]
	v_mfma_f32_16x16x32_f16 v[28:31], v[176:179], v[216:219], v[28:31]
	v_mfma_f32_16x16x32_f16 v[16:19], v[144:147], v[224:227], v[16:19]
	v_mfma_f32_16x16x32_f16 v[12:15], v[176:179], v[224:227], v[12:15]
	v_mfma_f32_16x16x32_f16 v[64:67], v[164:167], v[204:207], v[64:67]
	v_mfma_f32_16x16x32_f16 v[60:63], v[180:183], v[204:207], v[60:63]
	v_mfma_f32_16x16x32_f16 v[48:51], v[164:167], v[212:215], v[48:51]
	v_mfma_f32_16x16x32_f16 v[44:47], v[180:183], v[212:215], v[44:47]
	v_mfma_f32_16x16x32_f16 v[32:35], v[164:167], v[220:223], v[32:35]
	v_mfma_f32_16x16x32_f16 v[28:31], v[180:183], v[220:223], v[28:31]
	v_mfma_f32_16x16x32_f16 v[16:19], v[164:167], v[228:231], v[16:19]
	v_mfma_f32_16x16x32_f16 v[12:15], v[180:183], v[228:231], v[12:15]
	s_setprio 0
	s_setprio 1
	v_mfma_f32_16x16x32_f16 v[56:59], v[184:187], v[200:203], v[56:59]
	v_mfma_f32_16x16x32_f16 v[52:55], v[192:195], v[200:203], v[52:55]
	v_mfma_f32_16x16x32_f16 v[40:43], v[184:187], v[208:211], v[40:43]
	v_mfma_f32_16x16x32_f16 v[36:39], v[192:195], v[208:211], v[36:39]
	v_mfma_f32_16x16x32_f16 v[24:27], v[184:187], v[216:219], v[24:27]
	v_mfma_f32_16x16x32_f16 v[20:23], v[192:195], v[216:219], v[20:23]
	v_mfma_f32_16x16x32_f16 v[8:11], v[184:187], v[224:227], v[8:11]
	v_mfma_f32_16x16x32_f16 v[4:7], v[192:195], v[224:227], v[4:7]
	v_mfma_f32_16x16x32_f16 v[56:59], v[188:191], v[204:207], v[56:59]
	v_mfma_f32_16x16x32_f16 v[52:55], v[196:199], v[204:207], v[52:55]
	v_mfma_f32_16x16x32_f16 v[40:43], v[188:191], v[212:215], v[40:43]
	v_mfma_f32_16x16x32_f16 v[36:39], v[196:199], v[212:215], v[36:39]
	v_mfma_f32_16x16x32_f16 v[24:27], v[188:191], v[220:223], v[24:27]
	v_mfma_f32_16x16x32_f16 v[20:23], v[196:199], v[220:223], v[20:23]
	v_mfma_f32_16x16x32_f16 v[8:11], v[188:191], v[228:231], v[8:11]
	v_mfma_f32_16x16x32_f16 v[4:7], v[196:199], v[228:231], v[4:7]
	s_setprio 0
	s_barrier
	s_add_i32 s2, 0, 0x18000
	s_add_i32 s3, 0, 0x1c000
	v_add_u32_e32 v180, s2, v151
	v_add_u32_e32 v196, s3, v151
	ds_read_b128 v[144:147], v180
	ds_read_b128 v[164:167], v180 offset:1024
	ds_read_b128 v[176:179], v180 offset:2048
	ds_read_b128 v[180:183], v180 offset:3072
	ds_read_b128 v[184:187], v196
	ds_read_b128 v[188:191], v196 offset:1024
	ds_read_b128 v[192:195], v196 offset:2048
	ds_read_b128 v[196:199], v196 offset:3072
	s_add_u32 s56, s56, 0x40000
	s_addc_u32 s57, s57, 0
	s_mov_b32 m0, s58
	v_lshl_add_u64 v[240:241], s[56:57], 0, v[138:139]
	ds_read_b128 v[200:203], v153 offset:32768
	ds_read_b128 v[204:207], v153 offset:33792
	ds_read_b128 v[208:211], v153 offset:34816
	ds_read_b128 v[212:215], v153 offset:35840
	ds_read_b128 v[216:219], v153 offset:36864
	ds_read_b128 v[220:223], v153 offset:37888
	ds_read_b128 v[224:227], v153 offset:38912
	ds_read_b128 v[228:231], v153 offset:39936
	global_load_lds_dwordx4 v[240:241], off
	v_lshl_add_u64 v[240:241], s[56:57], 0, v[134:135]
	s_mov_b32 m0, s59
	s_nop 0
	global_load_lds_dwordx4 v[240:241], off
	s_waitcnt vmcnt(8)
	s_waitcnt lgkmcnt(0)
	v_mfma_f32_16x16x32_f16 v[128:131], v[144:147], v[200:203], v[128:131]
	v_mfma_f32_16x16x32_f16 v[124:127], v[176:179], v[200:203], v[124:127]
	v_mfma_f32_16x16x32_f16 v[112:115], v[144:147], v[208:211], v[112:115]
	v_mfma_f32_16x16x32_f16 v[108:111], v[176:179], v[208:211], v[108:111]
	s_barrier
	s_setprio 1
	s_waitcnt lgkmcnt(0)
	v_mfma_f32_16x16x32_f16 v[96:99], v[144:147], v[216:219], v[96:99]
	v_mfma_f32_16x16x32_f16 v[92:95], v[176:179], v[216:219], v[92:95]
	v_mfma_f32_16x16x32_f16 v[80:83], v[144:147], v[224:227], v[80:83]
	v_mfma_f32_16x16x32_f16 v[76:79], v[176:179], v[224:227], v[76:79]
	v_mfma_f32_16x16x32_f16 v[128:131], v[164:167], v[204:207], v[128:131]
	v_mfma_f32_16x16x32_f16 v[124:127], v[180:183], v[204:207], v[124:127]
	v_mfma_f32_16x16x32_f16 v[112:115], v[164:167], v[212:215], v[112:115]
	v_mfma_f32_16x16x32_f16 v[108:111], v[180:183], v[212:215], v[108:111]
	v_mfma_f32_16x16x32_f16 v[96:99], v[164:167], v[220:223], v[96:99]
	v_mfma_f32_16x16x32_f16 v[92:95], v[180:183], v[220:223], v[92:95]
	v_mfma_f32_16x16x32_f16 v[80:83], v[164:167], v[228:231], v[80:83]
	v_mfma_f32_16x16x32_f16 v[76:79], v[180:183], v[228:231], v[76:79]
	s_setprio 0
	s_setprio 1
	v_mfma_f32_16x16x32_f16 v[120:123], v[184:187], v[200:203], v[120:123]
	v_mfma_f32_16x16x32_f16 v[116:119], v[192:195], v[200:203], v[116:119]
	v_mfma_f32_16x16x32_f16 v[104:107], v[184:187], v[208:211], v[104:107]
	v_mfma_f32_16x16x32_f16 v[100:103], v[192:195], v[208:211], v[100:103]
	v_mfma_f32_16x16x32_f16 v[88:91], v[184:187], v[216:219], v[88:91]
	v_mfma_f32_16x16x32_f16 v[84:87], v[192:195], v[216:219], v[84:87]
	v_mfma_f32_16x16x32_f16 v[72:75], v[184:187], v[224:227], v[72:75]
	v_mfma_f32_16x16x32_f16 v[68:71], v[192:195], v[224:227], v[68:71]
	v_mfma_f32_16x16x32_f16 v[120:123], v[188:191], v[204:207], v[120:123]
	v_mfma_f32_16x16x32_f16 v[116:119], v[196:199], v[204:207], v[116:119]
	v_mfma_f32_16x16x32_f16 v[104:107], v[188:191], v[212:215], v[104:107]
	v_mfma_f32_16x16x32_f16 v[100:103], v[196:199], v[212:215], v[100:103]
	v_mfma_f32_16x16x32_f16 v[88:91], v[188:191], v[220:223], v[88:91]
	v_mfma_f32_16x16x32_f16 v[84:87], v[196:199], v[220:223], v[84:87]
	v_mfma_f32_16x16x32_f16 v[72:75], v[188:191], v[228:231], v[72:75]
	v_mfma_f32_16x16x32_f16 v[68:71], v[196:199], v[228:231], v[68:71]
	s_setprio 0
	s_barrier
	s_add_i32 s2, s2, s16
	v_lshl_add_u64 v[148:149], v[148:149], 0, s[82:83]
	s_mov_b32 m0, s2
	ds_read_b128 v[200:203], v153 offset:49152
	ds_read_b128 v[204:207], v153 offset:50176
	ds_read_b128 v[208:211], v153 offset:51200
	ds_read_b128 v[212:215], v153 offset:52224
	ds_read_b128 v[216:219], v153 offset:53248
	ds_read_b128 v[220:223], v153 offset:54272
	ds_read_b128 v[224:227], v153 offset:55296
	ds_read_b128 v[228:231], v153 offset:56320
	global_load_lds_dwordx4 v[148:149], off
	v_lshl_add_u64 v[148:149], v[154:155], 0, s[82:83]
	s_add_i32 m0, s2, 0x2000
	s_add_i32 s2, s3, s16
	global_load_lds_dwordx4 v[148:149], off
	v_lshl_add_u64 v[148:149], v[232:233], 0, s[82:83]
	s_mov_b32 m0, s2
	s_nop 0
	global_load_lds_dwordx4 v[148:149], off
	v_lshl_add_u64 v[148:149], v[234:235], 0, s[82:83]
	s_add_i32 m0, s2, 0x2000
	s_nop 0
	global_load_lds_dwordx4 v[148:149], off
	v_lshl_add_u64 v[148:149], v[236:237], 0, s[82:83]
	s_mov_b32 m0, s60
	s_nop 0
	global_load_lds_dwordx4 v[148:149], off
	v_lshl_add_u64 v[148:149], v[238:239], 0, s[82:83]
	s_mov_b32 m0, s61
	s_nop 0
	global_load_lds_dwordx4 v[148:149], off
	s_waitcnt vmcnt(8)
	s_waitcnt lgkmcnt(0)
	v_mfma_f32_16x16x32_f16 v[64:67], v[144:147], v[200:203], v[64:67]
	v_mfma_f32_16x16x32_f16 v[60:63], v[176:179], v[200:203], v[60:63]
	v_mfma_f32_16x16x32_f16 v[48:51], v[144:147], v[208:211], v[48:51]
	v_mfma_f32_16x16x32_f16 v[44:47], v[176:179], v[208:211], v[44:47]
	s_barrier
	s_setprio 1
	s_waitcnt lgkmcnt(0)
	v_mfma_f32_16x16x32_f16 v[32:35], v[144:147], v[216:219], v[32:35]
	v_mfma_f32_16x16x32_f16 v[28:31], v[176:179], v[216:219], v[28:31]
	v_mfma_f32_16x16x32_f16 v[16:19], v[144:147], v[224:227], v[16:19]
	v_mfma_f32_16x16x32_f16 v[12:15], v[176:179], v[224:227], v[12:15]
	v_mfma_f32_16x16x32_f16 v[64:67], v[164:167], v[204:207], v[64:67]
	v_mfma_f32_16x16x32_f16 v[60:63], v[180:183], v[204:207], v[60:63]
	v_mfma_f32_16x16x32_f16 v[48:51], v[164:167], v[212:215], v[48:51]
	v_mfma_f32_16x16x32_f16 v[44:47], v[180:183], v[212:215], v[44:47]
	v_mfma_f32_16x16x32_f16 v[32:35], v[164:167], v[220:223], v[32:35]
	v_mfma_f32_16x16x32_f16 v[28:31], v[180:183], v[220:223], v[28:31]
	v_mfma_f32_16x16x32_f16 v[16:19], v[164:167], v[228:231], v[16:19]
	v_mfma_f32_16x16x32_f16 v[12:15], v[180:183], v[228:231], v[12:15]
	s_setprio 0
	s_setprio 1
	v_mfma_f32_16x16x32_f16 v[56:59], v[184:187], v[200:203], v[56:59]
	v_mfma_f32_16x16x32_f16 v[52:55], v[192:195], v[200:203], v[52:55]
	v_mfma_f32_16x16x32_f16 v[40:43], v[184:187], v[208:211], v[40:43]
	v_mfma_f32_16x16x32_f16 v[36:39], v[192:195], v[208:211], v[36:39]
	v_mfma_f32_16x16x32_f16 v[24:27], v[184:187], v[216:219], v[24:27]
	v_mfma_f32_16x16x32_f16 v[20:23], v[192:195], v[216:219], v[20:23]
	v_mfma_f32_16x16x32_f16 v[8:11], v[184:187], v[224:227], v[8:11]
	v_mfma_f32_16x16x32_f16 v[4:7], v[192:195], v[224:227], v[4:7]
	v_mfma_f32_16x16x32_f16 v[56:59], v[188:191], v[204:207], v[56:59]
	v_mfma_f32_16x16x32_f16 v[52:55], v[196:199], v[204:207], v[52:55]
	v_mfma_f32_16x16x32_f16 v[40:43], v[188:191], v[212:215], v[40:43]
	v_mfma_f32_16x16x32_f16 v[36:39], v[196:199], v[212:215], v[36:39]
	v_mfma_f32_16x16x32_f16 v[24:27], v[188:191], v[220:223], v[24:27]
	v_mfma_f32_16x16x32_f16 v[20:23], v[196:199], v[220:223], v[20:23]
	v_mfma_f32_16x16x32_f16 v[8:11], v[188:191], v[228:231], v[8:11]
	v_mfma_f32_16x16x32_f16 v[4:7], v[196:199], v[228:231], v[4:7]
	s_setprio 0
	s_barrier
	s_add_i32 s89, s89, 2
	s_add_u32 s6, s6, 0x100
	s_addc_u32 s7, s7, 0
	s_add_u32 s62, s62, 0x100
	s_addc_u32 s88, s88, 0
	s_cmp_gt_u32 s89, 13
	s_cbranch_scc0 .LBB0_202
	s_and_b64 vcc, exec, s[46:47]
	s_cbranch_vccz .LBB0_205
	s_barrier

.LBB0_426:
	s_add_u32 s3, s54, s58
	s_addc_u32 s60, s55, s59
	s_add_u32 s3, s3, 0x100
	s_addc_u32 s60, s60, 0
	s_add_u32 s66, s21, s58
	s_addc_u32 s67, s62, s59
	s_add_i32 s85, 0, 0x10000
	s_cmpk_eq_i32 s58, 0xf00
	s_cselect_b32 s61, s53, s60
	s_cselect_b32 s60, vcc_lo, s3
	v_add_u32_e32 v146, s85, v144
	s_cselect_b32 s67, s51, s67
	s_cselect_b32 s66, vcc_hi, s66
	s_add_i32 s3, 0, 0x14000
	ds_read_b128 v[150:153], v146
	ds_read_b128 v[164:167], v146 offset:1024
	ds_read_b128 v[178:181], v146 offset:2048
	ds_read_b128 v[182:185], v146 offset:3072
	v_add_u32_e32 v146, s3, v144
	ds_read_b128 v[186:189], v146
	ds_read_b128 v[190:193], v146 offset:1024
	ds_read_b128 v[194:197], v146 offset:2048
	ds_read_b128 v[198:201], v146 offset:3072
	v_lshl_add_u64 v[146:147], v[140:141], 0, s[58:59]
	s_add_i32 m0, s16, 0xc000
	ds_read_b128 v[202:205], v145
	ds_read_b128 v[206:209], v145 offset:1024
	ds_read_b128 v[210:213], v145 offset:2048
	ds_read_b128 v[214:217], v145 offset:3072
	ds_read_b128 v[218:221], v145 offset:4096
	ds_read_b128 v[222:225], v145 offset:5120
	ds_read_b128 v[226:229], v145 offset:6144
	ds_read_b128 v[230:233], v145 offset:7168
	global_load_lds_dwordx4 v[146:147], off
	v_lshl_add_u64 v[146:147], v[142:143], 0, s[58:59]
	s_add_i32 m0, s16, 0xe000
	s_nop 0
	global_load_lds_dwordx4 v[146:147], off
	s_waitcnt vmcnt(8)
	s_waitcnt lgkmcnt(0)
	v_mfma_f32_16x16x32_bf16 v[28:31], v[150:153], v[202:205], v[28:31]
	v_mfma_f32_16x16x32_bf16 v[20:23], v[178:181], v[202:205], v[20:23]
	v_mfma_f32_16x16x32_bf16 v[32:35], v[150:153], v[210:213], v[32:35]
	v_mfma_f32_16x16x32_bf16 v[24:27], v[178:181], v[210:213], v[24:27]
	s_barrier
	s_setprio 1
	s_waitcnt lgkmcnt(0)
	v_mfma_f32_16x16x32_bf16 v[60:63], v[150:153], v[218:221], v[60:63]
	v_mfma_f32_16x16x32_bf16 v[52:55], v[178:181], v[218:221], v[52:55]
	v_mfma_f32_16x16x32_bf16 v[64:67], v[150:153], v[226:229], v[64:67]
	v_mfma_f32_16x16x32_bf16 v[56:59], v[178:181], v[226:229], v[56:59]
	v_mfma_f32_16x16x32_bf16 v[28:31], v[164:167], v[206:209], v[28:31]
	v_mfma_f32_16x16x32_bf16 v[20:23], v[182:185], v[206:209], v[20:23]
	v_mfma_f32_16x16x32_bf16 v[32:35], v[164:167], v[214:217], v[32:35]
	v_mfma_f32_16x16x32_bf16 v[24:27], v[182:185], v[214:217], v[24:27]
	v_mfma_f32_16x16x32_bf16 v[60:63], v[164:167], v[222:225], v[60:63]
	v_mfma_f32_16x16x32_bf16 v[52:55], v[182:185], v[222:225], v[52:55]
	v_mfma_f32_16x16x32_bf16 v[64:67], v[164:167], v[230:233], v[64:67]
	v_mfma_f32_16x16x32_bf16 v[56:59], v[182:185], v[230:233], v[56:59]
	s_setprio 0
	s_setprio 1
	v_mfma_f32_16x16x32_bf16 v[12:15], v[186:189], v[202:205], v[12:15]
	v_mfma_f32_16x16x32_bf16 v[4:7], v[194:197], v[202:205], v[4:7]
	v_mfma_f32_16x16x32_bf16 v[16:19], v[186:189], v[210:213], v[16:19]
	v_mfma_f32_16x16x32_bf16 v[8:11], v[194:197], v[210:213], v[8:11]
	v_mfma_f32_16x16x32_bf16 v[44:47], v[186:189], v[218:221], v[44:47]
	v_mfma_f32_16x16x32_bf16 v[36:39], v[194:197], v[218:221], v[36:39]
	v_mfma_f32_16x16x32_bf16 v[48:51], v[186:189], v[226:229], v[48:51]
	v_mfma_f32_16x16x32_bf16 v[40:43], v[194:197], v[226:229], v[40:43]
	v_mfma_f32_16x16x32_bf16 v[12:15], v[190:193], v[206:209], v[12:15]
	v_mfma_f32_16x16x32_bf16 v[4:7], v[198:201], v[206:209], v[4:7]
	v_mfma_f32_16x16x32_bf16 v[16:19], v[190:193], v[214:217], v[16:19]
	v_mfma_f32_16x16x32_bf16 v[8:11], v[198:201], v[214:217], v[8:11]
	v_mfma_f32_16x16x32_bf16 v[44:47], v[190:193], v[222:225], v[44:47]
	v_mfma_f32_16x16x32_bf16 v[36:39], v[198:201], v[222:225], v[36:39]
	v_mfma_f32_16x16x32_bf16 v[48:51], v[190:193], v[230:233], v[48:51]
	v_mfma_f32_16x16x32_bf16 v[40:43], v[198:201], v[230:233], v[40:43]
	s_setprio 0
	s_barrier
	s_add_i32 s85, s85, s15
	v_lshl_add_u64 v[146:147], s[66:67], 0, v[2:3]
	s_mov_b32 m0, s85
	ds_read_b128 v[202:205], v145 offset:16384
	ds_read_b128 v[206:209], v145 offset:17408
	ds_read_b128 v[210:213], v145 offset:18432
	ds_read_b128 v[214:217], v145 offset:19456
	ds_read_b128 v[218:221], v145 offset:20480
	ds_read_b128 v[222:225], v145 offset:21504
	ds_read_b128 v[226:229], v145 offset:22528
	ds_read_b128 v[230:233], v145 offset:23552
	global_load_lds_dwordx4 v[146:147], off
	v_lshl_add_u64 v[154:155], s[66:67], 0, v[132:133]
	s_add_i32 m0, s85, 0x2000
	s_add_i32 s3, s3, s15
	global_load_lds_dwordx4 v[154:155], off
	v_lshl_add_u64 v[234:235], s[66:67], 0, v[134:135]
	s_mov_b32 m0, s3
	v_lshl_add_u64 v[236:237], s[66:67], 0, v[0:1]
	global_load_lds_dwordx4 v[234:235], off
	s_add_i32 m0, s3, 0x2000
	v_lshl_add_u64 v[238:239], s[60:61], 0, v[2:3]
	global_load_lds_dwordx4 v[236:237], off
	s_mov_b32 m0, s16
	v_lshl_add_u64 v[240:241], s[60:61], 0, v[132:133]
	global_load_lds_dwordx4 v[238:239], off
	s_mov_b32 m0, s17
	s_nop 0
	global_load_lds_dwordx4 v[240:241], off
	s_waitcnt vmcnt(8)
	s_waitcnt lgkmcnt(0)
	v_mfma_f32_16x16x32_bf16 v[92:95], v[150:153], v[202:205], v[92:95]
	v_mfma_f32_16x16x32_bf16 v[84:87], v[178:181], v[202:205], v[84:87]
	v_mfma_f32_16x16x32_bf16 v[96:99], v[150:153], v[210:213], v[96:99]
	v_mfma_f32_16x16x32_bf16 v[88:91], v[178:181], v[210:213], v[88:91]
	s_barrier
	s_setprio 1
	s_waitcnt lgkmcnt(0)
	v_mfma_f32_16x16x32_bf16 v[124:127], v[150:153], v[218:221], v[124:127]
	v_mfma_f32_16x16x32_bf16 v[116:119], v[178:181], v[218:221], v[116:119]
	v_mfma_f32_16x16x32_bf16 v[128:131], v[150:153], v[226:229], v[128:131]
	v_mfma_f32_16x16x32_bf16 v[120:123], v[178:181], v[226:229], v[120:123]
	v_mfma_f32_16x16x32_bf16 v[92:95], v[164:167], v[206:209], v[92:95]
	v_mfma_f32_16x16x32_bf16 v[84:87], v[182:185], v[206:209], v[84:87]
	v_mfma_f32_16x16x32_bf16 v[96:99], v[164:167], v[214:217], v[96:99]
	v_mfma_f32_16x16x32_bf16 v[88:91], v[182:185], v[214:217], v[88:91]
	v_mfma_f32_16x16x32_bf16 v[124:127], v[164:167], v[222:225], v[124:127]
	v_mfma_f32_16x16x32_bf16 v[116:119], v[182:185], v[222:225], v[116:119]
	v_mfma_f32_16x16x32_bf16 v[128:131], v[164:167], v[230:233], v[128:131]
	v_mfma_f32_16x16x32_bf16 v[120:123], v[182:185], v[230:233], v[120:123]
	s_setprio 0
	s_setprio 1
	v_mfma_f32_16x16x32_bf16 v[76:79], v[186:189], v[202:205], v[76:79]
	v_mfma_f32_16x16x32_bf16 v[68:71], v[194:197], v[202:205], v[68:71]
	v_mfma_f32_16x16x32_bf16 v[80:83], v[186:189], v[210:213], v[80:83]
	v_mfma_f32_16x16x32_bf16 v[72:75], v[194:197], v[210:213], v[72:75]
	v_mfma_f32_16x16x32_bf16 v[108:111], v[186:189], v[218:221], v[108:111]
	v_mfma_f32_16x16x32_bf16 v[100:103], v[194:197], v[218:221], v[100:103]
	v_mfma_f32_16x16x32_bf16 v[112:115], v[186:189], v[226:229], v[112:115]
	v_mfma_f32_16x16x32_bf16 v[104:107], v[194:197], v[226:229], v[104:107]
	v_mfma_f32_16x16x32_bf16 v[76:79], v[190:193], v[206:209], v[76:79]
	v_mfma_f32_16x16x32_bf16 v[68:71], v[198:201], v[206:209], v[68:71]
	v_mfma_f32_16x16x32_bf16 v[80:83], v[190:193], v[214:217], v[80:83]
	v_mfma_f32_16x16x32_bf16 v[72:75], v[198:201], v[214:217], v[72:75]
	v_mfma_f32_16x16x32_bf16 v[108:111], v[190:193], v[222:225], v[108:111]
	v_mfma_f32_16x16x32_bf16 v[100:103], v[198:201], v[222:225], v[100:103]
	v_mfma_f32_16x16x32_bf16 v[112:115], v[190:193], v[230:233], v[112:115]
	v_mfma_f32_16x16x32_bf16 v[104:107], v[198:201], v[230:233], v[104:107]
	s_setprio 0
	s_barrier
	s_add_i32 s3, 0, 0x18000
	v_add_u32_e32 v149, s3, v144
	s_add_i32 s66, 0, 0x1c000
	ds_read_b128 v[150:153], v149
	ds_read_b128 v[164:167], v149 offset:1024
	ds_read_b128 v[178:181], v149 offset:2048
	ds_read_b128 v[182:185], v149 offset:3072
	v_add_u32_e32 v149, s66, v144
	ds_read_b128 v[186:189], v149
	ds_read_b128 v[190:193], v149 offset:1024
	ds_read_b128 v[194:197], v149 offset:2048
	ds_read_b128 v[198:201], v149 offset:3072
	s_add_u32 s60, s60, 0x80000
	s_addc_u32 s61, s61, 0
	s_mov_b32 m0, s28
	v_lshl_add_u64 v[242:243], s[60:61], 0, v[2:3]
	ds_read_b128 v[202:205], v145 offset:32768
	ds_read_b128 v[206:209], v145 offset:33792
	ds_read_b128 v[210:213], v145 offset:34816
	ds_read_b128 v[214:217], v145 offset:35840
	ds_read_b128 v[218:221], v145 offset:36864
	ds_read_b128 v[222:225], v145 offset:37888
	ds_read_b128 v[226:229], v145 offset:38912
	ds_read_b128 v[230:233], v145 offset:39936
	global_load_lds_dwordx4 v[242:243], off
	v_lshl_add_u64 v[242:243], s[60:61], 0, v[132:133]
	s_mov_b32 m0, s95
	s_nop 0
	global_load_lds_dwordx4 v[242:243], off
	s_waitcnt vmcnt(8)
	s_waitcnt lgkmcnt(0)
	v_mfma_f32_16x16x32_bf16 v[28:31], v[150:153], v[202:205], v[28:31]
	v_mfma_f32_16x16x32_bf16 v[20:23], v[178:181], v[202:205], v[20:23]
	v_mfma_f32_16x16x32_bf16 v[32:35], v[150:153], v[210:213], v[32:35]
	v_mfma_f32_16x16x32_bf16 v[24:27], v[178:181], v[210:213], v[24:27]
	s_barrier
	s_setprio 1
	s_waitcnt lgkmcnt(0)
	v_mfma_f32_16x16x32_bf16 v[60:63], v[150:153], v[218:221], v[60:63]
	v_mfma_f32_16x16x32_bf16 v[52:55], v[178:181], v[218:221], v[52:55]
	v_mfma_f32_16x16x32_bf16 v[64:67], v[150:153], v[226:229], v[64:67]
	v_mfma_f32_16x16x32_bf16 v[56:59], v[178:181], v[226:229], v[56:59]
	v_mfma_f32_16x16x32_bf16 v[28:31], v[164:167], v[206:209], v[28:31]
	v_mfma_f32_16x16x32_bf16 v[20:23], v[182:185], v[206:209], v[20:23]
	v_mfma_f32_16x16x32_bf16 v[32:35], v[164:167], v[214:217], v[32:35]
	v_mfma_f32_16x16x32_bf16 v[24:27], v[182:185], v[214:217], v[24:27]
	v_mfma_f32_16x16x32_bf16 v[60:63], v[164:167], v[222:225], v[60:63]
	v_mfma_f32_16x16x32_bf16 v[52:55], v[182:185], v[222:225], v[52:55]
	v_mfma_f32_16x16x32_bf16 v[64:67], v[164:167], v[230:233], v[64:67]
	v_mfma_f32_16x16x32_bf16 v[56:59], v[182:185], v[230:233], v[56:59]
	s_setprio 0
	s_setprio 1
	v_mfma_f32_16x16x32_bf16 v[12:15], v[186:189], v[202:205], v[12:15]
	v_mfma_f32_16x16x32_bf16 v[4:7], v[194:197], v[202:205], v[4:7]
	v_mfma_f32_16x16x32_bf16 v[16:19], v[186:189], v[210:213], v[16:19]
	v_mfma_f32_16x16x32_bf16 v[8:11], v[194:197], v[210:213], v[8:11]
	v_mfma_f32_16x16x32_bf16 v[44:47], v[186:189], v[218:221], v[44:47]
	v_mfma_f32_16x16x32_bf16 v[36:39], v[194:197], v[218:221], v[36:39]
	v_mfma_f32_16x16x32_bf16 v[48:51], v[186:189], v[226:229], v[48:51]
	v_mfma_f32_16x16x32_bf16 v[40:43], v[194:197], v[226:229], v[40:43]
	v_mfma_f32_16x16x32_bf16 v[12:15], v[190:193], v[206:209], v[12:15]
	v_mfma_f32_16x16x32_bf16 v[4:7], v[198:201], v[206:209], v[4:7]
	v_mfma_f32_16x16x32_bf16 v[16:19], v[190:193], v[214:217], v[16:19]
	v_mfma_f32_16x16x32_bf16 v[8:11], v[198:201], v[214:217], v[8:11]
	v_mfma_f32_16x16x32_bf16 v[44:47], v[190:193], v[222:225], v[44:47]
	v_mfma_f32_16x16x32_bf16 v[36:39], v[198:201], v[222:225], v[36:39]
	v_mfma_f32_16x16x32_bf16 v[48:51], v[190:193], v[230:233], v[48:51]
	v_mfma_f32_16x16x32_bf16 v[40:43], v[198:201], v[230:233], v[40:43]
	s_setprio 0
	s_barrier
	s_add_i32 s3, s3, s15
	v_lshl_add_u64 v[146:147], v[146:147], 0, s[82:83]
	s_mov_b32 m0, s3
	ds_read_b128 v[202:205], v145 offset:49152
	ds_read_b128 v[206:209], v145 offset:50176
	ds_read_b128 v[210:213], v145 offset:51200
	ds_read_b128 v[214:217], v145 offset:52224
	ds_read_b128 v[218:221], v145 offset:53248
	ds_read_b128 v[222:225], v145 offset:54272
	ds_read_b128 v[226:229], v145 offset:55296
	ds_read_b128 v[230:233], v145 offset:56320
	global_load_lds_dwordx4 v[146:147], off
	v_lshl_add_u64 v[146:147], v[154:155], 0, s[82:83]
	s_add_i32 m0, s3, 0x2000
	s_add_i32 s3, s66, s15
	global_load_lds_dwordx4 v[146:147], off
	v_lshl_add_u64 v[146:147], v[234:235], 0, s[82:83]
	s_mov_b32 m0, s3
	s_nop 0
	global_load_lds_dwordx4 v[146:147], off
	v_lshl_add_u64 v[146:147], v[236:237], 0, s[82:83]
	s_add_i32 m0, s3, 0x2000
	s_nop 0
	global_load_lds_dwordx4 v[146:147], off
	v_lshl_add_u64 v[146:147], v[238:239], 0, s[82:83]
	s_mov_b32 m0, s97
	s_nop 0
	global_load_lds_dwordx4 v[146:147], off
	v_lshl_add_u64 v[146:147], v[240:241], 0, s[82:83]
	s_mov_b32 m0, s12
	s_nop 0
	global_load_lds_dwordx4 v[146:147], off
	s_waitcnt vmcnt(8)
	s_waitcnt lgkmcnt(0)
	v_mfma_f32_16x16x32_bf16 v[92:95], v[150:153], v[202:205], v[92:95]
	v_mfma_f32_16x16x32_bf16 v[84:87], v[178:181], v[202:205], v[84:87]
	v_mfma_f32_16x16x32_bf16 v[96:99], v[150:153], v[210:213], v[96:99]
	v_mfma_f32_16x16x32_bf16 v[88:91], v[178:181], v[210:213], v[88:91]
	s_barrier
	s_setprio 1
	s_waitcnt lgkmcnt(0)
	v_mfma_f32_16x16x32_bf16 v[124:127], v[150:153], v[218:221], v[124:127]
	v_mfma_f32_16x16x32_bf16 v[116:119], v[178:181], v[218:221], v[116:119]
	v_mfma_f32_16x16x32_bf16 v[128:131], v[150:153], v[226:229], v[128:131]
	v_mfma_f32_16x16x32_bf16 v[120:123], v[178:181], v[226:229], v[120:123]
	v_mfma_f32_16x16x32_bf16 v[92:95], v[164:167], v[206:209], v[92:95]
	v_mfma_f32_16x16x32_bf16 v[84:87], v[182:185], v[206:209], v[84:87]
	v_mfma_f32_16x16x32_bf16 v[96:99], v[164:167], v[214:217], v[96:99]
	v_mfma_f32_16x16x32_bf16 v[88:91], v[182:185], v[214:217], v[88:91]
	v_mfma_f32_16x16x32_bf16 v[124:127], v[164:167], v[222:225], v[124:127]
	v_mfma_f32_16x16x32_bf16 v[116:119], v[182:185], v[222:225], v[116:119]
	v_mfma_f32_16x16x32_bf16 v[128:131], v[164:167], v[230:233], v[128:131]
	v_mfma_f32_16x16x32_bf16 v[120:123], v[182:185], v[230:233], v[120:123]
	s_setprio 0
	s_setprio 1
	v_mfma_f32_16x16x32_bf16 v[76:79], v[186:189], v[202:205], v[76:79]
	v_mfma_f32_16x16x32_bf16 v[68:71], v[194:197], v[202:205], v[68:71]
	v_mfma_f32_16x16x32_bf16 v[80:83], v[186:189], v[210:213], v[80:83]
	v_mfma_f32_16x16x32_bf16 v[72:75], v[194:197], v[210:213], v[72:75]
	v_mfma_f32_16x16x32_bf16 v[108:111], v[186:189], v[218:221], v[108:111]
	v_mfma_f32_16x16x32_bf16 v[100:103], v[194:197], v[218:221], v[100:103]
	v_mfma_f32_16x16x32_bf16 v[112:115], v[186:189], v[226:229], v[112:115]
	v_mfma_f32_16x16x32_bf16 v[104:107], v[194:197], v[226:229], v[104:107]
	v_mfma_f32_16x16x32_bf16 v[76:79], v[190:193], v[206:209], v[76:79]
	v_mfma_f32_16x16x32_bf16 v[68:71], v[198:201], v[206:209], v[68:71]
	v_mfma_f32_16x16x32_bf16 v[80:83], v[190:193], v[214:217], v[80:83]
	v_mfma_f32_16x16x32_bf16 v[72:75], v[198:201], v[214:217], v[72:75]
	v_mfma_f32_16x16x32_bf16 v[108:111], v[190:193], v[222:225], v[108:111]
	v_mfma_f32_16x16x32_bf16 v[100:103], v[198:201], v[222:225], v[100:103]
	v_mfma_f32_16x16x32_bf16 v[112:115], v[190:193], v[230:233], v[112:115]
	v_mfma_f32_16x16x32_bf16 v[104:107], v[198:201], v[230:233], v[104:107]
	s_setprio 0
	s_barrier
	s_add_i32 s2, s2, 2
	s_add_u32 s58, s58, 0x100
	s_addc_u32 s59, s59, 0
	s_cmp_gt_u32 s2, 29
	s_cbranch_scc0 .LBB0_426
	s_and_b64 vcc, exec, s[48:49]
	s_cbranch_vccz .LBB0_429
	s_barrier

.LBB0_483:
	s_add_u32 s2, s52, s58
	s_addc_u32 s3, s53, s59
	s_add_u32 s2, s2, 0x100
	s_addc_u32 s3, s3, 0
	s_add_u32 s66, s20, s58
	s_addc_u32 s67, s21, s59
	s_add_i32 vcc_hi, 0, 0x10000
	s_cmpk_eq_i32 s58, 0xf00
	s_cselect_b32 s61, s51, s3
	s_cselect_b32 s60, s62, s2
	v_add_u32_e32 v146, vcc_hi, v144
	s_cselect_b32 s3, s49, s67
	s_cselect_b32 s2, s97, s66
	s_add_i32 s66, 0, 0x14000
	ds_read_b128 v[150:153], v146
	ds_read_b128 v[164:167], v146 offset:1024
	ds_read_b128 v[178:181], v146 offset:2048
	ds_read_b128 v[182:185], v146 offset:3072
	v_add_u32_e32 v146, s66, v144
	ds_read_b128 v[186:189], v146
	ds_read_b128 v[190:193], v146 offset:1024
	ds_read_b128 v[194:197], v146 offset:2048
	ds_read_b128 v[198:201], v146 offset:3072
	v_lshl_add_u64 v[146:147], v[140:141], 0, s[58:59]
	s_add_i32 m0, s16, 0xc000
	ds_read_b128 v[202:205], v145
	ds_read_b128 v[206:209], v145 offset:1024
	ds_read_b128 v[210:213], v145 offset:2048
	ds_read_b128 v[214:217], v145 offset:3072
	ds_read_b128 v[218:221], v145 offset:4096
	ds_read_b128 v[222:225], v145 offset:5120
	ds_read_b128 v[226:229], v145 offset:6144
	ds_read_b128 v[230:233], v145 offset:7168
	global_load_lds_dwordx4 v[146:147], off
	v_lshl_add_u64 v[146:147], v[142:143], 0, s[58:59]
	s_add_i32 m0, s16, 0xe000
	s_nop 0
	global_load_lds_dwordx4 v[146:147], off
	s_waitcnt vmcnt(8)
	s_waitcnt lgkmcnt(0)
	v_mfma_f32_16x16x32_bf16 v[28:31], v[150:153], v[202:205], v[28:31]
	v_mfma_f32_16x16x32_bf16 v[20:23], v[178:181], v[202:205], v[20:23]
	v_mfma_f32_16x16x32_bf16 v[32:35], v[150:153], v[210:213], v[32:35]
	v_mfma_f32_16x16x32_bf16 v[24:27], v[178:181], v[210:213], v[24:27]
	s_barrier
	s_setprio 1
	s_waitcnt lgkmcnt(0)
	v_mfma_f32_16x16x32_bf16 v[60:63], v[150:153], v[218:221], v[60:63]
	v_mfma_f32_16x16x32_bf16 v[52:55], v[178:181], v[218:221], v[52:55]
	v_mfma_f32_16x16x32_bf16 v[64:67], v[150:153], v[226:229], v[64:67]
	v_mfma_f32_16x16x32_bf16 v[56:59], v[178:181], v[226:229], v[56:59]
	v_mfma_f32_16x16x32_bf16 v[28:31], v[164:167], v[206:209], v[28:31]
	v_mfma_f32_16x16x32_bf16 v[20:23], v[182:185], v[206:209], v[20:23]
	v_mfma_f32_16x16x32_bf16 v[32:35], v[164:167], v[214:217], v[32:35]
	v_mfma_f32_16x16x32_bf16 v[24:27], v[182:185], v[214:217], v[24:27]
	v_mfma_f32_16x16x32_bf16 v[60:63], v[164:167], v[222:225], v[60:63]
	v_mfma_f32_16x16x32_bf16 v[52:55], v[182:185], v[222:225], v[52:55]
	v_mfma_f32_16x16x32_bf16 v[64:67], v[164:167], v[230:233], v[64:67]
	v_mfma_f32_16x16x32_bf16 v[56:59], v[182:185], v[230:233], v[56:59]
	s_setprio 0
	s_setprio 1
	v_mfma_f32_16x16x32_bf16 v[12:15], v[186:189], v[202:205], v[12:15]
	v_mfma_f32_16x16x32_bf16 v[4:7], v[194:197], v[202:205], v[4:7]
	v_mfma_f32_16x16x32_bf16 v[16:19], v[186:189], v[210:213], v[16:19]
	v_mfma_f32_16x16x32_bf16 v[8:11], v[194:197], v[210:213], v[8:11]
	v_mfma_f32_16x16x32_bf16 v[44:47], v[186:189], v[218:221], v[44:47]
	v_mfma_f32_16x16x32_bf16 v[36:39], v[194:197], v[218:221], v[36:39]
	v_mfma_f32_16x16x32_bf16 v[48:51], v[186:189], v[226:229], v[48:51]
	v_mfma_f32_16x16x32_bf16 v[40:43], v[194:197], v[226:229], v[40:43]
	v_mfma_f32_16x16x32_bf16 v[12:15], v[190:193], v[206:209], v[12:15]
	v_mfma_f32_16x16x32_bf16 v[4:7], v[198:201], v[206:209], v[4:7]
	v_mfma_f32_16x16x32_bf16 v[16:19], v[190:193], v[214:217], v[16:19]
	v_mfma_f32_16x16x32_bf16 v[8:11], v[198:201], v[214:217], v[8:11]
	v_mfma_f32_16x16x32_bf16 v[44:47], v[190:193], v[222:225], v[44:47]
	v_mfma_f32_16x16x32_bf16 v[36:39], v[198:201], v[222:225], v[36:39]
	v_mfma_f32_16x16x32_bf16 v[48:51], v[190:193], v[230:233], v[48:51]
	v_mfma_f32_16x16x32_bf16 v[40:43], v[198:201], v[230:233], v[40:43]
	s_setprio 0
	s_barrier
	s_add_i32 s67, vcc_hi, s15
	v_lshl_add_u64 v[146:147], s[2:3], 0, v[2:3]
	s_mov_b32 m0, s67
	ds_read_b128 v[202:205], v145 offset:16384
	ds_read_b128 v[206:209], v145 offset:17408
	ds_read_b128 v[210:213], v145 offset:18432
	ds_read_b128 v[214:217], v145 offset:19456
	ds_read_b128 v[218:221], v145 offset:20480
	ds_read_b128 v[222:225], v145 offset:21504
	ds_read_b128 v[226:229], v145 offset:22528
	ds_read_b128 v[230:233], v145 offset:23552
	global_load_lds_dwordx4 v[146:147], off
	v_lshl_add_u64 v[154:155], s[2:3], 0, v[132:133]
	s_add_i32 m0, s67, 0x2000
	s_add_i32 s66, s66, s15
	global_load_lds_dwordx4 v[154:155], off
	v_lshl_add_u64 v[234:235], s[2:3], 0, v[134:135]
	s_mov_b32 m0, s66
	v_lshl_add_u64 v[236:237], s[2:3], 0, v[0:1]
	global_load_lds_dwordx4 v[234:235], off
	s_add_i32 m0, s66, 0x2000
	v_lshl_add_u64 v[238:239], s[60:61], 0, v[2:3]
	global_load_lds_dwordx4 v[236:237], off
	s_mov_b32 m0, s16
	v_lshl_add_u64 v[240:241], s[60:61], 0, v[132:133]
	global_load_lds_dwordx4 v[238:239], off
	s_mov_b32 m0, s17
	s_nop 0
	global_load_lds_dwordx4 v[240:241], off
	s_waitcnt vmcnt(8)
	s_waitcnt lgkmcnt(0)
	v_mfma_f32_16x16x32_bf16 v[92:95], v[150:153], v[202:205], v[92:95]
	v_mfma_f32_16x16x32_bf16 v[84:87], v[178:181], v[202:205], v[84:87]
	v_mfma_f32_16x16x32_bf16 v[96:99], v[150:153], v[210:213], v[96:99]
	v_mfma_f32_16x16x32_bf16 v[88:91], v[178:181], v[210:213], v[88:91]
	s_barrier
	s_setprio 1
	s_waitcnt lgkmcnt(0)
	v_mfma_f32_16x16x32_bf16 v[124:127], v[150:153], v[218:221], v[124:127]
	v_mfma_f32_16x16x32_bf16 v[116:119], v[178:181], v[218:221], v[116:119]
	v_mfma_f32_16x16x32_bf16 v[128:131], v[150:153], v[226:229], v[128:131]
	v_mfma_f32_16x16x32_bf16 v[120:123], v[178:181], v[226:229], v[120:123]
	v_mfma_f32_16x16x32_bf16 v[92:95], v[164:167], v[206:209], v[92:95]
	v_mfma_f32_16x16x32_bf16 v[84:87], v[182:185], v[206:209], v[84:87]
	v_mfma_f32_16x16x32_bf16 v[96:99], v[164:167], v[214:217], v[96:99]
	v_mfma_f32_16x16x32_bf16 v[88:91], v[182:185], v[214:217], v[88:91]
	v_mfma_f32_16x16x32_bf16 v[124:127], v[164:167], v[222:225], v[124:127]
	v_mfma_f32_16x16x32_bf16 v[116:119], v[182:185], v[222:225], v[116:119]
	v_mfma_f32_16x16x32_bf16 v[128:131], v[164:167], v[230:233], v[128:131]
	v_mfma_f32_16x16x32_bf16 v[120:123], v[182:185], v[230:233], v[120:123]
	s_setprio 0
	s_setprio 1
	v_mfma_f32_16x16x32_bf16 v[76:79], v[186:189], v[202:205], v[76:79]
	v_mfma_f32_16x16x32_bf16 v[68:71], v[194:197], v[202:205], v[68:71]
	v_mfma_f32_16x16x32_bf16 v[80:83], v[186:189], v[210:213], v[80:83]
	v_mfma_f32_16x16x32_bf16 v[72:75], v[194:197], v[210:213], v[72:75]
	v_mfma_f32_16x16x32_bf16 v[108:111], v[186:189], v[218:221], v[108:111]
	v_mfma_f32_16x16x32_bf16 v[100:103], v[194:197], v[218:221], v[100:103]
	v_mfma_f32_16x16x32_bf16 v[112:115], v[186:189], v[226:229], v[112:115]
	v_mfma_f32_16x16x32_bf16 v[104:107], v[194:197], v[226:229], v[104:107]
	v_mfma_f32_16x16x32_bf16 v[76:79], v[190:193], v[206:209], v[76:79]
	v_mfma_f32_16x16x32_bf16 v[68:71], v[198:201], v[206:209], v[68:71]
	v_mfma_f32_16x16x32_bf16 v[80:83], v[190:193], v[214:217], v[80:83]
	v_mfma_f32_16x16x32_bf16 v[72:75], v[198:201], v[214:217], v[72:75]
	v_mfma_f32_16x16x32_bf16 v[108:111], v[190:193], v[222:225], v[108:111]
	v_mfma_f32_16x16x32_bf16 v[100:103], v[198:201], v[222:225], v[100:103]
	v_mfma_f32_16x16x32_bf16 v[112:115], v[190:193], v[230:233], v[112:115]
	v_mfma_f32_16x16x32_bf16 v[104:107], v[198:201], v[230:233], v[104:107]
	s_setprio 0
	s_barrier
	s_add_i32 s66, 0, 0x18000
	v_add_u32_e32 v149, s66, v144
	s_add_i32 s67, 0, 0x1c000
	ds_read_b128 v[150:153], v149
	ds_read_b128 v[164:167], v149 offset:1024
	ds_read_b128 v[178:181], v149 offset:2048
	ds_read_b128 v[182:185], v149 offset:3072
	v_add_u32_e32 v149, s67, v144
	ds_read_b128 v[186:189], v149
	ds_read_b128 v[190:193], v149 offset:1024
	ds_read_b128 v[194:197], v149 offset:2048
	ds_read_b128 v[198:201], v149 offset:3072
	s_add_u32 s2, s60, 0x80000
	s_addc_u32 s3, s61, 0
	s_mov_b32 m0, s28
	v_lshl_add_u64 v[242:243], s[2:3], 0, v[2:3]
	ds_read_b128 v[202:205], v145 offset:32768
	ds_read_b128 v[206:209], v145 offset:33792
	ds_read_b128 v[210:213], v145 offset:34816
	ds_read_b128 v[214:217], v145 offset:35840
	ds_read_b128 v[218:221], v145 offset:36864
	ds_read_b128 v[222:225], v145 offset:37888
	ds_read_b128 v[226:229], v145 offset:38912
	ds_read_b128 v[230:233], v145 offset:39936
	global_load_lds_dwordx4 v[242:243], off
	v_lshl_add_u64 v[242:243], s[2:3], 0, v[132:133]
	s_mov_b32 m0, s91
	s_nop 0
	global_load_lds_dwordx4 v[242:243], off
	s_waitcnt vmcnt(8)
	s_waitcnt lgkmcnt(0)
	v_mfma_f32_16x16x32_bf16 v[28:31], v[150:153], v[202:205], v[28:31]
	v_mfma_f32_16x16x32_bf16 v[20:23], v[178:181], v[202:205], v[20:23]
	v_mfma_f32_16x16x32_bf16 v[32:35], v[150:153], v[210:213], v[32:35]
	v_mfma_f32_16x16x32_bf16 v[24:27], v[178:181], v[210:213], v[24:27]
	s_barrier
	s_setprio 1
	s_waitcnt lgkmcnt(0)
	v_mfma_f32_16x16x32_bf16 v[60:63], v[150:153], v[218:221], v[60:63]
	v_mfma_f32_16x16x32_bf16 v[52:55], v[178:181], v[218:221], v[52:55]
	v_mfma_f32_16x16x32_bf16 v[64:67], v[150:153], v[226:229], v[64:67]
	v_mfma_f32_16x16x32_bf16 v[56:59], v[178:181], v[226:229], v[56:59]
	v_mfma_f32_16x16x32_bf16 v[28:31], v[164:167], v[206:209], v[28:31]
	v_mfma_f32_16x16x32_bf16 v[20:23], v[182:185], v[206:209], v[20:23]
	v_mfma_f32_16x16x32_bf16 v[32:35], v[164:167], v[214:217], v[32:35]
	v_mfma_f32_16x16x32_bf16 v[24:27], v[182:185], v[214:217], v[24:27]
	v_mfma_f32_16x16x32_bf16 v[60:63], v[164:167], v[222:225], v[60:63]
	v_mfma_f32_16x16x32_bf16 v[52:55], v[182:185], v[222:225], v[52:55]
	v_mfma_f32_16x16x32_bf16 v[64:67], v[164:167], v[230:233], v[64:67]
	v_mfma_f32_16x16x32_bf16 v[56:59], v[182:185], v[230:233], v[56:59]
	s_setprio 0
	s_setprio 1
	v_mfma_f32_16x16x32_bf16 v[12:15], v[186:189], v[202:205], v[12:15]
	v_mfma_f32_16x16x32_bf16 v[4:7], v[194:197], v[202:205], v[4:7]
	v_mfma_f32_16x16x32_bf16 v[16:19], v[186:189], v[210:213], v[16:19]
	v_mfma_f32_16x16x32_bf16 v[8:11], v[194:197], v[210:213], v[8:11]
	v_mfma_f32_16x16x32_bf16 v[44:47], v[186:189], v[218:221], v[44:47]
	v_mfma_f32_16x16x32_bf16 v[36:39], v[194:197], v[218:221], v[36:39]
	v_mfma_f32_16x16x32_bf16 v[48:51], v[186:189], v[226:229], v[48:51]
	v_mfma_f32_16x16x32_bf16 v[40:43], v[194:197], v[226:229], v[40:43]
	v_mfma_f32_16x16x32_bf16 v[12:15], v[190:193], v[206:209], v[12:15]
	v_mfma_f32_16x16x32_bf16 v[4:7], v[198:201], v[206:209], v[4:7]
	v_mfma_f32_16x16x32_bf16 v[16:19], v[190:193], v[214:217], v[16:19]
	v_mfma_f32_16x16x32_bf16 v[8:11], v[198:201], v[214:217], v[8:11]
	v_mfma_f32_16x16x32_bf16 v[44:47], v[190:193], v[222:225], v[44:47]
	v_mfma_f32_16x16x32_bf16 v[36:39], v[198:201], v[222:225], v[36:39]
	v_mfma_f32_16x16x32_bf16 v[48:51], v[190:193], v[230:233], v[48:51]
	v_mfma_f32_16x16x32_bf16 v[40:43], v[198:201], v[230:233], v[40:43]
	s_setprio 0
	s_barrier
	s_add_i32 s2, s66, s15
	v_lshl_add_u64 v[146:147], v[146:147], 0, s[82:83]
	s_mov_b32 m0, s2
	ds_read_b128 v[202:205], v145 offset:49152
	ds_read_b128 v[206:209], v145 offset:50176
	ds_read_b128 v[210:213], v145 offset:51200
	ds_read_b128 v[214:217], v145 offset:52224
	ds_read_b128 v[218:221], v145 offset:53248
	ds_read_b128 v[222:225], v145 offset:54272
	ds_read_b128 v[226:229], v145 offset:55296
	ds_read_b128 v[230:233], v145 offset:56320
	global_load_lds_dwordx4 v[146:147], off
	v_lshl_add_u64 v[146:147], v[154:155], 0, s[82:83]
	s_add_i32 m0, s2, 0x2000
	s_add_i32 s2, s67, s15
	global_load_lds_dwordx4 v[146:147], off
	v_lshl_add_u64 v[146:147], v[234:235], 0, s[82:83]
	s_mov_b32 m0, s2
	s_nop 0
	global_load_lds_dwordx4 v[146:147], off
	v_lshl_add_u64 v[146:147], v[236:237], 0, s[82:83]
	s_add_i32 m0, s2, 0x2000
	s_nop 0
	global_load_lds_dwordx4 v[146:147], off
	v_lshl_add_u64 v[146:147], v[238:239], 0, s[82:83]
	s_mov_b32 m0, s95
	s_nop 0
	global_load_lds_dwordx4 v[146:147], off
	v_lshl_add_u64 v[146:147], v[240:241], 0, s[82:83]
	s_mov_b32 m0, s12
	s_nop 0
	global_load_lds_dwordx4 v[146:147], off
	s_waitcnt vmcnt(8)
	s_waitcnt lgkmcnt(0)
	v_mfma_f32_16x16x32_bf16 v[92:95], v[150:153], v[202:205], v[92:95]
	v_mfma_f32_16x16x32_bf16 v[84:87], v[178:181], v[202:205], v[84:87]
	v_mfma_f32_16x16x32_bf16 v[96:99], v[150:153], v[210:213], v[96:99]
	v_mfma_f32_16x16x32_bf16 v[88:91], v[178:181], v[210:213], v[88:91]
	s_barrier
	s_setprio 1
	s_waitcnt lgkmcnt(0)
	v_mfma_f32_16x16x32_bf16 v[124:127], v[150:153], v[218:221], v[124:127]
	v_mfma_f32_16x16x32_bf16 v[116:119], v[178:181], v[218:221], v[116:119]
	v_mfma_f32_16x16x32_bf16 v[128:131], v[150:153], v[226:229], v[128:131]
	v_mfma_f32_16x16x32_bf16 v[120:123], v[178:181], v[226:229], v[120:123]
	v_mfma_f32_16x16x32_bf16 v[92:95], v[164:167], v[206:209], v[92:95]
	v_mfma_f32_16x16x32_bf16 v[84:87], v[182:185], v[206:209], v[84:87]
	v_mfma_f32_16x16x32_bf16 v[96:99], v[164:167], v[214:217], v[96:99]
	v_mfma_f32_16x16x32_bf16 v[88:91], v[182:185], v[214:217], v[88:91]
	v_mfma_f32_16x16x32_bf16 v[124:127], v[164:167], v[222:225], v[124:127]
	v_mfma_f32_16x16x32_bf16 v[116:119], v[182:185], v[222:225], v[116:119]
	v_mfma_f32_16x16x32_bf16 v[128:131], v[164:167], v[230:233], v[128:131]
	v_mfma_f32_16x16x32_bf16 v[120:123], v[182:185], v[230:233], v[120:123]
	s_setprio 0
	s_setprio 1
	v_mfma_f32_16x16x32_bf16 v[76:79], v[186:189], v[202:205], v[76:79]
	v_mfma_f32_16x16x32_bf16 v[68:71], v[194:197], v[202:205], v[68:71]
	v_mfma_f32_16x16x32_bf16 v[80:83], v[186:189], v[210:213], v[80:83]
	v_mfma_f32_16x16x32_bf16 v[72:75], v[194:197], v[210:213], v[72:75]
	v_mfma_f32_16x16x32_bf16 v[108:111], v[186:189], v[218:221], v[108:111]
	v_mfma_f32_16x16x32_bf16 v[100:103], v[194:197], v[218:221], v[100:103]
	v_mfma_f32_16x16x32_bf16 v[112:115], v[186:189], v[226:229], v[112:115]
	v_mfma_f32_16x16x32_bf16 v[104:107], v[194:197], v[226:229], v[104:107]
	v_mfma_f32_16x16x32_bf16 v[76:79], v[190:193], v[206:209], v[76:79]
	v_mfma_f32_16x16x32_bf16 v[68:71], v[198:201], v[206:209], v[68:71]
	v_mfma_f32_16x16x32_bf16 v[80:83], v[190:193], v[214:217], v[80:83]
	v_mfma_f32_16x16x32_bf16 v[72:75], v[198:201], v[214:217], v[72:75]
	v_mfma_f32_16x16x32_bf16 v[108:111], v[190:193], v[222:225], v[108:111]
	v_mfma_f32_16x16x32_bf16 v[100:103], v[198:201], v[222:225], v[100:103]
	v_mfma_f32_16x16x32_bf16 v[112:115], v[190:193], v[230:233], v[112:115]
	v_mfma_f32_16x16x32_bf16 v[104:107], v[198:201], v[230:233], v[104:107]
	s_setprio 0
	s_barrier
	s_add_i32 vcc_lo, vcc_lo, 2
	s_add_u32 s58, s58, 0x100
	s_addc_u32 s59, s59, 0
	s_cmp_gt_u32 vcc_lo, 29
	s_cbranch_scc0 .LBB0_483
	s_and_b64 vcc, exec, s[46:47]
	s_cbranch_vccz .LBB0_486
	s_barrier

.LBB0_589:
	ds_read_b128 v[156:159], v152
	ds_read_b128 v[160:163], v152 offset:1024
	ds_read_b128 v[164:167], v152 offset:2048
	ds_read_b128 v[172:175], v152 offset:3072
	ds_read_b128 v[176:179], v153
	ds_read_b128 v[180:183], v153 offset:1024
	ds_read_b128 v[184:187], v153 offset:2048
	ds_read_b128 v[188:191], v153 offset:3072
	s_add_u32 s2, s44, 0xfffc0080
	s_addc_u32 s3, s45, -1
	s_cmp_eq_u32 s54, 12
	s_cselect_b32 s47, s25, s3
	s_cselect_b32 s46, s50, s2
	s_cselect_b32 s57, s19, s53
	s_cselect_b32 s56, s51, s52
	v_lshl_add_u64 v[168:169], s[44:45], 0, v[142:143]
	s_add_i32 m0, s14, 0xc000
	ds_read_b128 v[192:195], v154
	ds_read_b128 v[196:199], v154 offset:1024
	ds_read_b128 v[200:203], v154 offset:2048
	ds_read_b128 v[204:207], v154 offset:3072
	ds_read_b128 v[208:211], v154 offset:4096
	ds_read_b128 v[212:215], v154 offset:5120
	ds_read_b128 v[216:219], v154 offset:6144
	ds_read_b128 v[220:223], v154 offset:7168
	global_load_lds_dwordx4 v[168:169], off
	v_lshl_add_u64 v[168:169], s[44:45], 0, v[144:145]
	s_add_i32 m0, s14, 0xe000
	s_nop 0
	global_load_lds_dwordx4 v[168:169], off
	s_waitcnt vmcnt(8)
	s_waitcnt lgkmcnt(0)
	v_mfma_f32_16x16x32_f16 v[124:127], v[156:159], v[192:195], v[124:127]
	v_mfma_f32_16x16x32_f16 v[120:123], v[164:167], v[192:195], v[120:123]
	v_mfma_f32_16x16x32_f16 v[116:119], v[156:159], v[200:203], v[116:119]
	v_mfma_f32_16x16x32_f16 v[108:111], v[164:167], v[200:203], v[108:111]
	s_barrier
	s_setprio 1
	s_waitcnt lgkmcnt(0)
	v_mfma_f32_16x16x32_f16 v[100:103], v[156:159], v[208:211], v[100:103]
	v_mfma_f32_16x16x32_f16 v[92:95], v[164:167], v[208:211], v[92:95]
	v_mfma_f32_16x16x32_f16 v[84:87], v[156:159], v[216:219], v[84:87]
	v_mfma_f32_16x16x32_f16 v[76:79], v[164:167], v[216:219], v[76:79]
	v_mfma_f32_16x16x32_f16 v[124:127], v[160:163], v[196:199], v[124:127]
	v_mfma_f32_16x16x32_f16 v[120:123], v[172:175], v[196:199], v[120:123]
	v_mfma_f32_16x16x32_f16 v[116:119], v[160:163], v[204:207], v[116:119]
	v_mfma_f32_16x16x32_f16 v[108:111], v[172:175], v[204:207], v[108:111]
	v_mfma_f32_16x16x32_f16 v[100:103], v[160:163], v[212:215], v[100:103]
	v_mfma_f32_16x16x32_f16 v[92:95], v[172:175], v[212:215], v[92:95]
	v_mfma_f32_16x16x32_f16 v[84:87], v[160:163], v[220:223], v[84:87]
	v_mfma_f32_16x16x32_f16 v[76:79], v[172:175], v[220:223], v[76:79]
	s_setprio 0
	s_setprio 1
	v_mfma_f32_16x16x32_f16 v[112:115], v[176:179], v[192:195], v[112:115]
	v_mfma_f32_16x16x32_f16 v[104:107], v[184:187], v[192:195], v[104:107]
	v_mfma_f32_16x16x32_f16 v[96:99], v[176:179], v[200:203], v[96:99]
	v_mfma_f32_16x16x32_f16 v[88:91], v[184:187], v[200:203], v[88:91]
	v_mfma_f32_16x16x32_f16 v[80:83], v[176:179], v[208:211], v[80:83]
	v_mfma_f32_16x16x32_f16 v[72:75], v[184:187], v[208:211], v[72:75]
	v_mfma_f32_16x16x32_f16 v[68:71], v[176:179], v[216:219], v[68:71]
	v_mfma_f32_16x16x32_f16 v[64:67], v[184:187], v[216:219], v[64:67]
	v_mfma_f32_16x16x32_f16 v[112:115], v[180:183], v[196:199], v[112:115]
	v_mfma_f32_16x16x32_f16 v[104:107], v[188:191], v[196:199], v[104:107]
	v_mfma_f32_16x16x32_f16 v[96:99], v[180:183], v[204:207], v[96:99]
	v_mfma_f32_16x16x32_f16 v[88:91], v[188:191], v[204:207], v[88:91]
	v_mfma_f32_16x16x32_f16 v[80:83], v[180:183], v[212:215], v[80:83]
	v_mfma_f32_16x16x32_f16 v[72:75], v[188:191], v[212:215], v[72:75]
	v_mfma_f32_16x16x32_f16 v[68:71], v[180:183], v[220:223], v[68:71]
	v_mfma_f32_16x16x32_f16 v[64:67], v[188:191], v[220:223], v[64:67]
	s_setprio 0
	s_barrier
	s_add_i32 s2, s29, s12
	v_lshl_add_u64 v[168:169], s[56:57], 0, v[134:135]
	s_mov_b32 m0, s2
	ds_read_b128 v[192:195], v154 offset:16384
	ds_read_b128 v[196:199], v154 offset:17408
	ds_read_b128 v[200:203], v154 offset:18432
	ds_read_b128 v[204:207], v154 offset:19456
	ds_read_b128 v[208:211], v154 offset:20480
	ds_read_b128 v[212:215], v154 offset:21504
	ds_read_b128 v[216:219], v154 offset:22528
	ds_read_b128 v[220:223], v154 offset:23552
	global_load_lds_dwordx4 v[168:169], off
	v_lshl_add_u64 v[224:225], s[56:57], 0, v[128:129]
	s_add_i32 m0, s2, 0x2000
	s_add_i32 s2, s48, s12
	global_load_lds_dwordx4 v[224:225], off
	v_lshl_add_u64 v[226:227], s[56:57], 0, v[136:137]
	s_mov_b32 m0, s2
	v_lshl_add_u64 v[228:229], s[56:57], 0, v[130:131]
	global_load_lds_dwordx4 v[226:227], off
	s_add_i32 m0, s2, 0x2000
	v_lshl_add_u64 v[230:231], s[46:47], 0, v[138:139]
	global_load_lds_dwordx4 v[228:229], off
	s_mov_b32 m0, s14
	v_lshl_add_u64 v[232:233], s[46:47], 0, v[132:133]
	global_load_lds_dwordx4 v[230:231], off
	s_mov_b32 m0, s15
	s_nop 0
	global_load_lds_dwordx4 v[232:233], off
	s_waitcnt vmcnt(8)
	s_waitcnt lgkmcnt(0)
	v_mfma_f32_16x16x32_f16 v[60:63], v[156:159], v[192:195], v[60:63]
	v_mfma_f32_16x16x32_f16 v[56:59], v[164:167], v[192:195], v[56:59]
	v_mfma_f32_16x16x32_f16 v[52:55], v[156:159], v[200:203], v[52:55]
	v_mfma_f32_16x16x32_f16 v[44:47], v[164:167], v[200:203], v[44:47]
	s_barrier
	s_setprio 1
	s_waitcnt lgkmcnt(0)
	v_mfma_f32_16x16x32_f16 v[36:39], v[156:159], v[208:211], v[36:39]
	v_mfma_f32_16x16x32_f16 v[28:31], v[164:167], v[208:211], v[28:31]
	v_mfma_f32_16x16x32_f16 v[20:23], v[156:159], v[216:219], v[20:23]
	v_mfma_f32_16x16x32_f16 v[12:15], v[164:167], v[216:219], v[12:15]
	v_mfma_f32_16x16x32_f16 v[60:63], v[160:163], v[196:199], v[60:63]
	v_mfma_f32_16x16x32_f16 v[56:59], v[172:175], v[196:199], v[56:59]
	v_mfma_f32_16x16x32_f16 v[52:55], v[160:163], v[204:207], v[52:55]
	v_mfma_f32_16x16x32_f16 v[44:47], v[172:175], v[204:207], v[44:47]
	v_mfma_f32_16x16x32_f16 v[36:39], v[160:163], v[212:215], v[36:39]
	v_mfma_f32_16x16x32_f16 v[28:31], v[172:175], v[212:215], v[28:31]
	v_mfma_f32_16x16x32_f16 v[20:23], v[160:163], v[220:223], v[20:23]
	v_mfma_f32_16x16x32_f16 v[12:15], v[172:175], v[220:223], v[12:15]
	s_setprio 0
	s_setprio 1
	v_mfma_f32_16x16x32_f16 v[48:51], v[176:179], v[192:195], v[48:51]
	v_mfma_f32_16x16x32_f16 v[40:43], v[184:187], v[192:195], v[40:43]
	v_mfma_f32_16x16x32_f16 v[32:35], v[176:179], v[200:203], v[32:35]
	v_mfma_f32_16x16x32_f16 v[24:27], v[184:187], v[200:203], v[24:27]
	v_mfma_f32_16x16x32_f16 v[16:19], v[176:179], v[208:211], v[16:19]
	v_mfma_f32_16x16x32_f16 v[8:11], v[184:187], v[208:211], v[8:11]
	v_mfma_f32_16x16x32_f16 v[4:7], v[176:179], v[216:219], v[4:7]
	v_mfma_f32_16x16x32_f16 v[0:3], v[184:187], v[216:219], v[0:3]
	v_mfma_f32_16x16x32_f16 v[48:51], v[180:183], v[196:199], v[48:51]
	v_mfma_f32_16x16x32_f16 v[40:43], v[188:191], v[196:199], v[40:43]
	v_mfma_f32_16x16x32_f16 v[32:35], v[180:183], v[204:207], v[32:35]
	v_mfma_f32_16x16x32_f16 v[24:27], v[188:191], v[204:207], v[24:27]
	v_mfma_f32_16x16x32_f16 v[16:19], v[180:183], v[212:215], v[16:19]
	v_mfma_f32_16x16x32_f16 v[8:11], v[188:191], v[212:215], v[8:11]
	v_mfma_f32_16x16x32_f16 v[4:7], v[180:183], v[220:223], v[4:7]
	v_mfma_f32_16x16x32_f16 v[0:3], v[188:191], v[220:223], v[0:3]
	s_setprio 0
	s_barrier
	s_add_i32 s2, 0, 0x18000
	s_add_i32 s3, 0, 0x1c000
	v_add_u32_e32 v172, s2, v151
	v_add_u32_e32 v188, s3, v151
	ds_read_b128 v[156:159], v172
	ds_read_b128 v[160:163], v172 offset:1024
	ds_read_b128 v[164:167], v172 offset:2048
	ds_read_b128 v[172:175], v172 offset:3072
	ds_read_b128 v[176:179], v188
	ds_read_b128 v[180:183], v188 offset:1024
	ds_read_b128 v[184:187], v188 offset:2048
	ds_read_b128 v[188:191], v188 offset:3072
	s_add_u32 s46, s46, 0x40000
	s_addc_u32 s47, s47, 0
	s_mov_b32 m0, s16
	v_lshl_add_u64 v[234:235], s[46:47], 0, v[138:139]
	ds_read_b128 v[192:195], v154 offset:32768
	ds_read_b128 v[196:199], v154 offset:33792
	ds_read_b128 v[200:203], v154 offset:34816
	ds_read_b128 v[204:207], v154 offset:35840
	ds_read_b128 v[208:211], v154 offset:36864
	ds_read_b128 v[212:215], v154 offset:37888
	ds_read_b128 v[216:219], v154 offset:38912
	ds_read_b128 v[220:223], v154 offset:39936
	global_load_lds_dwordx4 v[234:235], off
	v_lshl_add_u64 v[234:235], s[46:47], 0, v[132:133]
	s_mov_b32 m0, s17
	s_nop 0
	global_load_lds_dwordx4 v[234:235], off
	s_waitcnt vmcnt(8)
	s_waitcnt lgkmcnt(0)
	v_mfma_f32_16x16x32_f16 v[124:127], v[156:159], v[192:195], v[124:127]
	v_mfma_f32_16x16x32_f16 v[120:123], v[164:167], v[192:195], v[120:123]
	v_mfma_f32_16x16x32_f16 v[116:119], v[156:159], v[200:203], v[116:119]
	v_mfma_f32_16x16x32_f16 v[108:111], v[164:167], v[200:203], v[108:111]
	s_barrier
	s_setprio 1
	s_waitcnt lgkmcnt(0)
	v_mfma_f32_16x16x32_f16 v[100:103], v[156:159], v[208:211], v[100:103]
	v_mfma_f32_16x16x32_f16 v[92:95], v[164:167], v[208:211], v[92:95]
	v_mfma_f32_16x16x32_f16 v[84:87], v[156:159], v[216:219], v[84:87]
	v_mfma_f32_16x16x32_f16 v[76:79], v[164:167], v[216:219], v[76:79]
	v_mfma_f32_16x16x32_f16 v[124:127], v[160:163], v[196:199], v[124:127]
	v_mfma_f32_16x16x32_f16 v[120:123], v[172:175], v[196:199], v[120:123]
	v_mfma_f32_16x16x32_f16 v[116:119], v[160:163], v[204:207], v[116:119]
	v_mfma_f32_16x16x32_f16 v[108:111], v[172:175], v[204:207], v[108:111]
	v_mfma_f32_16x16x32_f16 v[100:103], v[160:163], v[212:215], v[100:103]
	v_mfma_f32_16x16x32_f16 v[92:95], v[172:175], v[212:215], v[92:95]
	v_mfma_f32_16x16x32_f16 v[84:87], v[160:163], v[220:223], v[84:87]
	v_mfma_f32_16x16x32_f16 v[76:79], v[172:175], v[220:223], v[76:79]
	s_setprio 0
	s_setprio 1
	v_mfma_f32_16x16x32_f16 v[112:115], v[176:179], v[192:195], v[112:115]
	v_mfma_f32_16x16x32_f16 v[104:107], v[184:187], v[192:195], v[104:107]
	v_mfma_f32_16x16x32_f16 v[96:99], v[176:179], v[200:203], v[96:99]
	v_mfma_f32_16x16x32_f16 v[88:91], v[184:187], v[200:203], v[88:91]
	v_mfma_f32_16x16x32_f16 v[80:83], v[176:179], v[208:211], v[80:83]
	v_mfma_f32_16x16x32_f16 v[72:75], v[184:187], v[208:211], v[72:75]
	v_mfma_f32_16x16x32_f16 v[68:71], v[176:179], v[216:219], v[68:71]
	v_mfma_f32_16x16x32_f16 v[64:67], v[184:187], v[216:219], v[64:67]
	v_mfma_f32_16x16x32_f16 v[112:115], v[180:183], v[196:199], v[112:115]
	v_mfma_f32_16x16x32_f16 v[104:107], v[188:191], v[196:199], v[104:107]
	v_mfma_f32_16x16x32_f16 v[96:99], v[180:183], v[204:207], v[96:99]
	v_mfma_f32_16x16x32_f16 v[88:91], v[188:191], v[204:207], v[88:91]
	v_mfma_f32_16x16x32_f16 v[80:83], v[180:183], v[212:215], v[80:83]
	v_mfma_f32_16x16x32_f16 v[72:75], v[188:191], v[212:215], v[72:75]
	v_mfma_f32_16x16x32_f16 v[68:71], v[180:183], v[220:223], v[68:71]
	v_mfma_f32_16x16x32_f16 v[64:67], v[188:191], v[220:223], v[64:67]
	s_setprio 0
	s_barrier
	s_add_i32 s2, s2, s12
	v_lshl_add_u64 v[168:169], v[168:169], 0, s[6:7]
	s_mov_b32 m0, s2
	ds_read_b128 v[192:195], v154 offset:49152
	ds_read_b128 v[196:199], v154 offset:50176
	ds_read_b128 v[200:203], v154 offset:51200
	ds_read_b128 v[204:207], v154 offset:52224
	ds_read_b128 v[208:211], v154 offset:53248
	ds_read_b128 v[212:215], v154 offset:54272
	ds_read_b128 v[216:219], v154 offset:55296
	ds_read_b128 v[220:223], v154 offset:56320
	global_load_lds_dwordx4 v[168:169], off
	v_lshl_add_u64 v[168:169], v[224:225], 0, s[6:7]
	s_add_i32 m0, s2, 0x2000
	s_add_i32 s2, s3, s12
	global_load_lds_dwordx4 v[168:169], off
	v_lshl_add_u64 v[168:169], v[226:227], 0, s[6:7]
	s_mov_b32 m0, s2
	s_nop 0
	global_load_lds_dwordx4 v[168:169], off
	v_lshl_add_u64 v[168:169], v[228:229], 0, s[6:7]
	s_add_i32 m0, s2, 0x2000
	s_nop 0
	global_load_lds_dwordx4 v[168:169], off
	v_lshl_add_u64 v[168:169], v[230:231], 0, s[6:7]
	s_mov_b32 m0, s20
	s_nop 0
	global_load_lds_dwordx4 v[168:169], off
	v_lshl_add_u64 v[168:169], v[232:233], 0, s[6:7]
	s_mov_b32 m0, s21
	s_nop 0
	global_load_lds_dwordx4 v[168:169], off
	s_waitcnt vmcnt(8)
	s_waitcnt lgkmcnt(0)
	v_mfma_f32_16x16x32_f16 v[60:63], v[156:159], v[192:195], v[60:63]
	v_mfma_f32_16x16x32_f16 v[56:59], v[164:167], v[192:195], v[56:59]
	v_mfma_f32_16x16x32_f16 v[52:55], v[156:159], v[200:203], v[52:55]
	v_mfma_f32_16x16x32_f16 v[44:47], v[164:167], v[200:203], v[44:47]
	s_barrier
	s_setprio 1
	s_waitcnt lgkmcnt(0)
	v_mfma_f32_16x16x32_f16 v[36:39], v[156:159], v[208:211], v[36:39]
	v_mfma_f32_16x16x32_f16 v[28:31], v[164:167], v[208:211], v[28:31]
	v_mfma_f32_16x16x32_f16 v[20:23], v[156:159], v[216:219], v[20:23]
	v_mfma_f32_16x16x32_f16 v[12:15], v[164:167], v[216:219], v[12:15]
	v_mfma_f32_16x16x32_f16 v[60:63], v[160:163], v[196:199], v[60:63]
	v_mfma_f32_16x16x32_f16 v[56:59], v[172:175], v[196:199], v[56:59]
	v_mfma_f32_16x16x32_f16 v[52:55], v[160:163], v[204:207], v[52:55]
	v_mfma_f32_16x16x32_f16 v[44:47], v[172:175], v[204:207], v[44:47]
	v_mfma_f32_16x16x32_f16 v[36:39], v[160:163], v[212:215], v[36:39]
	v_mfma_f32_16x16x32_f16 v[28:31], v[172:175], v[212:215], v[28:31]
	v_mfma_f32_16x16x32_f16 v[20:23], v[160:163], v[220:223], v[20:23]
	v_mfma_f32_16x16x32_f16 v[12:15], v[172:175], v[220:223], v[12:15]
	s_setprio 0
	s_setprio 1
	v_mfma_f32_16x16x32_f16 v[48:51], v[176:179], v[192:195], v[48:51]
	v_mfma_f32_16x16x32_f16 v[40:43], v[184:187], v[192:195], v[40:43]
	v_mfma_f32_16x16x32_f16 v[32:35], v[176:179], v[200:203], v[32:35]
	v_mfma_f32_16x16x32_f16 v[24:27], v[184:187], v[200:203], v[24:27]
	v_mfma_f32_16x16x32_f16 v[16:19], v[176:179], v[208:211], v[16:19]
	v_mfma_f32_16x16x32_f16 v[8:11], v[184:187], v[208:211], v[8:11]
	v_mfma_f32_16x16x32_f16 v[4:7], v[176:179], v[216:219], v[4:7]
	v_mfma_f32_16x16x32_f16 v[0:3], v[184:187], v[216:219], v[0:3]
	v_mfma_f32_16x16x32_f16 v[48:51], v[180:183], v[196:199], v[48:51]
	v_mfma_f32_16x16x32_f16 v[40:43], v[188:191], v[196:199], v[40:43]
	v_mfma_f32_16x16x32_f16 v[32:35], v[180:183], v[204:207], v[32:35]
	v_mfma_f32_16x16x32_f16 v[24:27], v[188:191], v[204:207], v[24:27]
	v_mfma_f32_16x16x32_f16 v[16:19], v[180:183], v[212:215], v[16:19]
	v_mfma_f32_16x16x32_f16 v[8:11], v[188:191], v[212:215], v[8:11]
	v_mfma_f32_16x16x32_f16 v[4:7], v[180:183], v[220:223], v[4:7]
	v_mfma_f32_16x16x32_f16 v[0:3], v[188:191], v[220:223], v[0:3]
	s_setprio 0
	s_barrier
	s_add_i32 s54, s54, 2
	s_add_u32 s44, s44, 0x100
	s_addc_u32 s45, s45, 0
	s_add_u32 s52, s52, 0x100
	s_addc_u32 s53, s53, 0
	s_cmp_gt_u32 s54, 13
	s_cbranch_scc0 .LBB0_589
	s_and_b64 vcc, exec, s[8:9]
	s_cbranch_vccz .LBB0_592
	s_barrier

.LBB0_609:
	ds_read_b128 v[156:159], v152
	ds_read_b128 v[160:163], v152 offset:1024
	ds_read_b128 v[164:167], v152 offset:2048
	ds_read_b128 v[172:175], v152 offset:3072
	ds_read_b128 v[176:179], v153
	ds_read_b128 v[180:183], v153 offset:1024
	ds_read_b128 v[184:187], v153 offset:2048
	ds_read_b128 v[188:191], v153 offset:3072
	s_add_u32 s2, s44, 0xfffc0080
	s_addc_u32 s3, s45, -1
	s_cmp_eq_u32 s53, 12
	s_cselect_b32 s47, s27, s3
	s_cselect_b32 s46, s49, s2
	s_cselect_b32 s55, s25, s52
	s_cselect_b32 s54, s50, s51
	v_lshl_add_u64 v[168:169], s[44:45], 0, v[142:143]
	s_add_i32 m0, s15, 0xc000
	ds_read_b128 v[192:195], v154
	ds_read_b128 v[196:199], v154 offset:1024
	ds_read_b128 v[200:203], v154 offset:2048
	ds_read_b128 v[204:207], v154 offset:3072
	ds_read_b128 v[208:211], v154 offset:4096
	ds_read_b128 v[212:215], v154 offset:5120
	ds_read_b128 v[216:219], v154 offset:6144
	ds_read_b128 v[220:223], v154 offset:7168
	global_load_lds_dwordx4 v[168:169], off
	v_lshl_add_u64 v[168:169], s[44:45], 0, v[144:145]
	s_add_i32 m0, s15, 0xe000
	s_nop 0
	global_load_lds_dwordx4 v[168:169], off
	s_waitcnt vmcnt(8)
	s_waitcnt lgkmcnt(0)
	v_mfma_f32_16x16x32_f16 v[124:127], v[156:159], v[192:195], v[124:127]
	v_mfma_f32_16x16x32_f16 v[120:123], v[164:167], v[192:195], v[120:123]
	v_mfma_f32_16x16x32_f16 v[116:119], v[156:159], v[200:203], v[116:119]
	v_mfma_f32_16x16x32_f16 v[112:115], v[164:167], v[200:203], v[112:115]
	s_barrier
	s_setprio 1
	s_waitcnt lgkmcnt(0)
	v_mfma_f32_16x16x32_f16 v[100:103], v[156:159], v[208:211], v[100:103]
	v_mfma_f32_16x16x32_f16 v[96:99], v[164:167], v[208:211], v[96:99]
	v_mfma_f32_16x16x32_f16 v[84:87], v[156:159], v[216:219], v[84:87]
	v_mfma_f32_16x16x32_f16 v[80:83], v[164:167], v[216:219], v[80:83]
	v_mfma_f32_16x16x32_f16 v[124:127], v[160:163], v[196:199], v[124:127]
	v_mfma_f32_16x16x32_f16 v[120:123], v[172:175], v[196:199], v[120:123]
	v_mfma_f32_16x16x32_f16 v[116:119], v[160:163], v[204:207], v[116:119]
	v_mfma_f32_16x16x32_f16 v[112:115], v[172:175], v[204:207], v[112:115]
	v_mfma_f32_16x16x32_f16 v[100:103], v[160:163], v[212:215], v[100:103]
	v_mfma_f32_16x16x32_f16 v[96:99], v[172:175], v[212:215], v[96:99]
	v_mfma_f32_16x16x32_f16 v[84:87], v[160:163], v[220:223], v[84:87]
	v_mfma_f32_16x16x32_f16 v[80:83], v[172:175], v[220:223], v[80:83]
	s_setprio 0
	s_setprio 1
	v_mfma_f32_16x16x32_f16 v[108:111], v[176:179], v[192:195], v[108:111]
	v_mfma_f32_16x16x32_f16 v[104:107], v[184:187], v[192:195], v[104:107]
	v_mfma_f32_16x16x32_f16 v[92:95], v[176:179], v[200:203], v[92:95]
	v_mfma_f32_16x16x32_f16 v[88:91], v[184:187], v[200:203], v[88:91]
	v_mfma_f32_16x16x32_f16 v[76:79], v[176:179], v[208:211], v[76:79]
	v_mfma_f32_16x16x32_f16 v[72:75], v[184:187], v[208:211], v[72:75]
	v_mfma_f32_16x16x32_f16 v[68:71], v[176:179], v[216:219], v[68:71]
	v_mfma_f32_16x16x32_f16 v[64:67], v[184:187], v[216:219], v[64:67]
	v_mfma_f32_16x16x32_f16 v[108:111], v[180:183], v[196:199], v[108:111]
	v_mfma_f32_16x16x32_f16 v[104:107], v[188:191], v[196:199], v[104:107]
	v_mfma_f32_16x16x32_f16 v[92:95], v[180:183], v[204:207], v[92:95]
	v_mfma_f32_16x16x32_f16 v[88:91], v[188:191], v[204:207], v[88:91]
	v_mfma_f32_16x16x32_f16 v[76:79], v[180:183], v[212:215], v[76:79]
	v_mfma_f32_16x16x32_f16 v[72:75], v[188:191], v[212:215], v[72:75]
	v_mfma_f32_16x16x32_f16 v[68:71], v[180:183], v[220:223], v[68:71]
	v_mfma_f32_16x16x32_f16 v[64:67], v[188:191], v[220:223], v[64:67]
	s_setprio 0
	s_barrier
	s_add_i32 s2, s21, s14
	v_lshl_add_u64 v[168:169], s[54:55], 0, v[134:135]
	s_mov_b32 m0, s2
	ds_read_b128 v[192:195], v154 offset:16384
	ds_read_b128 v[196:199], v154 offset:17408
	ds_read_b128 v[200:203], v154 offset:18432
	ds_read_b128 v[204:207], v154 offset:19456
	ds_read_b128 v[208:211], v154 offset:20480
	ds_read_b128 v[212:215], v154 offset:21504
	ds_read_b128 v[216:219], v154 offset:22528
	ds_read_b128 v[220:223], v154 offset:23552
	global_load_lds_dwordx4 v[168:169], off
	v_lshl_add_u64 v[224:225], s[54:55], 0, v[128:129]
	s_add_i32 m0, s2, 0x2000
	s_add_i32 s2, s28, s14
	global_load_lds_dwordx4 v[224:225], off
	v_lshl_add_u64 v[226:227], s[54:55], 0, v[136:137]
	s_mov_b32 m0, s2
	v_lshl_add_u64 v[228:229], s[54:55], 0, v[130:131]
	global_load_lds_dwordx4 v[226:227], off
	s_add_i32 m0, s2, 0x2000
	v_lshl_add_u64 v[230:231], s[46:47], 0, v[138:139]
	global_load_lds_dwordx4 v[228:229], off
	s_mov_b32 m0, s15
	v_lshl_add_u64 v[232:233], s[46:47], 0, v[132:133]
	global_load_lds_dwordx4 v[230:231], off
	s_mov_b32 m0, s16
	s_nop 0
	global_load_lds_dwordx4 v[232:233], off
	s_waitcnt vmcnt(8)
	s_waitcnt lgkmcnt(0)
	v_mfma_f32_16x16x32_f16 v[60:63], v[156:159], v[192:195], v[60:63]
	v_mfma_f32_16x16x32_f16 v[56:59], v[164:167], v[192:195], v[56:59]
	v_mfma_f32_16x16x32_f16 v[52:55], v[156:159], v[200:203], v[52:55]
	v_mfma_f32_16x16x32_f16 v[48:51], v[164:167], v[200:203], v[48:51]
	s_barrier
	s_setprio 1
	s_waitcnt lgkmcnt(0)
	v_mfma_f32_16x16x32_f16 v[36:39], v[156:159], v[208:211], v[36:39]
	v_mfma_f32_16x16x32_f16 v[32:35], v[164:167], v[208:211], v[32:35]
	v_mfma_f32_16x16x32_f16 v[20:23], v[156:159], v[216:219], v[20:23]
	v_mfma_f32_16x16x32_f16 v[16:19], v[164:167], v[216:219], v[16:19]
	v_mfma_f32_16x16x32_f16 v[60:63], v[160:163], v[196:199], v[60:63]
	v_mfma_f32_16x16x32_f16 v[56:59], v[172:175], v[196:199], v[56:59]
	v_mfma_f32_16x16x32_f16 v[52:55], v[160:163], v[204:207], v[52:55]
	v_mfma_f32_16x16x32_f16 v[48:51], v[172:175], v[204:207], v[48:51]
	v_mfma_f32_16x16x32_f16 v[36:39], v[160:163], v[212:215], v[36:39]
	v_mfma_f32_16x16x32_f16 v[32:35], v[172:175], v[212:215], v[32:35]
	v_mfma_f32_16x16x32_f16 v[20:23], v[160:163], v[220:223], v[20:23]
	v_mfma_f32_16x16x32_f16 v[16:19], v[172:175], v[220:223], v[16:19]
	s_setprio 0
	s_setprio 1
	v_mfma_f32_16x16x32_f16 v[44:47], v[176:179], v[192:195], v[44:47]
	v_mfma_f32_16x16x32_f16 v[40:43], v[184:187], v[192:195], v[40:43]
	v_mfma_f32_16x16x32_f16 v[28:31], v[176:179], v[200:203], v[28:31]
	v_mfma_f32_16x16x32_f16 v[24:27], v[184:187], v[200:203], v[24:27]
	v_mfma_f32_16x16x32_f16 v[12:15], v[176:179], v[208:211], v[12:15]
	v_mfma_f32_16x16x32_f16 v[8:11], v[184:187], v[208:211], v[8:11]
	v_mfma_f32_16x16x32_f16 v[4:7], v[176:179], v[216:219], v[4:7]
	v_mfma_f32_16x16x32_f16 v[0:3], v[184:187], v[216:219], v[0:3]
	v_mfma_f32_16x16x32_f16 v[44:47], v[180:183], v[196:199], v[44:47]
	v_mfma_f32_16x16x32_f16 v[40:43], v[188:191], v[196:199], v[40:43]
	v_mfma_f32_16x16x32_f16 v[28:31], v[180:183], v[204:207], v[28:31]
	v_mfma_f32_16x16x32_f16 v[24:27], v[188:191], v[204:207], v[24:27]
	v_mfma_f32_16x16x32_f16 v[12:15], v[180:183], v[212:215], v[12:15]
	v_mfma_f32_16x16x32_f16 v[8:11], v[188:191], v[212:215], v[8:11]
	v_mfma_f32_16x16x32_f16 v[4:7], v[180:183], v[220:223], v[4:7]
	v_mfma_f32_16x16x32_f16 v[0:3], v[188:191], v[220:223], v[0:3]
	s_setprio 0
	s_barrier
	s_add_i32 s2, 0, 0x18000
	v_add_u32_e32 v155, s2, v151
	s_add_i32 s3, 0, 0x1c000
	ds_read_b128 v[156:159], v155
	ds_read_b128 v[160:163], v155 offset:1024
	ds_read_b128 v[164:167], v155 offset:2048
	ds_read_b128 v[172:175], v155 offset:3072
	v_add_u32_e32 v155, s3, v151
	ds_read_b128 v[176:179], v155
	ds_read_b128 v[180:183], v155 offset:1024
	ds_read_b128 v[184:187], v155 offset:2048
	ds_read_b128 v[188:191], v155 offset:3072
	s_add_u32 s46, s46, 0x40000
	s_addc_u32 s47, s47, 0
	s_mov_b32 m0, s17
	v_lshl_add_u64 v[234:235], s[46:47], 0, v[138:139]
	ds_read_b128 v[192:195], v154 offset:32768
	ds_read_b128 v[196:199], v154 offset:33792
	ds_read_b128 v[200:203], v154 offset:34816
	ds_read_b128 v[204:207], v154 offset:35840
	ds_read_b128 v[208:211], v154 offset:36864
	ds_read_b128 v[212:215], v154 offset:37888
	ds_read_b128 v[216:219], v154 offset:38912
	ds_read_b128 v[220:223], v154 offset:39936
	global_load_lds_dwordx4 v[234:235], off
	v_lshl_add_u64 v[234:235], s[46:47], 0, v[132:133]
	s_mov_b32 m0, s18
	s_nop 0
	global_load_lds_dwordx4 v[234:235], off
	s_waitcnt vmcnt(8)
	s_waitcnt lgkmcnt(0)
	v_mfma_f32_16x16x32_f16 v[124:127], v[156:159], v[192:195], v[124:127]
	v_mfma_f32_16x16x32_f16 v[120:123], v[164:167], v[192:195], v[120:123]
	v_mfma_f32_16x16x32_f16 v[116:119], v[156:159], v[200:203], v[116:119]
	v_mfma_f32_16x16x32_f16 v[112:115], v[164:167], v[200:203], v[112:115]
	s_barrier
	s_setprio 1
	s_waitcnt lgkmcnt(0)
	v_mfma_f32_16x16x32_f16 v[100:103], v[156:159], v[208:211], v[100:103]
	v_mfma_f32_16x16x32_f16 v[96:99], v[164:167], v[208:211], v[96:99]
	v_mfma_f32_16x16x32_f16 v[84:87], v[156:159], v[216:219], v[84:87]
	v_mfma_f32_16x16x32_f16 v[80:83], v[164:167], v[216:219], v[80:83]
	v_mfma_f32_16x16x32_f16 v[124:127], v[160:163], v[196:199], v[124:127]
	v_mfma_f32_16x16x32_f16 v[120:123], v[172:175], v[196:199], v[120:123]
	v_mfma_f32_16x16x32_f16 v[116:119], v[160:163], v[204:207], v[116:119]
	v_mfma_f32_16x16x32_f16 v[112:115], v[172:175], v[204:207], v[112:115]
	v_mfma_f32_16x16x32_f16 v[100:103], v[160:163], v[212:215], v[100:103]
	v_mfma_f32_16x16x32_f16 v[96:99], v[172:175], v[212:215], v[96:99]
	v_mfma_f32_16x16x32_f16 v[84:87], v[160:163], v[220:223], v[84:87]
	v_mfma_f32_16x16x32_f16 v[80:83], v[172:175], v[220:223], v[80:83]
	s_setprio 0
	s_setprio 1
	v_mfma_f32_16x16x32_f16 v[108:111], v[176:179], v[192:195], v[108:111]
	v_mfma_f32_16x16x32_f16 v[104:107], v[184:187], v[192:195], v[104:107]
	v_mfma_f32_16x16x32_f16 v[92:95], v[176:179], v[200:203], v[92:95]
	v_mfma_f32_16x16x32_f16 v[88:91], v[184:187], v[200:203], v[88:91]
	v_mfma_f32_16x16x32_f16 v[76:79], v[176:179], v[208:211], v[76:79]
	v_mfma_f32_16x16x32_f16 v[72:75], v[184:187], v[208:211], v[72:75]
	v_mfma_f32_16x16x32_f16 v[68:71], v[176:179], v[216:219], v[68:71]
	v_mfma_f32_16x16x32_f16 v[64:67], v[184:187], v[216:219], v[64:67]
	v_mfma_f32_16x16x32_f16 v[108:111], v[180:183], v[196:199], v[108:111]
	v_mfma_f32_16x16x32_f16 v[104:107], v[188:191], v[196:199], v[104:107]
	v_mfma_f32_16x16x32_f16 v[92:95], v[180:183], v[204:207], v[92:95]
	v_mfma_f32_16x16x32_f16 v[88:91], v[188:191], v[204:207], v[88:91]
	v_mfma_f32_16x16x32_f16 v[76:79], v[180:183], v[212:215], v[76:79]
	v_mfma_f32_16x16x32_f16 v[72:75], v[188:191], v[212:215], v[72:75]
	v_mfma_f32_16x16x32_f16 v[68:71], v[180:183], v[220:223], v[68:71]
	v_mfma_f32_16x16x32_f16 v[64:67], v[188:191], v[220:223], v[64:67]
	s_setprio 0
	s_barrier
	s_add_i32 s2, s2, s14
	v_lshl_add_u64 v[168:169], v[168:169], 0, s[8:9]
	s_mov_b32 m0, s2
	ds_read_b128 v[192:195], v154 offset:49152
	ds_read_b128 v[196:199], v154 offset:50176
	ds_read_b128 v[200:203], v154 offset:51200
	ds_read_b128 v[204:207], v154 offset:52224
	ds_read_b128 v[208:211], v154 offset:53248
	ds_read_b128 v[212:215], v154 offset:54272
	ds_read_b128 v[216:219], v154 offset:55296
	ds_read_b128 v[220:223], v154 offset:56320
	global_load_lds_dwordx4 v[168:169], off
	v_lshl_add_u64 v[168:169], v[224:225], 0, s[8:9]
	s_add_i32 m0, s2, 0x2000
	s_add_i32 s2, s3, s14
	global_load_lds_dwordx4 v[168:169], off
	v_lshl_add_u64 v[168:169], v[226:227], 0, s[8:9]
	s_mov_b32 m0, s2
	s_nop 0
	global_load_lds_dwordx4 v[168:169], off
	v_lshl_add_u64 v[168:169], v[228:229], 0, s[8:9]
	s_add_i32 m0, s2, 0x2000
	s_nop 0
	global_load_lds_dwordx4 v[168:169], off
	v_lshl_add_u64 v[168:169], v[230:231], 0, s[8:9]
	s_mov_b32 m0, s19
	s_nop 0
	global_load_lds_dwordx4 v[168:169], off
	v_lshl_add_u64 v[168:169], v[232:233], 0, s[8:9]
	s_mov_b32 m0, s20
	s_nop 0
	global_load_lds_dwordx4 v[168:169], off
	s_waitcnt vmcnt(8)
	s_waitcnt lgkmcnt(0)
	v_mfma_f32_16x16x32_f16 v[60:63], v[156:159], v[192:195], v[60:63]
	v_mfma_f32_16x16x32_f16 v[56:59], v[164:167], v[192:195], v[56:59]
	v_mfma_f32_16x16x32_f16 v[52:55], v[156:159], v[200:203], v[52:55]
	v_mfma_f32_16x16x32_f16 v[48:51], v[164:167], v[200:203], v[48:51]
	s_barrier
	s_setprio 1
	s_waitcnt lgkmcnt(0)
	v_mfma_f32_16x16x32_f16 v[36:39], v[156:159], v[208:211], v[36:39]
	v_mfma_f32_16x16x32_f16 v[32:35], v[164:167], v[208:211], v[32:35]
	v_mfma_f32_16x16x32_f16 v[20:23], v[156:159], v[216:219], v[20:23]
	v_mfma_f32_16x16x32_f16 v[16:19], v[164:167], v[216:219], v[16:19]
	v_mfma_f32_16x16x32_f16 v[60:63], v[160:163], v[196:199], v[60:63]
	v_mfma_f32_16x16x32_f16 v[56:59], v[172:175], v[196:199], v[56:59]
	v_mfma_f32_16x16x32_f16 v[52:55], v[160:163], v[204:207], v[52:55]
	v_mfma_f32_16x16x32_f16 v[48:51], v[172:175], v[204:207], v[48:51]
	v_mfma_f32_16x16x32_f16 v[36:39], v[160:163], v[212:215], v[36:39]
	v_mfma_f32_16x16x32_f16 v[32:35], v[172:175], v[212:215], v[32:35]
	v_mfma_f32_16x16x32_f16 v[20:23], v[160:163], v[220:223], v[20:23]
	v_mfma_f32_16x16x32_f16 v[16:19], v[172:175], v[220:223], v[16:19]
	s_setprio 0
	s_setprio 1
	v_mfma_f32_16x16x32_f16 v[44:47], v[176:179], v[192:195], v[44:47]
	v_mfma_f32_16x16x32_f16 v[40:43], v[184:187], v[192:195], v[40:43]
	v_mfma_f32_16x16x32_f16 v[28:31], v[176:179], v[200:203], v[28:31]
	v_mfma_f32_16x16x32_f16 v[24:27], v[184:187], v[200:203], v[24:27]
	v_mfma_f32_16x16x32_f16 v[12:15], v[176:179], v[208:211], v[12:15]
	v_mfma_f32_16x16x32_f16 v[8:11], v[184:187], v[208:211], v[8:11]
	v_mfma_f32_16x16x32_f16 v[4:7], v[176:179], v[216:219], v[4:7]
	v_mfma_f32_16x16x32_f16 v[0:3], v[184:187], v[216:219], v[0:3]
	v_mfma_f32_16x16x32_f16 v[44:47], v[180:183], v[196:199], v[44:47]
	v_mfma_f32_16x16x32_f16 v[40:43], v[188:191], v[196:199], v[40:43]
	v_mfma_f32_16x16x32_f16 v[28:31], v[180:183], v[204:207], v[28:31]
	v_mfma_f32_16x16x32_f16 v[24:27], v[188:191], v[204:207], v[24:27]
	v_mfma_f32_16x16x32_f16 v[12:15], v[180:183], v[212:215], v[12:15]
	v_mfma_f32_16x16x32_f16 v[8:11], v[188:191], v[212:215], v[8:11]
	v_mfma_f32_16x16x32_f16 v[4:7], v[180:183], v[220:223], v[4:7]
	v_mfma_f32_16x16x32_f16 v[0:3], v[188:191], v[220:223], v[0:3]
	s_setprio 0
	s_barrier
	s_add_i32 s53, s53, 2
	s_add_u32 s44, s44, 0x100
	s_addc_u32 s45, s45, 0
	s_add_u32 s51, s51, 0x100
	s_addc_u32 s52, s52, 0
	s_cmp_gt_u32 s53, 13
	s_cbranch_scc0 .LBB0_609
	s_and_b64 vcc, exec, s[22:23]
	s_cbranch_vccz .LBB0_612
	s_barrier

.LBB0_629:
	ds_read_b128 v[156:159], v152
	ds_read_b128 v[160:163], v152 offset:1024
	ds_read_b128 v[164:167], v152 offset:2048
	ds_read_b128 v[172:175], v152 offset:3072
	ds_read_b128 v[176:179], v153
	ds_read_b128 v[180:183], v153 offset:1024
	ds_read_b128 v[184:187], v153 offset:2048
	ds_read_b128 v[188:191], v153 offset:3072
	s_add_u32 s2, s48, 0xfffc0080
	s_addc_u32 s3, s49, -1
	s_cmp_eq_u32 s55, 12
	s_cselect_b32 s51, s27, s3
	s_cselect_b32 s50, s35, s2
	s_cselect_b32 s57, s31, s54
	s_cselect_b32 s56, s52, s53
	v_lshl_add_u64 v[168:169], s[48:49], 0, v[142:143]
	s_add_i32 m0, s15, 0xc000
	ds_read_b128 v[192:195], v154
	ds_read_b128 v[196:199], v154 offset:1024
	ds_read_b128 v[200:203], v154 offset:2048
	ds_read_b128 v[204:207], v154 offset:3072
	ds_read_b128 v[208:211], v154 offset:4096
	ds_read_b128 v[212:215], v154 offset:5120
	ds_read_b128 v[216:219], v154 offset:6144
	ds_read_b128 v[220:223], v154 offset:7168
	global_load_lds_dwordx4 v[168:169], off
	v_lshl_add_u64 v[168:169], s[48:49], 0, v[144:145]
	s_add_i32 m0, s15, 0xe000
	s_nop 0
	global_load_lds_dwordx4 v[168:169], off
	s_waitcnt vmcnt(8)
	s_waitcnt lgkmcnt(0)
	v_mfma_f32_16x16x32_f16 v[124:127], v[156:159], v[192:195], v[124:127]
	v_mfma_f32_16x16x32_f16 v[120:123], v[164:167], v[192:195], v[120:123]
	v_mfma_f32_16x16x32_f16 v[116:119], v[156:159], v[200:203], v[116:119]
	v_mfma_f32_16x16x32_f16 v[108:111], v[164:167], v[200:203], v[108:111]
	s_barrier
	s_setprio 1
	s_waitcnt lgkmcnt(0)
	v_mfma_f32_16x16x32_f16 v[100:103], v[156:159], v[208:211], v[100:103]
	v_mfma_f32_16x16x32_f16 v[92:95], v[164:167], v[208:211], v[92:95]
	v_mfma_f32_16x16x32_f16 v[84:87], v[156:159], v[216:219], v[84:87]
	v_mfma_f32_16x16x32_f16 v[76:79], v[164:167], v[216:219], v[76:79]
	v_mfma_f32_16x16x32_f16 v[124:127], v[160:163], v[196:199], v[124:127]
	v_mfma_f32_16x16x32_f16 v[120:123], v[172:175], v[196:199], v[120:123]
	v_mfma_f32_16x16x32_f16 v[116:119], v[160:163], v[204:207], v[116:119]
	v_mfma_f32_16x16x32_f16 v[108:111], v[172:175], v[204:207], v[108:111]
	v_mfma_f32_16x16x32_f16 v[100:103], v[160:163], v[212:215], v[100:103]
	v_mfma_f32_16x16x32_f16 v[92:95], v[172:175], v[212:215], v[92:95]
	v_mfma_f32_16x16x32_f16 v[84:87], v[160:163], v[220:223], v[84:87]
	v_mfma_f32_16x16x32_f16 v[76:79], v[172:175], v[220:223], v[76:79]
	s_setprio 0
	s_setprio 1
	v_mfma_f32_16x16x32_f16 v[112:115], v[176:179], v[192:195], v[112:115]
	v_mfma_f32_16x16x32_f16 v[104:107], v[184:187], v[192:195], v[104:107]
	v_mfma_f32_16x16x32_f16 v[96:99], v[176:179], v[200:203], v[96:99]
	v_mfma_f32_16x16x32_f16 v[88:91], v[184:187], v[200:203], v[88:91]
	v_mfma_f32_16x16x32_f16 v[80:83], v[176:179], v[208:211], v[80:83]
	v_mfma_f32_16x16x32_f16 v[72:75], v[184:187], v[208:211], v[72:75]
	v_mfma_f32_16x16x32_f16 v[68:71], v[176:179], v[216:219], v[68:71]
	v_mfma_f32_16x16x32_f16 v[64:67], v[184:187], v[216:219], v[64:67]
	v_mfma_f32_16x16x32_f16 v[112:115], v[180:183], v[196:199], v[112:115]
	v_mfma_f32_16x16x32_f16 v[104:107], v[188:191], v[196:199], v[104:107]
	v_mfma_f32_16x16x32_f16 v[96:99], v[180:183], v[204:207], v[96:99]
	v_mfma_f32_16x16x32_f16 v[88:91], v[188:191], v[204:207], v[88:91]
	v_mfma_f32_16x16x32_f16 v[80:83], v[180:183], v[212:215], v[80:83]
	v_mfma_f32_16x16x32_f16 v[72:75], v[188:191], v[212:215], v[72:75]
	v_mfma_f32_16x16x32_f16 v[68:71], v[180:183], v[220:223], v[68:71]
	v_mfma_f32_16x16x32_f16 v[64:67], v[188:191], v[220:223], v[64:67]
	s_setprio 0
	s_barrier
	s_add_i32 s2, s21, s14
	v_lshl_add_u64 v[168:169], s[56:57], 0, v[136:137]
	s_mov_b32 m0, s2
	ds_read_b128 v[192:195], v154 offset:16384
	ds_read_b128 v[196:199], v154 offset:17408
	ds_read_b128 v[200:203], v154 offset:18432
	ds_read_b128 v[204:207], v154 offset:19456
	ds_read_b128 v[208:211], v154 offset:20480
	ds_read_b128 v[212:215], v154 offset:21504
	ds_read_b128 v[216:219], v154 offset:22528
	ds_read_b128 v[220:223], v154 offset:23552
	global_load_lds_dwordx4 v[168:169], off
	v_lshl_add_u64 v[224:225], s[56:57], 0, v[130:131]
	s_add_i32 m0, s2, 0x2000
	s_add_i32 s2, s28, s14
	global_load_lds_dwordx4 v[224:225], off
	v_lshl_add_u64 v[226:227], s[56:57], 0, v[134:135]
	s_mov_b32 m0, s2
	v_lshl_add_u64 v[228:229], s[56:57], 0, v[128:129]
	global_load_lds_dwordx4 v[226:227], off
	s_add_i32 m0, s2, 0x2000
	v_lshl_add_u64 v[230:231], s[50:51], 0, v[138:139]
	global_load_lds_dwordx4 v[228:229], off
	s_mov_b32 m0, s15
	v_lshl_add_u64 v[232:233], s[50:51], 0, v[132:133]
	global_load_lds_dwordx4 v[230:231], off
	s_mov_b32 m0, s16
	s_nop 0
	global_load_lds_dwordx4 v[232:233], off
	s_waitcnt vmcnt(8)
	s_waitcnt lgkmcnt(0)
	v_mfma_f32_16x16x32_f16 v[60:63], v[156:159], v[192:195], v[60:63]
	v_mfma_f32_16x16x32_f16 v[56:59], v[164:167], v[192:195], v[56:59]
	v_mfma_f32_16x16x32_f16 v[52:55], v[156:159], v[200:203], v[52:55]
	v_mfma_f32_16x16x32_f16 v[48:51], v[164:167], v[200:203], v[48:51]
	s_barrier
	s_setprio 1
	s_waitcnt lgkmcnt(0)
	v_mfma_f32_16x16x32_f16 v[36:39], v[156:159], v[208:211], v[36:39]
	v_mfma_f32_16x16x32_f16 v[32:35], v[164:167], v[208:211], v[32:35]
	v_mfma_f32_16x16x32_f16 v[20:23], v[156:159], v[216:219], v[20:23]
	v_mfma_f32_16x16x32_f16 v[16:19], v[164:167], v[216:219], v[16:19]
	v_mfma_f32_16x16x32_f16 v[60:63], v[160:163], v[196:199], v[60:63]
	v_mfma_f32_16x16x32_f16 v[56:59], v[172:175], v[196:199], v[56:59]
	v_mfma_f32_16x16x32_f16 v[52:55], v[160:163], v[204:207], v[52:55]
	v_mfma_f32_16x16x32_f16 v[48:51], v[172:175], v[204:207], v[48:51]
	v_mfma_f32_16x16x32_f16 v[36:39], v[160:163], v[212:215], v[36:39]
	v_mfma_f32_16x16x32_f16 v[32:35], v[172:175], v[212:215], v[32:35]
	v_mfma_f32_16x16x32_f16 v[20:23], v[160:163], v[220:223], v[20:23]
	v_mfma_f32_16x16x32_f16 v[16:19], v[172:175], v[220:223], v[16:19]
	s_setprio 0
	s_setprio 1
	v_mfma_f32_16x16x32_f16 v[44:47], v[176:179], v[192:195], v[44:47]
	v_mfma_f32_16x16x32_f16 v[40:43], v[184:187], v[192:195], v[40:43]
	v_mfma_f32_16x16x32_f16 v[28:31], v[176:179], v[200:203], v[28:31]
	v_mfma_f32_16x16x32_f16 v[24:27], v[184:187], v[200:203], v[24:27]
	v_mfma_f32_16x16x32_f16 v[12:15], v[176:179], v[208:211], v[12:15]
	v_mfma_f32_16x16x32_f16 v[8:11], v[184:187], v[208:211], v[8:11]
	v_mfma_f32_16x16x32_f16 v[4:7], v[176:179], v[216:219], v[4:7]
	v_mfma_f32_16x16x32_f16 v[0:3], v[184:187], v[216:219], v[0:3]
	v_mfma_f32_16x16x32_f16 v[44:47], v[180:183], v[196:199], v[44:47]
	v_mfma_f32_16x16x32_f16 v[40:43], v[188:191], v[196:199], v[40:43]
	v_mfma_f32_16x16x32_f16 v[28:31], v[180:183], v[204:207], v[28:31]
	v_mfma_f32_16x16x32_f16 v[24:27], v[188:191], v[204:207], v[24:27]
	v_mfma_f32_16x16x32_f16 v[12:15], v[180:183], v[212:215], v[12:15]
	v_mfma_f32_16x16x32_f16 v[8:11], v[188:191], v[212:215], v[8:11]
	v_mfma_f32_16x16x32_f16 v[4:7], v[180:183], v[220:223], v[4:7]
	v_mfma_f32_16x16x32_f16 v[0:3], v[188:191], v[220:223], v[0:3]
	s_setprio 0
	s_barrier
	s_add_i32 s2, 0, 0x18000
	v_add_u32_e32 v155, s2, v151
	s_add_i32 s3, 0, 0x1c000
	ds_read_b128 v[156:159], v155
	ds_read_b128 v[160:163], v155 offset:1024
	ds_read_b128 v[164:167], v155 offset:2048
	ds_read_b128 v[172:175], v155 offset:3072
	v_add_u32_e32 v155, s3, v151
	ds_read_b128 v[176:179], v155
	ds_read_b128 v[180:183], v155 offset:1024
	ds_read_b128 v[184:187], v155 offset:2048
	ds_read_b128 v[188:191], v155 offset:3072
	s_add_u32 s50, s50, 0x40000
	s_addc_u32 s51, s51, 0
	s_mov_b32 m0, s17
	v_lshl_add_u64 v[234:235], s[50:51], 0, v[138:139]
	ds_read_b128 v[192:195], v154 offset:32768
	ds_read_b128 v[196:199], v154 offset:33792
	ds_read_b128 v[200:203], v154 offset:34816
	ds_read_b128 v[204:207], v154 offset:35840
	ds_read_b128 v[208:211], v154 offset:36864
	ds_read_b128 v[212:215], v154 offset:37888
	ds_read_b128 v[216:219], v154 offset:38912
	ds_read_b128 v[220:223], v154 offset:39936
	global_load_lds_dwordx4 v[234:235], off
	v_lshl_add_u64 v[234:235], s[50:51], 0, v[132:133]
	s_mov_b32 m0, s18
	s_nop 0
	global_load_lds_dwordx4 v[234:235], off
	s_waitcnt vmcnt(8)
	s_waitcnt lgkmcnt(0)
	v_mfma_f32_16x16x32_f16 v[124:127], v[156:159], v[192:195], v[124:127]
	v_mfma_f32_16x16x32_f16 v[120:123], v[164:167], v[192:195], v[120:123]
	v_mfma_f32_16x16x32_f16 v[116:119], v[156:159], v[200:203], v[116:119]
	v_mfma_f32_16x16x32_f16 v[108:111], v[164:167], v[200:203], v[108:111]
	s_barrier
	s_setprio 1
	s_waitcnt lgkmcnt(0)
	v_mfma_f32_16x16x32_f16 v[100:103], v[156:159], v[208:211], v[100:103]
	v_mfma_f32_16x16x32_f16 v[92:95], v[164:167], v[208:211], v[92:95]
	v_mfma_f32_16x16x32_f16 v[84:87], v[156:159], v[216:219], v[84:87]
	v_mfma_f32_16x16x32_f16 v[76:79], v[164:167], v[216:219], v[76:79]
	v_mfma_f32_16x16x32_f16 v[124:127], v[160:163], v[196:199], v[124:127]
	v_mfma_f32_16x16x32_f16 v[120:123], v[172:175], v[196:199], v[120:123]
	v_mfma_f32_16x16x32_f16 v[116:119], v[160:163], v[204:207], v[116:119]
	v_mfma_f32_16x16x32_f16 v[108:111], v[172:175], v[204:207], v[108:111]
	v_mfma_f32_16x16x32_f16 v[100:103], v[160:163], v[212:215], v[100:103]
	v_mfma_f32_16x16x32_f16 v[92:95], v[172:175], v[212:215], v[92:95]
	v_mfma_f32_16x16x32_f16 v[84:87], v[160:163], v[220:223], v[84:87]
	v_mfma_f32_16x16x32_f16 v[76:79], v[172:175], v[220:223], v[76:79]
	s_setprio 0
	s_setprio 1
	v_mfma_f32_16x16x32_f16 v[112:115], v[176:179], v[192:195], v[112:115]
	v_mfma_f32_16x16x32_f16 v[104:107], v[184:187], v[192:195], v[104:107]
	v_mfma_f32_16x16x32_f16 v[96:99], v[176:179], v[200:203], v[96:99]
	v_mfma_f32_16x16x32_f16 v[88:91], v[184:187], v[200:203], v[88:91]
	v_mfma_f32_16x16x32_f16 v[80:83], v[176:179], v[208:211], v[80:83]
	v_mfma_f32_16x16x32_f16 v[72:75], v[184:187], v[208:211], v[72:75]
	v_mfma_f32_16x16x32_f16 v[68:71], v[176:179], v[216:219], v[68:71]
	v_mfma_f32_16x16x32_f16 v[64:67], v[184:187], v[216:219], v[64:67]
	v_mfma_f32_16x16x32_f16 v[112:115], v[180:183], v[196:199], v[112:115]
	v_mfma_f32_16x16x32_f16 v[104:107], v[188:191], v[196:199], v[104:107]
	v_mfma_f32_16x16x32_f16 v[96:99], v[180:183], v[204:207], v[96:99]
	v_mfma_f32_16x16x32_f16 v[88:91], v[188:191], v[204:207], v[88:91]
	v_mfma_f32_16x16x32_f16 v[80:83], v[180:183], v[212:215], v[80:83]
	v_mfma_f32_16x16x32_f16 v[72:75], v[188:191], v[212:215], v[72:75]
	v_mfma_f32_16x16x32_f16 v[68:71], v[180:183], v[220:223], v[68:71]
	v_mfma_f32_16x16x32_f16 v[64:67], v[188:191], v[220:223], v[64:67]
	s_setprio 0
	s_barrier
	s_add_i32 s2, s2, s14
	v_lshl_add_u64 v[168:169], v[168:169], 0, s[8:9]
	s_mov_b32 m0, s2
	ds_read_b128 v[192:195], v154 offset:49152
	ds_read_b128 v[196:199], v154 offset:50176
	ds_read_b128 v[200:203], v154 offset:51200
	ds_read_b128 v[204:207], v154 offset:52224
	ds_read_b128 v[208:211], v154 offset:53248
	ds_read_b128 v[212:215], v154 offset:54272
	ds_read_b128 v[216:219], v154 offset:55296
	ds_read_b128 v[220:223], v154 offset:56320
	global_load_lds_dwordx4 v[168:169], off
	v_lshl_add_u64 v[168:169], v[224:225], 0, s[8:9]
	s_add_i32 m0, s2, 0x2000
	s_add_i32 s2, s3, s14
	global_load_lds_dwordx4 v[168:169], off
	v_lshl_add_u64 v[168:169], v[226:227], 0, s[8:9]
	s_mov_b32 m0, s2
	s_nop 0
	global_load_lds_dwordx4 v[168:169], off
	v_lshl_add_u64 v[168:169], v[228:229], 0, s[8:9]
	s_add_i32 m0, s2, 0x2000
	s_nop 0
	global_load_lds_dwordx4 v[168:169], off
	v_lshl_add_u64 v[168:169], v[230:231], 0, s[8:9]
	s_mov_b32 m0, s19
	s_nop 0
	global_load_lds_dwordx4 v[168:169], off
	v_lshl_add_u64 v[168:169], v[232:233], 0, s[8:9]
	s_mov_b32 m0, s20
	s_nop 0
	global_load_lds_dwordx4 v[168:169], off
	s_waitcnt vmcnt(8)
	s_waitcnt lgkmcnt(0)
	v_mfma_f32_16x16x32_f16 v[60:63], v[156:159], v[192:195], v[60:63]
	v_mfma_f32_16x16x32_f16 v[56:59], v[164:167], v[192:195], v[56:59]
	v_mfma_f32_16x16x32_f16 v[52:55], v[156:159], v[200:203], v[52:55]
	v_mfma_f32_16x16x32_f16 v[48:51], v[164:167], v[200:203], v[48:51]
	s_barrier
	s_setprio 1
	s_waitcnt lgkmcnt(0)
	v_mfma_f32_16x16x32_f16 v[36:39], v[156:159], v[208:211], v[36:39]
	v_mfma_f32_16x16x32_f16 v[32:35], v[164:167], v[208:211], v[32:35]
	v_mfma_f32_16x16x32_f16 v[20:23], v[156:159], v[216:219], v[20:23]
	v_mfma_f32_16x16x32_f16 v[16:19], v[164:167], v[216:219], v[16:19]
	v_mfma_f32_16x16x32_f16 v[60:63], v[160:163], v[196:199], v[60:63]
	v_mfma_f32_16x16x32_f16 v[56:59], v[172:175], v[196:199], v[56:59]
	v_mfma_f32_16x16x32_f16 v[52:55], v[160:163], v[204:207], v[52:55]
	v_mfma_f32_16x16x32_f16 v[48:51], v[172:175], v[204:207], v[48:51]
	v_mfma_f32_16x16x32_f16 v[36:39], v[160:163], v[212:215], v[36:39]
	v_mfma_f32_16x16x32_f16 v[32:35], v[172:175], v[212:215], v[32:35]
	v_mfma_f32_16x16x32_f16 v[20:23], v[160:163], v[220:223], v[20:23]
	v_mfma_f32_16x16x32_f16 v[16:19], v[172:175], v[220:223], v[16:19]
	s_setprio 0
	s_setprio 1
	v_mfma_f32_16x16x32_f16 v[44:47], v[176:179], v[192:195], v[44:47]
	v_mfma_f32_16x16x32_f16 v[40:43], v[184:187], v[192:195], v[40:43]
	v_mfma_f32_16x16x32_f16 v[28:31], v[176:179], v[200:203], v[28:31]
	v_mfma_f32_16x16x32_f16 v[24:27], v[184:187], v[200:203], v[24:27]
	v_mfma_f32_16x16x32_f16 v[12:15], v[176:179], v[208:211], v[12:15]
	v_mfma_f32_16x16x32_f16 v[8:11], v[184:187], v[208:211], v[8:11]
	v_mfma_f32_16x16x32_f16 v[4:7], v[176:179], v[216:219], v[4:7]
	v_mfma_f32_16x16x32_f16 v[0:3], v[184:187], v[216:219], v[0:3]
	v_mfma_f32_16x16x32_f16 v[44:47], v[180:183], v[196:199], v[44:47]
	v_mfma_f32_16x16x32_f16 v[40:43], v[188:191], v[196:199], v[40:43]
	v_mfma_f32_16x16x32_f16 v[28:31], v[180:183], v[204:207], v[28:31]
	v_mfma_f32_16x16x32_f16 v[24:27], v[188:191], v[204:207], v[24:27]
	v_mfma_f32_16x16x32_f16 v[12:15], v[180:183], v[212:215], v[12:15]
	v_mfma_f32_16x16x32_f16 v[8:11], v[188:191], v[212:215], v[8:11]
	v_mfma_f32_16x16x32_f16 v[4:7], v[180:183], v[220:223], v[4:7]
	v_mfma_f32_16x16x32_f16 v[0:3], v[188:191], v[220:223], v[0:3]
	s_setprio 0
	s_barrier
	s_add_i32 s55, s55, 2
	s_add_u32 s48, s48, 0x100
	s_addc_u32 s49, s49, 0
	s_add_u32 s53, s53, 0x100
	s_addc_u32 s54, s54, 0
	s_cmp_gt_u32 s55, 13
	s_cbranch_scc0 .LBB0_629
	s_and_b64 vcc, exec, s[22:23]
	s_cbranch_vccz .LBB0_632
	s_barrier

.LBB0_649:
	ds_read_b128 v[160:163], v156
	ds_read_b128 v[164:167], v156 offset:1024
	ds_read_b128 v[172:175], v156 offset:2048
	ds_read_b128 v[176:179], v156 offset:3072
	ds_read_b128 v[180:183], v157
	ds_read_b128 v[184:187], v157 offset:1024
	ds_read_b128 v[188:191], v157 offset:2048
	ds_read_b128 v[192:195], v157 offset:3072
	s_add_u32 s2, s44, 0xfffc0080
	s_addc_u32 s3, s45, -1
	s_cmp_eq_u32 s52, 12
	s_cselect_b32 s47, s27, s3
	s_cselect_b32 s46, s48, s2
	s_cselect_b32 s55, s25, s51
	s_cselect_b32 s54, s49, s50
	v_lshl_add_u64 v[168:169], s[44:45], 0, v[142:143]
	s_add_i32 m0, s15, 0xc000
	ds_read_b128 v[196:199], v158
	ds_read_b128 v[200:203], v158 offset:1024
	ds_read_b128 v[204:207], v158 offset:2048
	ds_read_b128 v[208:211], v158 offset:3072
	ds_read_b128 v[212:215], v158 offset:4096
	ds_read_b128 v[216:219], v158 offset:5120
	ds_read_b128 v[220:223], v158 offset:6144
	ds_read_b128 v[224:227], v158 offset:7168
	global_load_lds_dwordx4 v[168:169], off
	v_lshl_add_u64 v[168:169], s[44:45], 0, v[144:145]
	s_add_i32 m0, s15, 0xe000
	s_nop 0
	global_load_lds_dwordx4 v[168:169], off
	s_waitcnt vmcnt(8)
	s_waitcnt lgkmcnt(0)
	v_mfma_f32_16x16x32_f16 v[124:127], v[160:163], v[196:199], v[124:127]
	v_mfma_f32_16x16x32_f16 v[120:123], v[172:175], v[196:199], v[120:123]
	v_mfma_f32_16x16x32_f16 v[116:119], v[160:163], v[204:207], v[116:119]
	v_mfma_f32_16x16x32_f16 v[108:111], v[172:175], v[204:207], v[108:111]
	s_barrier
	s_setprio 1
	s_waitcnt lgkmcnt(0)
	v_mfma_f32_16x16x32_f16 v[100:103], v[160:163], v[212:215], v[100:103]
	v_mfma_f32_16x16x32_f16 v[92:95], v[172:175], v[212:215], v[92:95]
	v_mfma_f32_16x16x32_f16 v[84:87], v[160:163], v[220:223], v[84:87]
	v_mfma_f32_16x16x32_f16 v[76:79], v[172:175], v[220:223], v[76:79]
	v_mfma_f32_16x16x32_f16 v[124:127], v[164:167], v[200:203], v[124:127]
	v_mfma_f32_16x16x32_f16 v[120:123], v[176:179], v[200:203], v[120:123]
	v_mfma_f32_16x16x32_f16 v[116:119], v[164:167], v[208:211], v[116:119]
	v_mfma_f32_16x16x32_f16 v[108:111], v[176:179], v[208:211], v[108:111]
	v_mfma_f32_16x16x32_f16 v[100:103], v[164:167], v[216:219], v[100:103]
	v_mfma_f32_16x16x32_f16 v[92:95], v[176:179], v[216:219], v[92:95]
	v_mfma_f32_16x16x32_f16 v[84:87], v[164:167], v[224:227], v[84:87]
	v_mfma_f32_16x16x32_f16 v[76:79], v[176:179], v[224:227], v[76:79]
	s_setprio 0
	s_setprio 1
	v_mfma_f32_16x16x32_f16 v[112:115], v[180:183], v[196:199], v[112:115]
	v_mfma_f32_16x16x32_f16 v[104:107], v[188:191], v[196:199], v[104:107]
	v_mfma_f32_16x16x32_f16 v[96:99], v[180:183], v[204:207], v[96:99]
	v_mfma_f32_16x16x32_f16 v[88:91], v[188:191], v[204:207], v[88:91]
	v_mfma_f32_16x16x32_f16 v[80:83], v[180:183], v[212:215], v[80:83]
	v_mfma_f32_16x16x32_f16 v[72:75], v[188:191], v[212:215], v[72:75]
	v_mfma_f32_16x16x32_f16 v[68:71], v[180:183], v[220:223], v[68:71]
	v_mfma_f32_16x16x32_f16 v[64:67], v[188:191], v[220:223], v[64:67]
	v_mfma_f32_16x16x32_f16 v[112:115], v[184:187], v[200:203], v[112:115]
	v_mfma_f32_16x16x32_f16 v[104:107], v[192:195], v[200:203], v[104:107]
	v_mfma_f32_16x16x32_f16 v[96:99], v[184:187], v[208:211], v[96:99]
	v_mfma_f32_16x16x32_f16 v[88:91], v[192:195], v[208:211], v[88:91]
	v_mfma_f32_16x16x32_f16 v[80:83], v[184:187], v[216:219], v[80:83]
	v_mfma_f32_16x16x32_f16 v[72:75], v[192:195], v[216:219], v[72:75]
	v_mfma_f32_16x16x32_f16 v[68:71], v[184:187], v[224:227], v[68:71]
	v_mfma_f32_16x16x32_f16 v[64:67], v[192:195], v[224:227], v[64:67]
	s_setprio 0
	s_barrier
	s_add_i32 s2, s21, s14
	v_lshl_add_u64 v[168:169], s[54:55], 0, v[136:137]
	s_mov_b32 m0, s2
	ds_read_b128 v[196:199], v158 offset:16384
	ds_read_b128 v[200:203], v158 offset:17408
	ds_read_b128 v[204:207], v158 offset:18432
	ds_read_b128 v[208:211], v158 offset:19456
	ds_read_b128 v[212:215], v158 offset:20480
	ds_read_b128 v[216:219], v158 offset:21504
	ds_read_b128 v[220:223], v158 offset:22528
	ds_read_b128 v[224:227], v158 offset:23552
	global_load_lds_dwordx4 v[168:169], off
	v_lshl_add_u64 v[228:229], s[54:55], 0, v[130:131]
	s_add_i32 m0, s2, 0x2000
	s_add_i32 s2, s28, s14
	global_load_lds_dwordx4 v[228:229], off
	v_lshl_add_u64 v[230:231], s[54:55], 0, v[134:135]
	s_mov_b32 m0, s2
	v_lshl_add_u64 v[232:233], s[54:55], 0, v[128:129]
	global_load_lds_dwordx4 v[230:231], off
	s_add_i32 m0, s2, 0x2000
	v_lshl_add_u64 v[234:235], s[46:47], 0, v[138:139]
	global_load_lds_dwordx4 v[232:233], off
	s_mov_b32 m0, s15
	v_lshl_add_u64 v[236:237], s[46:47], 0, v[132:133]
	global_load_lds_dwordx4 v[234:235], off
	s_mov_b32 m0, s16
	s_nop 0
	global_load_lds_dwordx4 v[236:237], off
	s_waitcnt vmcnt(8)
	s_waitcnt lgkmcnt(0)
	v_mfma_f32_16x16x32_f16 v[60:63], v[160:163], v[196:199], v[60:63]
	v_mfma_f32_16x16x32_f16 v[56:59], v[172:175], v[196:199], v[56:59]
	v_mfma_f32_16x16x32_f16 v[52:55], v[160:163], v[204:207], v[52:55]
	v_mfma_f32_16x16x32_f16 v[48:51], v[172:175], v[204:207], v[48:51]
	s_barrier
	s_setprio 1
	s_waitcnt lgkmcnt(0)
	v_mfma_f32_16x16x32_f16 v[36:39], v[160:163], v[212:215], v[36:39]
	v_mfma_f32_16x16x32_f16 v[32:35], v[172:175], v[212:215], v[32:35]
	v_mfma_f32_16x16x32_f16 v[20:23], v[160:163], v[220:223], v[20:23]
	v_mfma_f32_16x16x32_f16 v[16:19], v[172:175], v[220:223], v[16:19]
	v_mfma_f32_16x16x32_f16 v[60:63], v[164:167], v[200:203], v[60:63]
	v_mfma_f32_16x16x32_f16 v[56:59], v[176:179], v[200:203], v[56:59]
	v_mfma_f32_16x16x32_f16 v[52:55], v[164:167], v[208:211], v[52:55]
	v_mfma_f32_16x16x32_f16 v[48:51], v[176:179], v[208:211], v[48:51]
	v_mfma_f32_16x16x32_f16 v[36:39], v[164:167], v[216:219], v[36:39]
	v_mfma_f32_16x16x32_f16 v[32:35], v[176:179], v[216:219], v[32:35]
	v_mfma_f32_16x16x32_f16 v[20:23], v[164:167], v[224:227], v[20:23]
	v_mfma_f32_16x16x32_f16 v[16:19], v[176:179], v[224:227], v[16:19]
	s_setprio 0
	s_setprio 1
	v_mfma_f32_16x16x32_f16 v[44:47], v[180:183], v[196:199], v[44:47]
	v_mfma_f32_16x16x32_f16 v[40:43], v[188:191], v[196:199], v[40:43]
	v_mfma_f32_16x16x32_f16 v[28:31], v[180:183], v[204:207], v[28:31]
	v_mfma_f32_16x16x32_f16 v[24:27], v[188:191], v[204:207], v[24:27]
	v_mfma_f32_16x16x32_f16 v[12:15], v[180:183], v[212:215], v[12:15]
	v_mfma_f32_16x16x32_f16 v[8:11], v[188:191], v[212:215], v[8:11]
	v_mfma_f32_16x16x32_f16 v[4:7], v[180:183], v[220:223], v[4:7]
	v_mfma_f32_16x16x32_f16 v[0:3], v[188:191], v[220:223], v[0:3]
	v_mfma_f32_16x16x32_f16 v[44:47], v[184:187], v[200:203], v[44:47]
	v_mfma_f32_16x16x32_f16 v[40:43], v[192:195], v[200:203], v[40:43]
	v_mfma_f32_16x16x32_f16 v[28:31], v[184:187], v[208:211], v[28:31]
	v_mfma_f32_16x16x32_f16 v[24:27], v[192:195], v[208:211], v[24:27]
	v_mfma_f32_16x16x32_f16 v[12:15], v[184:187], v[216:219], v[12:15]
	v_mfma_f32_16x16x32_f16 v[8:11], v[192:195], v[216:219], v[8:11]
	v_mfma_f32_16x16x32_f16 v[4:7], v[184:187], v[224:227], v[4:7]
	v_mfma_f32_16x16x32_f16 v[0:3], v[192:195], v[224:227], v[0:3]
	s_setprio 0
	s_barrier
	s_add_i32 s2, 0, 0x18000
	v_add_u32_e32 v151, s2, v155
	s_add_i32 s3, 0, 0x1c000
	ds_read_b128 v[160:163], v151
	ds_read_b128 v[164:167], v151 offset:1024
	ds_read_b128 v[172:175], v151 offset:2048
	ds_read_b128 v[176:179], v151 offset:3072
	v_add_u32_e32 v151, s3, v155
	ds_read_b128 v[180:183], v151
	ds_read_b128 v[184:187], v151 offset:1024
	ds_read_b128 v[188:191], v151 offset:2048
	ds_read_b128 v[192:195], v151 offset:3072
	s_add_u32 s46, s46, 0x40000
	s_addc_u32 s47, s47, 0
	s_mov_b32 m0, s17
	v_lshl_add_u64 v[238:239], s[46:47], 0, v[138:139]
	ds_read_b128 v[196:199], v158 offset:32768
	ds_read_b128 v[200:203], v158 offset:33792
	ds_read_b128 v[204:207], v158 offset:34816
	ds_read_b128 v[208:211], v158 offset:35840
	ds_read_b128 v[212:215], v158 offset:36864
	ds_read_b128 v[216:219], v158 offset:37888
	ds_read_b128 v[220:223], v158 offset:38912
	ds_read_b128 v[224:227], v158 offset:39936
	global_load_lds_dwordx4 v[238:239], off
	v_lshl_add_u64 v[238:239], s[46:47], 0, v[132:133]
	s_mov_b32 m0, s18
	s_nop 0
	global_load_lds_dwordx4 v[238:239], off
	s_waitcnt vmcnt(8)
	s_waitcnt lgkmcnt(0)
	v_mfma_f32_16x16x32_f16 v[124:127], v[160:163], v[196:199], v[124:127]
	v_mfma_f32_16x16x32_f16 v[120:123], v[172:175], v[196:199], v[120:123]
	v_mfma_f32_16x16x32_f16 v[116:119], v[160:163], v[204:207], v[116:119]
	v_mfma_f32_16x16x32_f16 v[108:111], v[172:175], v[204:207], v[108:111]
	s_barrier
	s_setprio 1
	s_waitcnt lgkmcnt(0)
	v_mfma_f32_16x16x32_f16 v[100:103], v[160:163], v[212:215], v[100:103]
	v_mfma_f32_16x16x32_f16 v[92:95], v[172:175], v[212:215], v[92:95]
	v_mfma_f32_16x16x32_f16 v[84:87], v[160:163], v[220:223], v[84:87]
	v_mfma_f32_16x16x32_f16 v[76:79], v[172:175], v[220:223], v[76:79]
	v_mfma_f32_16x16x32_f16 v[124:127], v[164:167], v[200:203], v[124:127]
	v_mfma_f32_16x16x32_f16 v[120:123], v[176:179], v[200:203], v[120:123]
	v_mfma_f32_16x16x32_f16 v[116:119], v[164:167], v[208:211], v[116:119]
	v_mfma_f32_16x16x32_f16 v[108:111], v[176:179], v[208:211], v[108:111]
	v_mfma_f32_16x16x32_f16 v[100:103], v[164:167], v[216:219], v[100:103]
	v_mfma_f32_16x16x32_f16 v[92:95], v[176:179], v[216:219], v[92:95]
	v_mfma_f32_16x16x32_f16 v[84:87], v[164:167], v[224:227], v[84:87]
	v_mfma_f32_16x16x32_f16 v[76:79], v[176:179], v[224:227], v[76:79]
	s_setprio 0
	s_setprio 1
	v_mfma_f32_16x16x32_f16 v[112:115], v[180:183], v[196:199], v[112:115]
	v_mfma_f32_16x16x32_f16 v[104:107], v[188:191], v[196:199], v[104:107]
	v_mfma_f32_16x16x32_f16 v[96:99], v[180:183], v[204:207], v[96:99]
	v_mfma_f32_16x16x32_f16 v[88:91], v[188:191], v[204:207], v[88:91]
	v_mfma_f32_16x16x32_f16 v[80:83], v[180:183], v[212:215], v[80:83]
	v_mfma_f32_16x16x32_f16 v[72:75], v[188:191], v[212:215], v[72:75]
	v_mfma_f32_16x16x32_f16 v[68:71], v[180:183], v[220:223], v[68:71]
	v_mfma_f32_16x16x32_f16 v[64:67], v[188:191], v[220:223], v[64:67]
	v_mfma_f32_16x16x32_f16 v[112:115], v[184:187], v[200:203], v[112:115]
	v_mfma_f32_16x16x32_f16 v[104:107], v[192:195], v[200:203], v[104:107]
	v_mfma_f32_16x16x32_f16 v[96:99], v[184:187], v[208:211], v[96:99]
	v_mfma_f32_16x16x32_f16 v[88:91], v[192:195], v[208:211], v[88:91]
	v_mfma_f32_16x16x32_f16 v[80:83], v[184:187], v[216:219], v[80:83]
	v_mfma_f32_16x16x32_f16 v[72:75], v[192:195], v[216:219], v[72:75]
	v_mfma_f32_16x16x32_f16 v[68:71], v[184:187], v[224:227], v[68:71]
	v_mfma_f32_16x16x32_f16 v[64:67], v[192:195], v[224:227], v[64:67]
	s_setprio 0
	s_barrier
	s_add_i32 s2, s2, s14
	v_lshl_add_u64 v[168:169], v[168:169], 0, s[10:11]
	s_mov_b32 m0, s2
	ds_read_b128 v[196:199], v158 offset:49152
	ds_read_b128 v[200:203], v158 offset:50176
	ds_read_b128 v[204:207], v158 offset:51200
	ds_read_b128 v[208:211], v158 offset:52224
	ds_read_b128 v[212:215], v158 offset:53248
	ds_read_b128 v[216:219], v158 offset:54272
	ds_read_b128 v[220:223], v158 offset:55296
	ds_read_b128 v[224:227], v158 offset:56320
	global_load_lds_dwordx4 v[168:169], off
	v_lshl_add_u64 v[168:169], v[228:229], 0, s[10:11]
	s_add_i32 m0, s2, 0x2000
	s_add_i32 s2, s3, s14
	global_load_lds_dwordx4 v[168:169], off
	v_lshl_add_u64 v[168:169], v[230:231], 0, s[10:11]
	s_mov_b32 m0, s2
	s_nop 0
	global_load_lds_dwordx4 v[168:169], off
	v_lshl_add_u64 v[168:169], v[232:233], 0, s[10:11]
	s_add_i32 m0, s2, 0x2000
	s_nop 0
	global_load_lds_dwordx4 v[168:169], off
	v_lshl_add_u64 v[168:169], v[234:235], 0, s[10:11]
	s_mov_b32 m0, s19
	s_nop 0
	global_load_lds_dwordx4 v[168:169], off
	v_lshl_add_u64 v[168:169], v[236:237], 0, s[10:11]
	s_mov_b32 m0, s20
	s_nop 0
	global_load_lds_dwordx4 v[168:169], off
	s_waitcnt vmcnt(8)
	s_waitcnt lgkmcnt(0)
	v_mfma_f32_16x16x32_f16 v[60:63], v[160:163], v[196:199], v[60:63]
	v_mfma_f32_16x16x32_f16 v[56:59], v[172:175], v[196:199], v[56:59]
	v_mfma_f32_16x16x32_f16 v[52:55], v[160:163], v[204:207], v[52:55]
	v_mfma_f32_16x16x32_f16 v[48:51], v[172:175], v[204:207], v[48:51]
	s_barrier
	s_setprio 1
	s_waitcnt lgkmcnt(0)
	v_mfma_f32_16x16x32_f16 v[36:39], v[160:163], v[212:215], v[36:39]
	v_mfma_f32_16x16x32_f16 v[32:35], v[172:175], v[212:215], v[32:35]
	v_mfma_f32_16x16x32_f16 v[20:23], v[160:163], v[220:223], v[20:23]
	v_mfma_f32_16x16x32_f16 v[16:19], v[172:175], v[220:223], v[16:19]
	v_mfma_f32_16x16x32_f16 v[60:63], v[164:167], v[200:203], v[60:63]
	v_mfma_f32_16x16x32_f16 v[56:59], v[176:179], v[200:203], v[56:59]
	v_mfma_f32_16x16x32_f16 v[52:55], v[164:167], v[208:211], v[52:55]
	v_mfma_f32_16x16x32_f16 v[48:51], v[176:179], v[208:211], v[48:51]
	v_mfma_f32_16x16x32_f16 v[36:39], v[164:167], v[216:219], v[36:39]
	v_mfma_f32_16x16x32_f16 v[32:35], v[176:179], v[216:219], v[32:35]
	v_mfma_f32_16x16x32_f16 v[20:23], v[164:167], v[224:227], v[20:23]
	v_mfma_f32_16x16x32_f16 v[16:19], v[176:179], v[224:227], v[16:19]
	s_setprio 0
	s_setprio 1
	v_mfma_f32_16x16x32_f16 v[44:47], v[180:183], v[196:199], v[44:47]
	v_mfma_f32_16x16x32_f16 v[40:43], v[188:191], v[196:199], v[40:43]
	v_mfma_f32_16x16x32_f16 v[28:31], v[180:183], v[204:207], v[28:31]
	v_mfma_f32_16x16x32_f16 v[24:27], v[188:191], v[204:207], v[24:27]
	v_mfma_f32_16x16x32_f16 v[12:15], v[180:183], v[212:215], v[12:15]
	v_mfma_f32_16x16x32_f16 v[8:11], v[188:191], v[212:215], v[8:11]
	v_mfma_f32_16x16x32_f16 v[4:7], v[180:183], v[220:223], v[4:7]
	v_mfma_f32_16x16x32_f16 v[0:3], v[188:191], v[220:223], v[0:3]
	v_mfma_f32_16x16x32_f16 v[44:47], v[184:187], v[200:203], v[44:47]
	v_mfma_f32_16x16x32_f16 v[40:43], v[192:195], v[200:203], v[40:43]
	v_mfma_f32_16x16x32_f16 v[28:31], v[184:187], v[208:211], v[28:31]
	v_mfma_f32_16x16x32_f16 v[24:27], v[192:195], v[208:211], v[24:27]
	v_mfma_f32_16x16x32_f16 v[12:15], v[184:187], v[216:219], v[12:15]
	v_mfma_f32_16x16x32_f16 v[8:11], v[192:195], v[216:219], v[8:11]
	v_mfma_f32_16x16x32_f16 v[4:7], v[184:187], v[224:227], v[4:7]
	v_mfma_f32_16x16x32_f16 v[0:3], v[192:195], v[224:227], v[0:3]
	s_setprio 0
	s_barrier
	s_add_i32 s52, s52, 2
	s_add_u32 s44, s44, 0x100
	s_addc_u32 s45, s45, 0
	s_add_u32 s50, s50, 0x100
	s_addc_u32 s51, s51, 0
	s_cmp_gt_u32 s52, 13
	s_cbranch_scc0 .LBB0_649
	s_and_b64 vcc, exec, s[22:23]
	s_cbranch_vccz .LBB0_652
	s_barrier

.LBB0_673:
	s_add_u32 s23, s54, 0xfffc0080
	s_addc_u32 s24, s55, -1
	s_add_i32 s26, 0, 0x10000
	s_cmp_eq_u32 s21, 12
	s_cselect_b32 s57, s15, s24
	s_cselect_b32 s56, s16, s23
	v_add_u32_e32 v149, s26, v147
	s_cselect_b32 s25, s17, s20
	s_cselect_b32 s24, s18, s19
	s_add_i32 s23, 0, 0x14000
	ds_read_b128 v[150:153], v149
	ds_read_b128 v[184:187], v149 offset:1024
	ds_read_b128 v[188:191], v149 offset:2048
	ds_read_b128 v[192:195], v149 offset:3072
	v_add_u32_e32 v149, s23, v147
	ds_read_b128 v[196:199], v149
	ds_read_b128 v[200:203], v149 offset:1024
	ds_read_b128 v[204:207], v149 offset:2048
	ds_read_b128 v[208:211], v149 offset:3072
	v_lshl_add_u64 v[154:155], s[54:55], 0, v[142:143]
	s_add_i32 m0, s1, 0xc000
	ds_read_b128 v[212:215], v148
	ds_read_b128 v[216:219], v148 offset:1024
	ds_read_b128 v[220:223], v148 offset:2048
	ds_read_b128 v[224:227], v148 offset:3072
	ds_read_b128 v[228:231], v148 offset:4096
	ds_read_b128 v[232:235], v148 offset:5120
	ds_read_b128 v[236:239], v148 offset:6144
	ds_read_b128 v[240:243], v148 offset:7168
	global_load_lds_dwordx4 v[154:155], off
	v_lshl_add_u64 v[154:155], s[54:55], 0, v[144:145]
	s_add_i32 m0, s1, 0xe000
	s_nop 0
	global_load_lds_dwordx4 v[154:155], off
	s_waitcnt vmcnt(8)
	s_waitcnt lgkmcnt(0)
	v_mfma_f32_16x16x32_f16 v[128:131], v[150:153], v[212:215], v[128:131]
	v_mfma_f32_16x16x32_f16 v[124:127], v[188:191], v[212:215], v[124:127]
	v_mfma_f32_16x16x32_f16 v[120:123], v[150:153], v[220:223], v[120:123]
	v_mfma_f32_16x16x32_f16 v[112:115], v[188:191], v[220:223], v[112:115]
	s_barrier
	s_setprio 1
	s_waitcnt lgkmcnt(0)
	v_mfma_f32_16x16x32_f16 v[104:107], v[150:153], v[228:231], v[104:107]
	v_mfma_f32_16x16x32_f16 v[100:103], v[188:191], v[228:231], v[100:103]
	v_mfma_f32_16x16x32_f16 v[88:91], v[150:153], v[236:239], v[88:91]
	v_mfma_f32_16x16x32_f16 v[84:87], v[188:191], v[236:239], v[84:87]
	v_mfma_f32_16x16x32_f16 v[128:131], v[184:187], v[216:219], v[128:131]
	v_mfma_f32_16x16x32_f16 v[124:127], v[192:195], v[216:219], v[124:127]
	v_mfma_f32_16x16x32_f16 v[120:123], v[184:187], v[224:227], v[120:123]
	v_mfma_f32_16x16x32_f16 v[112:115], v[192:195], v[224:227], v[112:115]
	v_mfma_f32_16x16x32_f16 v[104:107], v[184:187], v[232:235], v[104:107]
	v_mfma_f32_16x16x32_f16 v[100:103], v[192:195], v[232:235], v[100:103]
	v_mfma_f32_16x16x32_f16 v[88:91], v[184:187], v[240:243], v[88:91]
	v_mfma_f32_16x16x32_f16 v[84:87], v[192:195], v[240:243], v[84:87]
	s_setprio 0
	s_setprio 1
	v_mfma_f32_16x16x32_f16 v[116:119], v[196:199], v[212:215], v[116:119]
	v_mfma_f32_16x16x32_f16 v[108:111], v[204:207], v[212:215], v[108:111]
	v_mfma_f32_16x16x32_f16 v[96:99], v[196:199], v[220:223], v[96:99]
	v_mfma_f32_16x16x32_f16 v[92:95], v[204:207], v[220:223], v[92:95]
	v_mfma_f32_16x16x32_f16 v[80:83], v[196:199], v[228:231], v[80:83]
	v_mfma_f32_16x16x32_f16 v[76:79], v[204:207], v[228:231], v[76:79]
	v_mfma_f32_16x16x32_f16 v[72:75], v[196:199], v[236:239], v[72:75]
	v_mfma_f32_16x16x32_f16 v[68:71], v[204:207], v[236:239], v[68:71]
	v_mfma_f32_16x16x32_f16 v[116:119], v[200:203], v[216:219], v[116:119]
	v_mfma_f32_16x16x32_f16 v[108:111], v[208:211], v[216:219], v[108:111]
	v_mfma_f32_16x16x32_f16 v[96:99], v[200:203], v[224:227], v[96:99]
	v_mfma_f32_16x16x32_f16 v[92:95], v[208:211], v[224:227], v[92:95]
	v_mfma_f32_16x16x32_f16 v[80:83], v[200:203], v[232:235], v[80:83]
	v_mfma_f32_16x16x32_f16 v[76:79], v[208:211], v[232:235], v[76:79]
	v_mfma_f32_16x16x32_f16 v[72:75], v[200:203], v[240:243], v[72:75]
	v_mfma_f32_16x16x32_f16 v[68:71], v[208:211], v[240:243], v[68:71]
	s_setprio 0
	s_barrier
	s_add_i32 s26, s26, s0
	v_lshl_add_u64 v[154:155], s[24:25], 0, v[136:137]
	s_mov_b32 m0, s26
	ds_read_b128 v[212:215], v148 offset:16384
	ds_read_b128 v[216:219], v148 offset:17408
	ds_read_b128 v[220:223], v148 offset:18432
	ds_read_b128 v[224:227], v148 offset:19456
	ds_read_b128 v[228:231], v148 offset:20480
	ds_read_b128 v[232:235], v148 offset:21504
	ds_read_b128 v[236:239], v148 offset:22528
	ds_read_b128 v[240:243], v148 offset:23552
	global_load_lds_dwordx4 v[154:155], off
	v_lshl_add_u64 v[168:169], s[24:25], 0, v[0:1]
	s_add_i32 m0, s26, 0x2000
	s_add_i32 s23, s23, s0
	global_load_lds_dwordx4 v[168:169], off
	v_lshl_add_u64 v[244:245], s[24:25], 0, v[138:139]
	s_mov_b32 m0, s23
	v_lshl_add_u64 v[246:247], s[24:25], 0, v[132:133]
	global_load_lds_dwordx4 v[244:245], off
	s_add_i32 m0, s23, 0x2000
	v_lshl_add_u64 v[248:249], s[56:57], 0, v[140:141]
	global_load_lds_dwordx4 v[246:247], off
	s_mov_b32 m0, s1
	v_lshl_add_u64 v[250:251], s[56:57], 0, v[134:135]
	global_load_lds_dwordx4 v[248:249], off
	s_mov_b32 m0, s2
	s_nop 0
	global_load_lds_dwordx4 v[250:251], off
	s_waitcnt vmcnt(8)
	s_waitcnt lgkmcnt(0)
	v_mfma_f32_16x16x32_f16 v[64:67], v[150:153], v[212:215], v[64:67]
	v_mfma_f32_16x16x32_f16 v[60:63], v[188:191], v[212:215], v[60:63]
	v_mfma_f32_16x16x32_f16 v[56:59], v[150:153], v[220:223], v[56:59]
	v_mfma_f32_16x16x32_f16 v[52:55], v[188:191], v[220:223], v[52:55]
	s_barrier
	s_setprio 1
	s_waitcnt lgkmcnt(0)
	v_mfma_f32_16x16x32_f16 v[40:43], v[150:153], v[228:231], v[40:43]
	v_mfma_f32_16x16x32_f16 v[36:39], v[188:191], v[228:231], v[36:39]
	v_mfma_f32_16x16x32_f16 v[24:27], v[150:153], v[236:239], v[24:27]
	v_mfma_f32_16x16x32_f16 v[20:23], v[188:191], v[236:239], v[20:23]
	v_mfma_f32_16x16x32_f16 v[64:67], v[184:187], v[216:219], v[64:67]
	v_mfma_f32_16x16x32_f16 v[60:63], v[192:195], v[216:219], v[60:63]
	v_mfma_f32_16x16x32_f16 v[56:59], v[184:187], v[224:227], v[56:59]
	v_mfma_f32_16x16x32_f16 v[52:55], v[192:195], v[224:227], v[52:55]
	v_mfma_f32_16x16x32_f16 v[40:43], v[184:187], v[232:235], v[40:43]
	v_mfma_f32_16x16x32_f16 v[36:39], v[192:195], v[232:235], v[36:39]
	v_mfma_f32_16x16x32_f16 v[24:27], v[184:187], v[240:243], v[24:27]
	v_mfma_f32_16x16x32_f16 v[20:23], v[192:195], v[240:243], v[20:23]
	s_setprio 0
	s_setprio 1
	v_mfma_f32_16x16x32_f16 v[48:51], v[196:199], v[212:215], v[48:51]
	v_mfma_f32_16x16x32_f16 v[44:47], v[204:207], v[212:215], v[44:47]
	v_mfma_f32_16x16x32_f16 v[32:35], v[196:199], v[220:223], v[32:35]
	v_mfma_f32_16x16x32_f16 v[28:31], v[204:207], v[220:223], v[28:31]
	v_mfma_f32_16x16x32_f16 v[16:19], v[196:199], v[228:231], v[16:19]
	v_mfma_f32_16x16x32_f16 v[12:15], v[204:207], v[228:231], v[12:15]
	v_mfma_f32_16x16x32_f16 v[8:11], v[196:199], v[236:239], v[8:11]
	v_mfma_f32_16x16x32_f16 v[4:7], v[204:207], v[236:239], v[4:7]
	v_mfma_f32_16x16x32_f16 v[48:51], v[200:203], v[216:219], v[48:51]
	v_mfma_f32_16x16x32_f16 v[44:47], v[208:211], v[216:219], v[44:47]
	v_mfma_f32_16x16x32_f16 v[32:35], v[200:203], v[224:227], v[32:35]
	v_mfma_f32_16x16x32_f16 v[28:31], v[208:211], v[224:227], v[28:31]
	v_mfma_f32_16x16x32_f16 v[16:19], v[200:203], v[232:235], v[16:19]
	v_mfma_f32_16x16x32_f16 v[12:15], v[208:211], v[232:235], v[12:15]
	v_mfma_f32_16x16x32_f16 v[8:11], v[200:203], v[240:243], v[8:11]
	v_mfma_f32_16x16x32_f16 v[4:7], v[208:211], v[240:243], v[4:7]
	s_setprio 0
	s_barrier
	s_add_i32 s23, 0, 0x18000
	v_add_u32_e32 v149, s23, v147
	s_add_i32 s26, 0, 0x1c000
	ds_read_b128 v[150:153], v149
	ds_read_b128 v[184:187], v149 offset:1024
	ds_read_b128 v[188:191], v149 offset:2048
	ds_read_b128 v[192:195], v149 offset:3072
	v_add_u32_e32 v149, s26, v147
	ds_read_b128 v[196:199], v149
	ds_read_b128 v[200:203], v149 offset:1024
	ds_read_b128 v[204:207], v149 offset:2048
	ds_read_b128 v[208:211], v149 offset:3072
	s_add_u32 s24, s56, 0x40000
	s_addc_u32 s25, s57, 0
	s_mov_b32 m0, s3
	v_lshl_add_u64 v[178:179], s[24:25], 0, v[140:141]
	ds_read_b128 v[212:215], v148 offset:32768
	ds_read_b128 v[216:219], v148 offset:33792
	ds_read_b128 v[220:223], v148 offset:34816
	ds_read_b128 v[224:227], v148 offset:35840
	ds_read_b128 v[228:231], v148 offset:36864
	ds_read_b128 v[232:235], v148 offset:37888
	ds_read_b128 v[236:239], v148 offset:38912
	ds_read_b128 v[240:243], v148 offset:39936
	global_load_lds_dwordx4 v[178:179], off
	v_lshl_add_u64 v[178:179], s[24:25], 0, v[134:135]
	s_mov_b32 m0, s4
	s_nop 0
	global_load_lds_dwordx4 v[178:179], off
	s_waitcnt vmcnt(8)
	s_waitcnt lgkmcnt(0)
	v_mfma_f32_16x16x32_f16 v[128:131], v[150:153], v[212:215], v[128:131]
	v_mfma_f32_16x16x32_f16 v[124:127], v[188:191], v[212:215], v[124:127]
	v_mfma_f32_16x16x32_f16 v[120:123], v[150:153], v[220:223], v[120:123]
	v_mfma_f32_16x16x32_f16 v[112:115], v[188:191], v[220:223], v[112:115]
	s_barrier
	s_setprio 1
	s_waitcnt lgkmcnt(0)
	v_mfma_f32_16x16x32_f16 v[104:107], v[150:153], v[228:231], v[104:107]
	v_mfma_f32_16x16x32_f16 v[100:103], v[188:191], v[228:231], v[100:103]
	v_mfma_f32_16x16x32_f16 v[88:91], v[150:153], v[236:239], v[88:91]
	v_mfma_f32_16x16x32_f16 v[84:87], v[188:191], v[236:239], v[84:87]
	v_mfma_f32_16x16x32_f16 v[128:131], v[184:187], v[216:219], v[128:131]
	v_mfma_f32_16x16x32_f16 v[124:127], v[192:195], v[216:219], v[124:127]
	v_mfma_f32_16x16x32_f16 v[120:123], v[184:187], v[224:227], v[120:123]
	v_mfma_f32_16x16x32_f16 v[112:115], v[192:195], v[224:227], v[112:115]
	v_mfma_f32_16x16x32_f16 v[104:107], v[184:187], v[232:235], v[104:107]
	v_mfma_f32_16x16x32_f16 v[100:103], v[192:195], v[232:235], v[100:103]
	v_mfma_f32_16x16x32_f16 v[88:91], v[184:187], v[240:243], v[88:91]
	v_mfma_f32_16x16x32_f16 v[84:87], v[192:195], v[240:243], v[84:87]
	s_setprio 0
	s_setprio 1
	v_mfma_f32_16x16x32_f16 v[116:119], v[196:199], v[212:215], v[116:119]
	v_mfma_f32_16x16x32_f16 v[108:111], v[204:207], v[212:215], v[108:111]
	v_mfma_f32_16x16x32_f16 v[96:99], v[196:199], v[220:223], v[96:99]
	v_mfma_f32_16x16x32_f16 v[92:95], v[204:207], v[220:223], v[92:95]
	v_mfma_f32_16x16x32_f16 v[80:83], v[196:199], v[228:231], v[80:83]
	v_mfma_f32_16x16x32_f16 v[76:79], v[204:207], v[228:231], v[76:79]
	v_mfma_f32_16x16x32_f16 v[72:75], v[196:199], v[236:239], v[72:75]
	v_mfma_f32_16x16x32_f16 v[68:71], v[204:207], v[236:239], v[68:71]
	v_mfma_f32_16x16x32_f16 v[116:119], v[200:203], v[216:219], v[116:119]
	v_mfma_f32_16x16x32_f16 v[108:111], v[208:211], v[216:219], v[108:111]
	v_mfma_f32_16x16x32_f16 v[96:99], v[200:203], v[224:227], v[96:99]
	v_mfma_f32_16x16x32_f16 v[92:95], v[208:211], v[224:227], v[92:95]
	v_mfma_f32_16x16x32_f16 v[80:83], v[200:203], v[232:235], v[80:83]
	v_mfma_f32_16x16x32_f16 v[76:79], v[208:211], v[232:235], v[76:79]
	v_mfma_f32_16x16x32_f16 v[72:75], v[200:203], v[240:243], v[72:75]
	v_mfma_f32_16x16x32_f16 v[68:71], v[208:211], v[240:243], v[68:71]
	s_setprio 0
	s_barrier
	s_add_i32 s23, s23, s0
	v_lshl_add_u64 v[154:155], v[154:155], 0, s[72:73]
	s_mov_b32 m0, s23
	ds_read_b128 v[212:215], v148 offset:49152
	ds_read_b128 v[216:219], v148 offset:50176
	ds_read_b128 v[220:223], v148 offset:51200
	ds_read_b128 v[224:227], v148 offset:52224
	ds_read_b128 v[228:231], v148 offset:53248
	ds_read_b128 v[232:235], v148 offset:54272
	ds_read_b128 v[236:239], v148 offset:55296
	ds_read_b128 v[240:243], v148 offset:56320
	global_load_lds_dwordx4 v[154:155], off
	v_lshl_add_u64 v[154:155], v[168:169], 0, s[72:73]
	s_add_i32 m0, s23, 0x2000
	s_add_i32 s23, s26, s0
	global_load_lds_dwordx4 v[154:155], off
	v_lshl_add_u64 v[154:155], v[244:245], 0, s[72:73]
	s_mov_b32 m0, s23
	s_nop 0
	global_load_lds_dwordx4 v[154:155], off
	v_lshl_add_u64 v[154:155], v[246:247], 0, s[72:73]
	s_add_i32 m0, s23, 0x2000
	s_nop 0
	global_load_lds_dwordx4 v[154:155], off
	v_lshl_add_u64 v[154:155], v[248:249], 0, s[72:73]
	s_mov_b32 m0, s10
	s_nop 0
	global_load_lds_dwordx4 v[154:155], off
	v_lshl_add_u64 v[154:155], v[250:251], 0, s[72:73]
	s_mov_b32 m0, s11
	s_nop 0
	global_load_lds_dwordx4 v[154:155], off
	s_waitcnt vmcnt(8)
	s_waitcnt lgkmcnt(0)
	v_mfma_f32_16x16x32_f16 v[64:67], v[150:153], v[212:215], v[64:67]
	v_mfma_f32_16x16x32_f16 v[60:63], v[188:191], v[212:215], v[60:63]
	v_mfma_f32_16x16x32_f16 v[56:59], v[150:153], v[220:223], v[56:59]
	v_mfma_f32_16x16x32_f16 v[52:55], v[188:191], v[220:223], v[52:55]
	s_barrier
	s_setprio 1
	s_waitcnt lgkmcnt(0)
	v_mfma_f32_16x16x32_f16 v[40:43], v[150:153], v[228:231], v[40:43]
	v_mfma_f32_16x16x32_f16 v[36:39], v[188:191], v[228:231], v[36:39]
	v_mfma_f32_16x16x32_f16 v[24:27], v[150:153], v[236:239], v[24:27]
	v_mfma_f32_16x16x32_f16 v[20:23], v[188:191], v[236:239], v[20:23]
	v_mfma_f32_16x16x32_f16 v[64:67], v[184:187], v[216:219], v[64:67]
	v_mfma_f32_16x16x32_f16 v[60:63], v[192:195], v[216:219], v[60:63]
	v_mfma_f32_16x16x32_f16 v[56:59], v[184:187], v[224:227], v[56:59]
	v_mfma_f32_16x16x32_f16 v[52:55], v[192:195], v[224:227], v[52:55]
	v_mfma_f32_16x16x32_f16 v[40:43], v[184:187], v[232:235], v[40:43]
	v_mfma_f32_16x16x32_f16 v[36:39], v[192:195], v[232:235], v[36:39]
	v_mfma_f32_16x16x32_f16 v[24:27], v[184:187], v[240:243], v[24:27]
	v_mfma_f32_16x16x32_f16 v[20:23], v[192:195], v[240:243], v[20:23]
	s_setprio 0
	s_setprio 1
	v_mfma_f32_16x16x32_f16 v[48:51], v[196:199], v[212:215], v[48:51]
	v_mfma_f32_16x16x32_f16 v[44:47], v[204:207], v[212:215], v[44:47]
	v_mfma_f32_16x16x32_f16 v[32:35], v[196:199], v[220:223], v[32:35]
	v_mfma_f32_16x16x32_f16 v[28:31], v[204:207], v[220:223], v[28:31]
	v_mfma_f32_16x16x32_f16 v[16:19], v[196:199], v[228:231], v[16:19]
	v_mfma_f32_16x16x32_f16 v[12:15], v[204:207], v[228:231], v[12:15]
	v_mfma_f32_16x16x32_f16 v[8:11], v[196:199], v[236:239], v[8:11]
	v_mfma_f32_16x16x32_f16 v[4:7], v[204:207], v[236:239], v[4:7]
	v_mfma_f32_16x16x32_f16 v[48:51], v[200:203], v[216:219], v[48:51]
	v_mfma_f32_16x16x32_f16 v[44:47], v[208:211], v[216:219], v[44:47]
	v_mfma_f32_16x16x32_f16 v[32:35], v[200:203], v[224:227], v[32:35]
	v_mfma_f32_16x16x32_f16 v[28:31], v[208:211], v[224:227], v[28:31]
	v_mfma_f32_16x16x32_f16 v[16:19], v[200:203], v[232:235], v[16:19]
	v_mfma_f32_16x16x32_f16 v[12:15], v[208:211], v[232:235], v[12:15]
	v_mfma_f32_16x16x32_f16 v[8:11], v[200:203], v[240:243], v[8:11]
	v_mfma_f32_16x16x32_f16 v[4:7], v[208:211], v[240:243], v[4:7]
	s_setprio 0
	s_barrier
	s_add_i32 s21, s21, 2
	s_add_u32 s54, s54, 0x100
	s_addc_u32 s55, s55, 0
	s_add_u32 s19, s19, 0x100
	s_addc_u32 s20, s20, 0
	s_cmp_gt_u32 s21, 13
	s_cbranch_scc0 .LBB0_673
	s_and_b64 vcc, exec, s[44:45]
	s_cbranch_vccz .LBB0_676
	s_barrier

.LBB0_929:
	v_add_u32_e32 v149, s67, v147
	ds_read_b128 v[150:153], v149
	ds_read_b128 v[186:189], v149 offset:1024
	ds_read_b128 v[190:193], v149 offset:2048
	ds_read_b128 v[194:197], v149 offset:3072
	v_add_u32_e32 v149, s68, v147
	ds_read_b128 v[198:201], v149
	ds_read_b128 v[202:205], v149 offset:1024
	ds_read_b128 v[206:209], v149 offset:2048
	ds_read_b128 v[210:213], v149 offset:3072
	s_add_u32 s25, s54, 0xfffc0080
	s_addc_u32 s26, s55, -1
	s_cmp_eq_u32 s24, 12
	s_cselect_b32 s57, s17, s26
	s_cselect_b32 s56, s18, s25
	s_cselect_b32 s27, s19, s23
	s_cselect_b32 s26, s20, s21
	v_lshl_add_u64 v[154:155], s[54:55], 0, v[142:143]
	s_add_i32 m0, s3, 0xc000
	ds_read_b128 v[214:217], v148
	ds_read_b128 v[218:221], v148 offset:1024
	ds_read_b128 v[222:225], v148 offset:2048
	ds_read_b128 v[226:229], v148 offset:3072
	ds_read_b128 v[230:233], v148 offset:4096
	ds_read_b128 v[234:237], v148 offset:5120
	ds_read_b128 v[238:241], v148 offset:6144
	ds_read_b128 v[242:245], v148 offset:7168
	global_load_lds_dwordx4 v[154:155], off
	v_lshl_add_u64 v[154:155], s[54:55], 0, v[144:145]
	s_add_i32 m0, s3, 0xe000
	s_nop 0
	global_load_lds_dwordx4 v[154:155], off
	s_waitcnt vmcnt(8)
	s_waitcnt lgkmcnt(0)
	v_mfma_f32_16x16x32_f16 v[128:131], v[150:153], v[214:217], v[128:131]
	v_mfma_f32_16x16x32_f16 v[124:127], v[190:193], v[214:217], v[124:127]
	v_mfma_f32_16x16x32_f16 v[116:119], v[150:153], v[222:225], v[116:119]
	v_mfma_f32_16x16x32_f16 v[108:111], v[190:193], v[222:225], v[108:111]
	s_barrier
	s_setprio 1
	s_waitcnt lgkmcnt(0)
	v_mfma_f32_16x16x32_f16 v[104:107], v[150:153], v[230:233], v[104:107]
	v_mfma_f32_16x16x32_f16 v[100:103], v[190:193], v[230:233], v[100:103]
	v_mfma_f32_16x16x32_f16 v[88:91], v[150:153], v[238:241], v[88:91]
	v_mfma_f32_16x16x32_f16 v[84:87], v[190:193], v[238:241], v[84:87]
	v_mfma_f32_16x16x32_f16 v[128:131], v[186:189], v[218:221], v[128:131]
	v_mfma_f32_16x16x32_f16 v[124:127], v[194:197], v[218:221], v[124:127]
	v_mfma_f32_16x16x32_f16 v[116:119], v[186:189], v[226:229], v[116:119]
	v_mfma_f32_16x16x32_f16 v[108:111], v[194:197], v[226:229], v[108:111]
	v_mfma_f32_16x16x32_f16 v[104:107], v[186:189], v[234:237], v[104:107]
	v_mfma_f32_16x16x32_f16 v[100:103], v[194:197], v[234:237], v[100:103]
	v_mfma_f32_16x16x32_f16 v[88:91], v[186:189], v[242:245], v[88:91]
	v_mfma_f32_16x16x32_f16 v[84:87], v[194:197], v[242:245], v[84:87]
	s_setprio 0
	s_setprio 1
	v_mfma_f32_16x16x32_f16 v[120:123], v[198:201], v[214:217], v[120:123]
	v_mfma_f32_16x16x32_f16 v[112:115], v[206:209], v[214:217], v[112:115]
	v_mfma_f32_16x16x32_f16 v[96:99], v[198:201], v[222:225], v[96:99]
	v_mfma_f32_16x16x32_f16 v[92:95], v[206:209], v[222:225], v[92:95]
	v_mfma_f32_16x16x32_f16 v[80:83], v[198:201], v[230:233], v[80:83]
	v_mfma_f32_16x16x32_f16 v[76:79], v[206:209], v[230:233], v[76:79]
	v_mfma_f32_16x16x32_f16 v[72:75], v[198:201], v[238:241], v[72:75]
	v_mfma_f32_16x16x32_f16 v[68:71], v[206:209], v[238:241], v[68:71]
	v_mfma_f32_16x16x32_f16 v[120:123], v[202:205], v[218:221], v[120:123]
	v_mfma_f32_16x16x32_f16 v[112:115], v[210:213], v[218:221], v[112:115]
	v_mfma_f32_16x16x32_f16 v[96:99], v[202:205], v[226:229], v[96:99]
	v_mfma_f32_16x16x32_f16 v[92:95], v[210:213], v[226:229], v[92:95]
	v_mfma_f32_16x16x32_f16 v[80:83], v[202:205], v[234:237], v[80:83]
	v_mfma_f32_16x16x32_f16 v[76:79], v[210:213], v[234:237], v[76:79]
	v_mfma_f32_16x16x32_f16 v[72:75], v[202:205], v[242:245], v[72:75]
	v_mfma_f32_16x16x32_f16 v[68:71], v[210:213], v[242:245], v[68:71]
	s_setprio 0
	s_barrier
	s_add_i32 s25, s67, s2
	v_lshl_add_u64 v[154:155], s[26:27], 0, v[136:137]
	s_mov_b32 m0, s25
	ds_read_b128 v[214:217], v148 offset:16384
	ds_read_b128 v[218:221], v148 offset:17408
	ds_read_b128 v[222:225], v148 offset:18432
	ds_read_b128 v[226:229], v148 offset:19456
	ds_read_b128 v[230:233], v148 offset:20480
	ds_read_b128 v[234:237], v148 offset:21504
	ds_read_b128 v[238:241], v148 offset:22528
	ds_read_b128 v[242:245], v148 offset:23552
	global_load_lds_dwordx4 v[154:155], off
	v_lshl_add_u64 v[168:169], s[26:27], 0, v[0:1]
	s_add_i32 m0, s25, 0x2000
	s_add_i32 s25, s68, s2
	global_load_lds_dwordx4 v[168:169], off
	v_lshl_add_u64 v[178:179], s[26:27], 0, v[138:139]
	s_mov_b32 m0, s25
	v_lshl_add_u64 v[246:247], s[26:27], 0, v[132:133]
	global_load_lds_dwordx4 v[178:179], off
	s_add_i32 m0, s25, 0x2000
	v_lshl_add_u64 v[248:249], s[56:57], 0, v[140:141]
	global_load_lds_dwordx4 v[246:247], off
	s_mov_b32 m0, s3
	v_lshl_add_u64 v[250:251], s[56:57], 0, v[134:135]
	global_load_lds_dwordx4 v[248:249], off
	s_mov_b32 m0, s8
	s_nop 0
	global_load_lds_dwordx4 v[250:251], off
	s_waitcnt vmcnt(8)
	s_waitcnt lgkmcnt(0)
	v_mfma_f32_16x16x32_f16 v[64:67], v[150:153], v[214:217], v[64:67]
	v_mfma_f32_16x16x32_f16 v[60:63], v[190:193], v[214:217], v[60:63]
	v_mfma_f32_16x16x32_f16 v[56:59], v[150:153], v[222:225], v[56:59]
	v_mfma_f32_16x16x32_f16 v[52:55], v[190:193], v[222:225], v[52:55]
	s_barrier
	s_setprio 1
	s_waitcnt lgkmcnt(0)
	v_mfma_f32_16x16x32_f16 v[40:43], v[150:153], v[230:233], v[40:43]
	v_mfma_f32_16x16x32_f16 v[36:39], v[190:193], v[230:233], v[36:39]
	v_mfma_f32_16x16x32_f16 v[24:27], v[150:153], v[238:241], v[24:27]
	v_mfma_f32_16x16x32_f16 v[20:23], v[190:193], v[238:241], v[20:23]
	v_mfma_f32_16x16x32_f16 v[64:67], v[186:189], v[218:221], v[64:67]
	v_mfma_f32_16x16x32_f16 v[60:63], v[194:197], v[218:221], v[60:63]
	v_mfma_f32_16x16x32_f16 v[56:59], v[186:189], v[226:229], v[56:59]
	v_mfma_f32_16x16x32_f16 v[52:55], v[194:197], v[226:229], v[52:55]
	v_mfma_f32_16x16x32_f16 v[40:43], v[186:189], v[234:237], v[40:43]
	v_mfma_f32_16x16x32_f16 v[36:39], v[194:197], v[234:237], v[36:39]
	v_mfma_f32_16x16x32_f16 v[24:27], v[186:189], v[242:245], v[24:27]
	v_mfma_f32_16x16x32_f16 v[20:23], v[194:197], v[242:245], v[20:23]
	s_setprio 0
	s_setprio 1
	v_mfma_f32_16x16x32_f16 v[48:51], v[198:201], v[214:217], v[48:51]
	v_mfma_f32_16x16x32_f16 v[44:47], v[206:209], v[214:217], v[44:47]
	v_mfma_f32_16x16x32_f16 v[32:35], v[198:201], v[222:225], v[32:35]
	v_mfma_f32_16x16x32_f16 v[28:31], v[206:209], v[222:225], v[28:31]
	v_mfma_f32_16x16x32_f16 v[16:19], v[198:201], v[230:233], v[16:19]
	v_mfma_f32_16x16x32_f16 v[12:15], v[206:209], v[230:233], v[12:15]
	v_mfma_f32_16x16x32_f16 v[8:11], v[198:201], v[238:241], v[8:11]
	v_mfma_f32_16x16x32_f16 v[4:7], v[206:209], v[238:241], v[4:7]
	v_mfma_f32_16x16x32_f16 v[48:51], v[202:205], v[218:221], v[48:51]
	v_mfma_f32_16x16x32_f16 v[44:47], v[210:213], v[218:221], v[44:47]
	v_mfma_f32_16x16x32_f16 v[32:35], v[202:205], v[226:229], v[32:35]
	v_mfma_f32_16x16x32_f16 v[28:31], v[210:213], v[226:229], v[28:31]
	v_mfma_f32_16x16x32_f16 v[16:19], v[202:205], v[234:237], v[16:19]
	v_mfma_f32_16x16x32_f16 v[12:15], v[210:213], v[234:237], v[12:15]
	v_mfma_f32_16x16x32_f16 v[8:11], v[202:205], v[242:245], v[8:11]
	v_mfma_f32_16x16x32_f16 v[4:7], v[210:213], v[242:245], v[4:7]
	s_setprio 0
	s_barrier
	v_add_u32_e32 v149, s82, v147
	ds_read_b128 v[150:153], v149
	ds_read_b128 v[186:189], v149 offset:1024
	ds_read_b128 v[190:193], v149 offset:2048
	ds_read_b128 v[194:197], v149 offset:3072
	v_add_u32_e32 v149, s62, v147
	ds_read_b128 v[198:201], v149
	ds_read_b128 v[202:205], v149 offset:1024
	ds_read_b128 v[206:209], v149 offset:2048
	ds_read_b128 v[210:213], v149 offset:3072
	s_add_u32 s26, s56, 0x40000
	s_addc_u32 s27, s57, 0
	s_mov_b32 m0, s9
	v_lshl_add_u64 v[176:177], s[26:27], 0, v[140:141]
	ds_read_b128 v[214:217], v148 offset:32768
	ds_read_b128 v[218:221], v148 offset:33792
	ds_read_b128 v[222:225], v148 offset:34816
	ds_read_b128 v[226:229], v148 offset:35840
	ds_read_b128 v[230:233], v148 offset:36864
	ds_read_b128 v[234:237], v148 offset:37888
	ds_read_b128 v[238:241], v148 offset:38912
	ds_read_b128 v[242:245], v148 offset:39936
	global_load_lds_dwordx4 v[176:177], off
	v_lshl_add_u64 v[176:177], s[26:27], 0, v[134:135]
	s_mov_b32 m0, s10
	s_nop 0
	global_load_lds_dwordx4 v[176:177], off
	s_waitcnt vmcnt(8)
	s_waitcnt lgkmcnt(0)
	v_mfma_f32_16x16x32_f16 v[128:131], v[150:153], v[214:217], v[128:131]
	v_mfma_f32_16x16x32_f16 v[124:127], v[190:193], v[214:217], v[124:127]
	v_mfma_f32_16x16x32_f16 v[116:119], v[150:153], v[222:225], v[116:119]
	v_mfma_f32_16x16x32_f16 v[108:111], v[190:193], v[222:225], v[108:111]
	s_barrier
	s_setprio 1
	s_waitcnt lgkmcnt(0)
	v_mfma_f32_16x16x32_f16 v[104:107], v[150:153], v[230:233], v[104:107]
	v_mfma_f32_16x16x32_f16 v[100:103], v[190:193], v[230:233], v[100:103]
	v_mfma_f32_16x16x32_f16 v[88:91], v[150:153], v[238:241], v[88:91]
	v_mfma_f32_16x16x32_f16 v[84:87], v[190:193], v[238:241], v[84:87]
	v_mfma_f32_16x16x32_f16 v[128:131], v[186:189], v[218:221], v[128:131]
	v_mfma_f32_16x16x32_f16 v[124:127], v[194:197], v[218:221], v[124:127]
	v_mfma_f32_16x16x32_f16 v[116:119], v[186:189], v[226:229], v[116:119]
	v_mfma_f32_16x16x32_f16 v[108:111], v[194:197], v[226:229], v[108:111]
	v_mfma_f32_16x16x32_f16 v[104:107], v[186:189], v[234:237], v[104:107]
	v_mfma_f32_16x16x32_f16 v[100:103], v[194:197], v[234:237], v[100:103]
	v_mfma_f32_16x16x32_f16 v[88:91], v[186:189], v[242:245], v[88:91]
	v_mfma_f32_16x16x32_f16 v[84:87], v[194:197], v[242:245], v[84:87]
	s_setprio 0
	s_setprio 1
	v_mfma_f32_16x16x32_f16 v[120:123], v[198:201], v[214:217], v[120:123]
	v_mfma_f32_16x16x32_f16 v[112:115], v[206:209], v[214:217], v[112:115]
	v_mfma_f32_16x16x32_f16 v[96:99], v[198:201], v[222:225], v[96:99]
	v_mfma_f32_16x16x32_f16 v[92:95], v[206:209], v[222:225], v[92:95]
	v_mfma_f32_16x16x32_f16 v[80:83], v[198:201], v[230:233], v[80:83]
	v_mfma_f32_16x16x32_f16 v[76:79], v[206:209], v[230:233], v[76:79]
	v_mfma_f32_16x16x32_f16 v[72:75], v[198:201], v[238:241], v[72:75]
	v_mfma_f32_16x16x32_f16 v[68:71], v[206:209], v[238:241], v[68:71]
	v_mfma_f32_16x16x32_f16 v[120:123], v[202:205], v[218:221], v[120:123]
	v_mfma_f32_16x16x32_f16 v[112:115], v[210:213], v[218:221], v[112:115]
	v_mfma_f32_16x16x32_f16 v[96:99], v[202:205], v[226:229], v[96:99]
	v_mfma_f32_16x16x32_f16 v[92:95], v[210:213], v[226:229], v[92:95]
	v_mfma_f32_16x16x32_f16 v[80:83], v[202:205], v[234:237], v[80:83]
	v_mfma_f32_16x16x32_f16 v[76:79], v[210:213], v[234:237], v[76:79]
	v_mfma_f32_16x16x32_f16 v[72:75], v[202:205], v[242:245], v[72:75]
	v_mfma_f32_16x16x32_f16 v[68:71], v[210:213], v[242:245], v[68:71]
	s_setprio 0
	s_barrier
	s_add_i32 s25, s82, s2
	v_lshl_add_u64 v[154:155], v[154:155], 0, s[72:73]
	s_mov_b32 m0, s25
	ds_read_b128 v[214:217], v148 offset:49152
	ds_read_b128 v[218:221], v148 offset:50176
	ds_read_b128 v[222:225], v148 offset:51200
	ds_read_b128 v[226:229], v148 offset:52224
	ds_read_b128 v[230:233], v148 offset:53248
	ds_read_b128 v[234:237], v148 offset:54272
	ds_read_b128 v[238:241], v148 offset:55296
	ds_read_b128 v[242:245], v148 offset:56320
	global_load_lds_dwordx4 v[154:155], off
	v_lshl_add_u64 v[154:155], v[168:169], 0, s[72:73]
	s_add_i32 m0, s25, 0x2000
	s_add_i32 s25, s62, s2
	global_load_lds_dwordx4 v[154:155], off
	v_lshl_add_u64 v[154:155], v[178:179], 0, s[72:73]
	s_mov_b32 m0, s25
	s_nop 0
	global_load_lds_dwordx4 v[154:155], off
	v_lshl_add_u64 v[154:155], v[246:247], 0, s[72:73]
	s_add_i32 m0, s25, 0x2000
	s_nop 0
	global_load_lds_dwordx4 v[154:155], off
	v_lshl_add_u64 v[154:155], v[248:249], 0, s[72:73]
	s_mov_b32 m0, s12
	s_nop 0
	global_load_lds_dwordx4 v[154:155], off
	v_lshl_add_u64 v[154:155], v[250:251], 0, s[72:73]
	s_mov_b32 m0, s13
	s_nop 0
	global_load_lds_dwordx4 v[154:155], off
	s_waitcnt vmcnt(8)
	s_waitcnt lgkmcnt(0)
	v_mfma_f32_16x16x32_f16 v[64:67], v[150:153], v[214:217], v[64:67]
	v_mfma_f32_16x16x32_f16 v[60:63], v[190:193], v[214:217], v[60:63]
	v_mfma_f32_16x16x32_f16 v[56:59], v[150:153], v[222:225], v[56:59]
	v_mfma_f32_16x16x32_f16 v[52:55], v[190:193], v[222:225], v[52:55]
	s_barrier
	s_setprio 1
	s_waitcnt lgkmcnt(0)
	v_mfma_f32_16x16x32_f16 v[40:43], v[150:153], v[230:233], v[40:43]
	v_mfma_f32_16x16x32_f16 v[36:39], v[190:193], v[230:233], v[36:39]
	v_mfma_f32_16x16x32_f16 v[24:27], v[150:153], v[238:241], v[24:27]
	v_mfma_f32_16x16x32_f16 v[20:23], v[190:193], v[238:241], v[20:23]
	v_mfma_f32_16x16x32_f16 v[64:67], v[186:189], v[218:221], v[64:67]
	v_mfma_f32_16x16x32_f16 v[60:63], v[194:197], v[218:221], v[60:63]
	v_mfma_f32_16x16x32_f16 v[56:59], v[186:189], v[226:229], v[56:59]
	v_mfma_f32_16x16x32_f16 v[52:55], v[194:197], v[226:229], v[52:55]
	v_mfma_f32_16x16x32_f16 v[40:43], v[186:189], v[234:237], v[40:43]
	v_mfma_f32_16x16x32_f16 v[36:39], v[194:197], v[234:237], v[36:39]
	v_mfma_f32_16x16x32_f16 v[24:27], v[186:189], v[242:245], v[24:27]
	v_mfma_f32_16x16x32_f16 v[20:23], v[194:197], v[242:245], v[20:23]
	s_setprio 0
	s_setprio 1
	v_mfma_f32_16x16x32_f16 v[48:51], v[198:201], v[214:217], v[48:51]
	v_mfma_f32_16x16x32_f16 v[44:47], v[206:209], v[214:217], v[44:47]
	v_mfma_f32_16x16x32_f16 v[32:35], v[198:201], v[222:225], v[32:35]
	v_mfma_f32_16x16x32_f16 v[28:31], v[206:209], v[222:225], v[28:31]
	v_mfma_f32_16x16x32_f16 v[16:19], v[198:201], v[230:233], v[16:19]
	v_mfma_f32_16x16x32_f16 v[12:15], v[206:209], v[230:233], v[12:15]
	v_mfma_f32_16x16x32_f16 v[8:11], v[198:201], v[238:241], v[8:11]
	v_mfma_f32_16x16x32_f16 v[4:7], v[206:209], v[238:241], v[4:7]
	v_mfma_f32_16x16x32_f16 v[48:51], v[202:205], v[218:221], v[48:51]
	v_mfma_f32_16x16x32_f16 v[44:47], v[210:213], v[218:221], v[44:47]
	v_mfma_f32_16x16x32_f16 v[32:35], v[202:205], v[226:229], v[32:35]
	v_mfma_f32_16x16x32_f16 v[28:31], v[210:213], v[226:229], v[28:31]
	v_mfma_f32_16x16x32_f16 v[16:19], v[202:205], v[234:237], v[16:19]
	v_mfma_f32_16x16x32_f16 v[12:15], v[210:213], v[234:237], v[12:15]
	v_mfma_f32_16x16x32_f16 v[8:11], v[202:205], v[242:245], v[8:11]
	v_mfma_f32_16x16x32_f16 v[4:7], v[210:213], v[242:245], v[4:7]
	s_setprio 0
	s_barrier
	s_add_i32 s24, s24, 2
	s_add_u32 s54, s54, 0x100
	s_addc_u32 s55, s55, 0
	s_add_u32 s21, s21, 0x100
	s_addc_u32 s23, s23, 0
	s_cmp_gt_u32 s24, 13
	s_cbranch_scc0 .LBB0_929
	s_and_b64 vcc, exec, s[44:45]
	s_cbranch_vccz .LBB0_932
	s_barrier

.LBB0_1074:
	v_add_u32_e32 v2, s67, v186
	ds_read_b128 v[132:135], v2
	ds_read_b128 v[150:153], v2 offset:1024
	ds_read_b128 v[188:191], v2 offset:2048
	ds_read_b128 v[192:195], v2 offset:3072
	v_add_u32_e32 v2, s68, v186
	ds_read_b128 v[196:199], v2
	ds_read_b128 v[200:203], v2 offset:1024
	ds_read_b128 v[204:207], v2 offset:2048
	ds_read_b128 v[208:211], v2 offset:3072
	s_add_u32 s13, s54, 0xfffc0080
	s_addc_u32 s14, s55, -1
	s_cmp_eq_u32 s12, 12
	s_cselect_b32 s57, s2, s14
	s_cselect_b32 s56, s3, s13
	s_cselect_b32 s15, s8, s11
	s_cselect_b32 s14, s9, s10
	v_lshl_add_u64 v[154:155], s[54:55], 0, v[146:147]
	s_add_i32 m0, s60, 0xc000
	ds_read_b128 v[212:215], v187
	ds_read_b128 v[216:219], v187 offset:1024
	ds_read_b128 v[220:223], v187 offset:2048
	ds_read_b128 v[224:227], v187 offset:3072
	ds_read_b128 v[228:231], v187 offset:4096
	ds_read_b128 v[232:235], v187 offset:5120
	ds_read_b128 v[236:239], v187 offset:6144
	ds_read_b128 v[240:243], v187 offset:7168
	global_load_lds_dwordx4 v[154:155], off
	v_lshl_add_u64 v[154:155], s[54:55], 0, v[148:149]
	s_add_i32 m0, s60, 0xe000
	s_nop 0
	global_load_lds_dwordx4 v[154:155], off
	s_waitcnt vmcnt(8)
	s_waitcnt lgkmcnt(0)
	v_mfma_f32_16x16x32_f16 v[128:131], v[132:135], v[212:215], v[128:131]
	v_mfma_f32_16x16x32_f16 v[124:127], v[188:191], v[212:215], v[124:127]
	v_mfma_f32_16x16x32_f16 v[112:115], v[132:135], v[220:223], v[112:115]
	v_mfma_f32_16x16x32_f16 v[108:111], v[188:191], v[220:223], v[108:111]
	s_barrier
	s_setprio 1
	s_waitcnt lgkmcnt(0)
	v_mfma_f32_16x16x32_f16 v[96:99], v[132:135], v[228:231], v[96:99]
	v_mfma_f32_16x16x32_f16 v[92:95], v[188:191], v[228:231], v[92:95]
	v_mfma_f32_16x16x32_f16 v[80:83], v[132:135], v[236:239], v[80:83]
	v_mfma_f32_16x16x32_f16 v[76:79], v[188:191], v[236:239], v[76:79]
	v_mfma_f32_16x16x32_f16 v[128:131], v[150:153], v[216:219], v[128:131]
	v_mfma_f32_16x16x32_f16 v[124:127], v[192:195], v[216:219], v[124:127]
	v_mfma_f32_16x16x32_f16 v[112:115], v[150:153], v[224:227], v[112:115]
	v_mfma_f32_16x16x32_f16 v[108:111], v[192:195], v[224:227], v[108:111]
	v_mfma_f32_16x16x32_f16 v[96:99], v[150:153], v[232:235], v[96:99]
	v_mfma_f32_16x16x32_f16 v[92:95], v[192:195], v[232:235], v[92:95]
	v_mfma_f32_16x16x32_f16 v[80:83], v[150:153], v[240:243], v[80:83]
	v_mfma_f32_16x16x32_f16 v[76:79], v[192:195], v[240:243], v[76:79]
	s_setprio 0
	s_setprio 1
	v_mfma_f32_16x16x32_f16 v[120:123], v[196:199], v[212:215], v[120:123]
	v_mfma_f32_16x16x32_f16 v[116:119], v[204:207], v[212:215], v[116:119]
	v_mfma_f32_16x16x32_f16 v[104:107], v[196:199], v[220:223], v[104:107]
	v_mfma_f32_16x16x32_f16 v[100:103], v[204:207], v[220:223], v[100:103]
	v_mfma_f32_16x16x32_f16 v[88:91], v[196:199], v[228:231], v[88:91]
	v_mfma_f32_16x16x32_f16 v[84:87], v[204:207], v[228:231], v[84:87]
	v_mfma_f32_16x16x32_f16 v[72:75], v[196:199], v[236:239], v[72:75]
	v_mfma_f32_16x16x32_f16 v[68:71], v[204:207], v[236:239], v[68:71]
	v_mfma_f32_16x16x32_f16 v[120:123], v[200:203], v[216:219], v[120:123]
	v_mfma_f32_16x16x32_f16 v[116:119], v[208:211], v[216:219], v[116:119]
	v_mfma_f32_16x16x32_f16 v[104:107], v[200:203], v[224:227], v[104:107]
	v_mfma_f32_16x16x32_f16 v[100:103], v[208:211], v[224:227], v[100:103]
	v_mfma_f32_16x16x32_f16 v[88:91], v[200:203], v[232:235], v[88:91]
	v_mfma_f32_16x16x32_f16 v[84:87], v[208:211], v[232:235], v[84:87]
	v_mfma_f32_16x16x32_f16 v[72:75], v[200:203], v[240:243], v[72:75]
	v_mfma_f32_16x16x32_f16 v[68:71], v[208:211], v[240:243], v[68:71]
	s_setprio 0
	s_barrier
	s_add_i32 s13, s67, s59
	v_lshl_add_u64 v[154:155], s[14:15], 0, v[140:141]
	s_mov_b32 m0, s13
	ds_read_b128 v[212:215], v187 offset:16384
	ds_read_b128 v[216:219], v187 offset:17408
	ds_read_b128 v[220:223], v187 offset:18432
	ds_read_b128 v[224:227], v187 offset:19456
	ds_read_b128 v[228:231], v187 offset:20480
	ds_read_b128 v[232:235], v187 offset:21504
	ds_read_b128 v[236:239], v187 offset:22528
	ds_read_b128 v[240:243], v187 offset:23552
	global_load_lds_dwordx4 v[154:155], off
	v_lshl_add_u64 v[168:169], s[14:15], 0, v[0:1]
	s_add_i32 m0, s13, 0x2000
	s_add_i32 s13, s68, s59
	global_load_lds_dwordx4 v[168:169], off
	v_lshl_add_u64 v[176:177], s[14:15], 0, v[142:143]
	s_mov_b32 m0, s13
	v_lshl_add_u64 v[178:179], s[14:15], 0, v[136:137]
	global_load_lds_dwordx4 v[176:177], off
	s_add_i32 m0, s13, 0x2000
	v_lshl_add_u64 v[244:245], s[56:57], 0, v[144:145]
	global_load_lds_dwordx4 v[178:179], off
	s_mov_b32 m0, s60
	v_lshl_add_u64 v[246:247], s[56:57], 0, v[138:139]
	global_load_lds_dwordx4 v[244:245], off
	s_mov_b32 m0, s61
	s_nop 0
	global_load_lds_dwordx4 v[246:247], off
	s_waitcnt vmcnt(8)
	s_waitcnt lgkmcnt(0)
	v_mfma_f32_16x16x32_f16 v[64:67], v[132:135], v[212:215], v[64:67]
	v_mfma_f32_16x16x32_f16 v[60:63], v[188:191], v[212:215], v[60:63]
	v_mfma_f32_16x16x32_f16 v[48:51], v[132:135], v[220:223], v[48:51]
	v_mfma_f32_16x16x32_f16 v[44:47], v[188:191], v[220:223], v[44:47]
	s_barrier
	s_setprio 1
	s_waitcnt lgkmcnt(0)
	v_mfma_f32_16x16x32_f16 v[32:35], v[132:135], v[228:231], v[32:35]
	v_mfma_f32_16x16x32_f16 v[28:31], v[188:191], v[228:231], v[28:31]
	v_mfma_f32_16x16x32_f16 v[16:19], v[132:135], v[236:239], v[16:19]
	v_mfma_f32_16x16x32_f16 v[12:15], v[188:191], v[236:239], v[12:15]
	v_mfma_f32_16x16x32_f16 v[64:67], v[150:153], v[216:219], v[64:67]
	v_mfma_f32_16x16x32_f16 v[60:63], v[192:195], v[216:219], v[60:63]
	v_mfma_f32_16x16x32_f16 v[48:51], v[150:153], v[224:227], v[48:51]
	v_mfma_f32_16x16x32_f16 v[44:47], v[192:195], v[224:227], v[44:47]
	v_mfma_f32_16x16x32_f16 v[32:35], v[150:153], v[232:235], v[32:35]
	v_mfma_f32_16x16x32_f16 v[28:31], v[192:195], v[232:235], v[28:31]
	v_mfma_f32_16x16x32_f16 v[16:19], v[150:153], v[240:243], v[16:19]
	v_mfma_f32_16x16x32_f16 v[12:15], v[192:195], v[240:243], v[12:15]
	s_setprio 0
	s_setprio 1
	v_mfma_f32_16x16x32_f16 v[56:59], v[196:199], v[212:215], v[56:59]
	v_mfma_f32_16x16x32_f16 v[52:55], v[204:207], v[212:215], v[52:55]
	v_mfma_f32_16x16x32_f16 v[40:43], v[196:199], v[220:223], v[40:43]
	v_mfma_f32_16x16x32_f16 v[36:39], v[204:207], v[220:223], v[36:39]
	v_mfma_f32_16x16x32_f16 v[24:27], v[196:199], v[228:231], v[24:27]
	v_mfma_f32_16x16x32_f16 v[20:23], v[204:207], v[228:231], v[20:23]
	v_mfma_f32_16x16x32_f16 v[8:11], v[196:199], v[236:239], v[8:11]
	v_mfma_f32_16x16x32_f16 v[4:7], v[204:207], v[236:239], v[4:7]
	v_mfma_f32_16x16x32_f16 v[56:59], v[200:203], v[216:219], v[56:59]
	v_mfma_f32_16x16x32_f16 v[52:55], v[208:211], v[216:219], v[52:55]
	v_mfma_f32_16x16x32_f16 v[40:43], v[200:203], v[224:227], v[40:43]
	v_mfma_f32_16x16x32_f16 v[36:39], v[208:211], v[224:227], v[36:39]
	v_mfma_f32_16x16x32_f16 v[24:27], v[200:203], v[232:235], v[24:27]
	v_mfma_f32_16x16x32_f16 v[20:23], v[208:211], v[232:235], v[20:23]
	v_mfma_f32_16x16x32_f16 v[8:11], v[200:203], v[240:243], v[8:11]
	v_mfma_f32_16x16x32_f16 v[4:7], v[208:211], v[240:243], v[4:7]
	s_setprio 0
	s_barrier
	v_add_u32_e32 v2, s82, v186
	ds_read_b128 v[132:135], v2
	ds_read_b128 v[150:153], v2 offset:1024
	ds_read_b128 v[188:191], v2 offset:2048
	ds_read_b128 v[192:195], v2 offset:3072
	v_add_u32_e32 v2, s62, v186
	ds_read_b128 v[196:199], v2
	ds_read_b128 v[200:203], v2 offset:1024
	ds_read_b128 v[204:207], v2 offset:2048
	ds_read_b128 v[208:211], v2 offset:3072
	s_add_u32 s14, s56, 0x40000
	s_addc_u32 s15, s57, 0
	s_mov_b32 m0, s90
	v_lshl_add_u64 v[248:249], s[14:15], 0, v[144:145]
	ds_read_b128 v[212:215], v187 offset:32768
	ds_read_b128 v[216:219], v187 offset:33792
	ds_read_b128 v[220:223], v187 offset:34816
	ds_read_b128 v[224:227], v187 offset:35840
	ds_read_b128 v[228:231], v187 offset:36864
	ds_read_b128 v[232:235], v187 offset:37888
	ds_read_b128 v[236:239], v187 offset:38912
	ds_read_b128 v[240:243], v187 offset:39936
	global_load_lds_dwordx4 v[248:249], off
	v_lshl_add_u64 v[248:249], s[14:15], 0, v[138:139]
	s_mov_b32 m0, s91
	s_nop 0
	global_load_lds_dwordx4 v[248:249], off
	s_waitcnt vmcnt(8)
	s_waitcnt lgkmcnt(0)
	v_mfma_f32_16x16x32_f16 v[128:131], v[132:135], v[212:215], v[128:131]
	v_mfma_f32_16x16x32_f16 v[124:127], v[188:191], v[212:215], v[124:127]
	v_mfma_f32_16x16x32_f16 v[112:115], v[132:135], v[220:223], v[112:115]
	v_mfma_f32_16x16x32_f16 v[108:111], v[188:191], v[220:223], v[108:111]
	s_barrier
	s_setprio 1
	s_waitcnt lgkmcnt(0)
	v_mfma_f32_16x16x32_f16 v[96:99], v[132:135], v[228:231], v[96:99]
	v_mfma_f32_16x16x32_f16 v[92:95], v[188:191], v[228:231], v[92:95]
	v_mfma_f32_16x16x32_f16 v[80:83], v[132:135], v[236:239], v[80:83]
	v_mfma_f32_16x16x32_f16 v[76:79], v[188:191], v[236:239], v[76:79]
	v_mfma_f32_16x16x32_f16 v[128:131], v[150:153], v[216:219], v[128:131]
	v_mfma_f32_16x16x32_f16 v[124:127], v[192:195], v[216:219], v[124:127]
	v_mfma_f32_16x16x32_f16 v[112:115], v[150:153], v[224:227], v[112:115]
	v_mfma_f32_16x16x32_f16 v[108:111], v[192:195], v[224:227], v[108:111]
	v_mfma_f32_16x16x32_f16 v[96:99], v[150:153], v[232:235], v[96:99]
	v_mfma_f32_16x16x32_f16 v[92:95], v[192:195], v[232:235], v[92:95]
	v_mfma_f32_16x16x32_f16 v[80:83], v[150:153], v[240:243], v[80:83]
	v_mfma_f32_16x16x32_f16 v[76:79], v[192:195], v[240:243], v[76:79]
	s_setprio 0
	s_setprio 1
	v_mfma_f32_16x16x32_f16 v[120:123], v[196:199], v[212:215], v[120:123]
	v_mfma_f32_16x16x32_f16 v[116:119], v[204:207], v[212:215], v[116:119]
	v_mfma_f32_16x16x32_f16 v[104:107], v[196:199], v[220:223], v[104:107]
	v_mfma_f32_16x16x32_f16 v[100:103], v[204:207], v[220:223], v[100:103]
	v_mfma_f32_16x16x32_f16 v[88:91], v[196:199], v[228:231], v[88:91]
	v_mfma_f32_16x16x32_f16 v[84:87], v[204:207], v[228:231], v[84:87]
	v_mfma_f32_16x16x32_f16 v[72:75], v[196:199], v[236:239], v[72:75]
	v_mfma_f32_16x16x32_f16 v[68:71], v[204:207], v[236:239], v[68:71]
	v_mfma_f32_16x16x32_f16 v[120:123], v[200:203], v[216:219], v[120:123]
	v_mfma_f32_16x16x32_f16 v[116:119], v[208:211], v[216:219], v[116:119]
	v_mfma_f32_16x16x32_f16 v[104:107], v[200:203], v[224:227], v[104:107]
	v_mfma_f32_16x16x32_f16 v[100:103], v[208:211], v[224:227], v[100:103]
	v_mfma_f32_16x16x32_f16 v[88:91], v[200:203], v[232:235], v[88:91]
	v_mfma_f32_16x16x32_f16 v[84:87], v[208:211], v[232:235], v[84:87]
	v_mfma_f32_16x16x32_f16 v[72:75], v[200:203], v[240:243], v[72:75]
	v_mfma_f32_16x16x32_f16 v[68:71], v[208:211], v[240:243], v[68:71]
	s_setprio 0
	s_barrier
	s_add_i32 s13, s82, s59
	v_lshl_add_u64 v[154:155], v[154:155], 0, s[72:73]
	s_mov_b32 m0, s13
	ds_read_b128 v[212:215], v187 offset:49152
	ds_read_b128 v[216:219], v187 offset:50176
	ds_read_b128 v[220:223], v187 offset:51200
	ds_read_b128 v[224:227], v187 offset:52224
	ds_read_b128 v[228:231], v187 offset:53248
	ds_read_b128 v[232:235], v187 offset:54272
	ds_read_b128 v[236:239], v187 offset:55296
	ds_read_b128 v[240:243], v187 offset:56320
	global_load_lds_dwordx4 v[154:155], off
	v_lshl_add_u64 v[154:155], v[168:169], 0, s[72:73]
	s_add_i32 m0, s13, 0x2000
	s_add_i32 s13, s62, s59
	global_load_lds_dwordx4 v[154:155], off
	v_lshl_add_u64 v[154:155], v[176:177], 0, s[72:73]
	s_mov_b32 m0, s13
	s_nop 0
	global_load_lds_dwordx4 v[154:155], off
	v_lshl_add_u64 v[154:155], v[178:179], 0, s[72:73]
	s_add_i32 m0, s13, 0x2000
	s_nop 0
	global_load_lds_dwordx4 v[154:155], off
	v_lshl_add_u64 v[154:155], v[244:245], 0, s[72:73]
	s_mov_b32 m0, s7
	s_nop 0
	global_load_lds_dwordx4 v[154:155], off
	v_lshl_add_u64 v[154:155], v[246:247], 0, s[72:73]
	s_mov_b32 m0, s86
	s_nop 0
	global_load_lds_dwordx4 v[154:155], off
	s_waitcnt vmcnt(8)
	s_waitcnt lgkmcnt(0)
	v_mfma_f32_16x16x32_f16 v[64:67], v[132:135], v[212:215], v[64:67]
	v_mfma_f32_16x16x32_f16 v[60:63], v[188:191], v[212:215], v[60:63]
	v_mfma_f32_16x16x32_f16 v[48:51], v[132:135], v[220:223], v[48:51]
	v_mfma_f32_16x16x32_f16 v[44:47], v[188:191], v[220:223], v[44:47]
	s_barrier
	s_setprio 1
	s_waitcnt lgkmcnt(0)
	v_mfma_f32_16x16x32_f16 v[32:35], v[132:135], v[228:231], v[32:35]
	v_mfma_f32_16x16x32_f16 v[28:31], v[188:191], v[228:231], v[28:31]
	v_mfma_f32_16x16x32_f16 v[16:19], v[132:135], v[236:239], v[16:19]
	v_mfma_f32_16x16x32_f16 v[12:15], v[188:191], v[236:239], v[12:15]
	v_mfma_f32_16x16x32_f16 v[64:67], v[150:153], v[216:219], v[64:67]
	v_mfma_f32_16x16x32_f16 v[60:63], v[192:195], v[216:219], v[60:63]
	v_mfma_f32_16x16x32_f16 v[48:51], v[150:153], v[224:227], v[48:51]
	v_mfma_f32_16x16x32_f16 v[44:47], v[192:195], v[224:227], v[44:47]
	v_mfma_f32_16x16x32_f16 v[32:35], v[150:153], v[232:235], v[32:35]
	v_mfma_f32_16x16x32_f16 v[28:31], v[192:195], v[232:235], v[28:31]
	v_mfma_f32_16x16x32_f16 v[16:19], v[150:153], v[240:243], v[16:19]
	v_mfma_f32_16x16x32_f16 v[12:15], v[192:195], v[240:243], v[12:15]
	s_setprio 0
	s_setprio 1
	v_mfma_f32_16x16x32_f16 v[56:59], v[196:199], v[212:215], v[56:59]
	v_mfma_f32_16x16x32_f16 v[52:55], v[204:207], v[212:215], v[52:55]
	v_mfma_f32_16x16x32_f16 v[40:43], v[196:199], v[220:223], v[40:43]
	v_mfma_f32_16x16x32_f16 v[36:39], v[204:207], v[220:223], v[36:39]
	v_mfma_f32_16x16x32_f16 v[24:27], v[196:199], v[228:231], v[24:27]
	v_mfma_f32_16x16x32_f16 v[20:23], v[204:207], v[228:231], v[20:23]
	v_mfma_f32_16x16x32_f16 v[8:11], v[196:199], v[236:239], v[8:11]
	v_mfma_f32_16x16x32_f16 v[4:7], v[204:207], v[236:239], v[4:7]
	v_mfma_f32_16x16x32_f16 v[56:59], v[200:203], v[216:219], v[56:59]
	v_mfma_f32_16x16x32_f16 v[52:55], v[208:211], v[216:219], v[52:55]
	v_mfma_f32_16x16x32_f16 v[40:43], v[200:203], v[224:227], v[40:43]
	v_mfma_f32_16x16x32_f16 v[36:39], v[208:211], v[224:227], v[36:39]
	v_mfma_f32_16x16x32_f16 v[24:27], v[200:203], v[232:235], v[24:27]
	v_mfma_f32_16x16x32_f16 v[20:23], v[208:211], v[232:235], v[20:23]
	v_mfma_f32_16x16x32_f16 v[8:11], v[200:203], v[240:243], v[8:11]
	v_mfma_f32_16x16x32_f16 v[4:7], v[208:211], v[240:243], v[4:7]
	s_setprio 0
	s_barrier
	s_add_i32 s12, s12, 2
	s_add_u32 s54, s54, 0x100
	s_addc_u32 s55, s55, 0
	s_add_u32 s10, s10, 0x100
	s_addc_u32 s11, s11, 0
	s_cmp_gt_u32 s12, 13
	s_cbranch_scc0 .LBB0_1074
	s_and_b64 vcc, exec, s[44:45]
	s_cbranch_vccz .LBB0_1077
	s_barrier

.LBB0_1145:
	v_add_u32_e32 v157, s67, v146
	ds_read_b128 v[148:151], v157
	ds_read_b128 v[152:155], v157 offset:1024
	ds_read_b128 v[186:189], v157 offset:2048
	ds_read_b128 v[190:193], v157 offset:3072
	v_add_u32_e32 v157, s68, v146
	s_add_u32 s28, s54, vcc_lo
	ds_read_b128 v[194:197], v157
	ds_read_b128 v[198:201], v157 offset:1024
	ds_read_b128 v[202:205], v157 offset:2048
	ds_read_b128 v[206:209], v157 offset:3072
	s_addc_u32 s29, s55, vcc_hi
	s_add_u32 s28, s28, 0x100
	s_addc_u32 s29, s29, 0
	s_add_u32 s30, s19, vcc_lo
	s_addc_u32 s31, s20, vcc_hi
	s_cmpk_eq_i32 vcc_lo, 0x700
	s_cselect_b32 s61, s21, s29
	s_cselect_b32 s60, s24, s28
	s_cselect_b32 s31, s25, s31
	s_cselect_b32 s30, s26, s30
	v_lshl_add_u64 v[168:169], v[140:141], 0, vcc
	s_add_i32 m0, s10, 0xc000
	ds_read_b128 v[210:213], v147
	ds_read_b128 v[214:217], v147 offset:1024
	ds_read_b128 v[218:221], v147 offset:2048
	ds_read_b128 v[222:225], v147 offset:3072
	ds_read_b128 v[226:229], v147 offset:4096
	ds_read_b128 v[230:233], v147 offset:5120
	ds_read_b128 v[234:237], v147 offset:6144
	ds_read_b128 v[238:241], v147 offset:7168
	global_load_lds_dwordx4 v[168:169], off
	v_lshl_add_u64 v[168:169], v[142:143], 0, vcc
	s_add_i32 m0, s10, 0xe000
	s_nop 0
	global_load_lds_dwordx4 v[168:169], off
	s_waitcnt vmcnt(8)
	s_waitcnt lgkmcnt(0)
	v_mfma_f32_16x16x32_bf16 v[36:39], v[148:151], v[210:213], v[36:39]
	v_mfma_f32_16x16x32_bf16 v[20:23], v[186:189], v[210:213], v[20:23]
	v_mfma_f32_16x16x32_bf16 v[40:43], v[148:151], v[218:221], v[40:43]
	v_mfma_f32_16x16x32_bf16 v[24:27], v[186:189], v[218:221], v[24:27]
	s_barrier
	s_setprio 1
	s_waitcnt lgkmcnt(0)
	v_mfma_f32_16x16x32_bf16 v[100:103], v[148:151], v[226:229], v[100:103]
	v_mfma_f32_16x16x32_bf16 v[84:87], v[186:189], v[226:229], v[84:87]
	v_mfma_f32_16x16x32_bf16 v[104:107], v[148:151], v[234:237], v[104:107]
	v_mfma_f32_16x16x32_bf16 v[88:91], v[186:189], v[234:237], v[88:91]
	v_mfma_f32_16x16x32_bf16 v[36:39], v[152:155], v[214:217], v[36:39]
	v_mfma_f32_16x16x32_bf16 v[20:23], v[190:193], v[214:217], v[20:23]
	v_mfma_f32_16x16x32_bf16 v[40:43], v[152:155], v[222:225], v[40:43]
	v_mfma_f32_16x16x32_bf16 v[24:27], v[190:193], v[222:225], v[24:27]
	v_mfma_f32_16x16x32_bf16 v[100:103], v[152:155], v[230:233], v[100:103]
	v_mfma_f32_16x16x32_bf16 v[84:87], v[190:193], v[230:233], v[84:87]
	v_mfma_f32_16x16x32_bf16 v[104:107], v[152:155], v[238:241], v[104:107]
	v_mfma_f32_16x16x32_bf16 v[88:91], v[190:193], v[238:241], v[88:91]
	s_setprio 0
	s_setprio 1
	v_mfma_f32_16x16x32_bf16 v[12:15], v[194:197], v[210:213], v[12:15]
	v_mfma_f32_16x16x32_bf16 v[4:7], v[202:205], v[210:213], v[4:7]
	v_mfma_f32_16x16x32_bf16 v[16:19], v[194:197], v[218:221], v[16:19]
	v_mfma_f32_16x16x32_bf16 v[8:11], v[202:205], v[218:221], v[8:11]
	v_mfma_f32_16x16x32_bf16 v[64:67], v[194:197], v[226:229], v[64:67]
	v_mfma_f32_16x16x32_bf16 v[32:35], v[202:205], v[226:229], v[32:35]
	v_mfma_f32_16x16x32_bf16 v[68:71], v[194:197], v[234:237], v[68:71]
	v_mfma_f32_16x16x32_bf16 v[28:31], v[202:205], v[234:237], v[28:31]
	v_mfma_f32_16x16x32_bf16 v[12:15], v[198:201], v[214:217], v[12:15]
	v_mfma_f32_16x16x32_bf16 v[4:7], v[206:209], v[214:217], v[4:7]
	v_mfma_f32_16x16x32_bf16 v[16:19], v[198:201], v[222:225], v[16:19]
	v_mfma_f32_16x16x32_bf16 v[8:11], v[206:209], v[222:225], v[8:11]
	v_mfma_f32_16x16x32_bf16 v[64:67], v[198:201], v[230:233], v[64:67]
	v_mfma_f32_16x16x32_bf16 v[32:35], v[206:209], v[230:233], v[32:35]
	v_mfma_f32_16x16x32_bf16 v[68:71], v[198:201], v[238:241], v[68:71]
	v_mfma_f32_16x16x32_bf16 v[28:31], v[206:209], v[238:241], v[28:31]
	s_setprio 0
	s_barrier
	s_add_i32 s28, s67, s9
	v_lshl_add_u64 v[168:169], s[30:31], 0, v[2:3]
	s_mov_b32 m0, s28
	ds_read_b128 v[210:213], v147 offset:16384
	ds_read_b128 v[214:217], v147 offset:17408
	ds_read_b128 v[218:221], v147 offset:18432
	ds_read_b128 v[222:225], v147 offset:19456
	ds_read_b128 v[226:229], v147 offset:20480
	ds_read_b128 v[230:233], v147 offset:21504
	ds_read_b128 v[234:237], v147 offset:22528
	ds_read_b128 v[238:241], v147 offset:23552
	global_load_lds_dwordx4 v[168:169], off
	v_lshl_add_u64 v[176:177], s[30:31], 0, v[0:1]
	s_add_i32 m0, s28, 0x2000
	s_add_i32 s28, s68, s9
	global_load_lds_dwordx4 v[176:177], off
	v_lshl_add_u64 v[178:179], s[30:31], 0, v[134:135]
	s_mov_b32 m0, s28
	v_lshl_add_u64 v[242:243], s[30:31], 0, v[132:133]
	global_load_lds_dwordx4 v[178:179], off
	s_add_i32 m0, s28, 0x2000
	v_lshl_add_u64 v[244:245], s[60:61], 0, v[2:3]
	global_load_lds_dwordx4 v[242:243], off
	s_mov_b32 m0, s10
	v_lshl_add_u64 v[246:247], s[60:61], 0, v[0:1]
	global_load_lds_dwordx4 v[244:245], off
	s_mov_b32 m0, s11
	s_nop 0
	global_load_lds_dwordx4 v[246:247], off
	s_waitcnt vmcnt(8)
	s_waitcnt lgkmcnt(0)
	v_mfma_f32_16x16x32_bf16 v[128:131], v[148:151], v[210:213], v[128:131]
	v_mfma_f32_16x16x32_bf16 v[124:127], v[186:189], v[210:213], v[124:127]
	v_mfma_f32_16x16x32_bf16 v[120:123], v[148:151], v[218:221], v[120:123]
	v_mfma_f32_16x16x32_bf16 v[116:119], v[186:189], v[218:221], v[116:119]
	s_barrier
	s_setprio 1
	s_waitcnt lgkmcnt(0)
	v_mfma_f32_16x16x32_bf16 v[80:83], v[148:151], v[226:229], v[80:83]
	v_mfma_f32_16x16x32_bf16 v[76:79], v[186:189], v[226:229], v[76:79]
	v_mfma_f32_16x16x32_bf16 v[72:75], v[148:151], v[234:237], v[72:75]
	v_mfma_f32_16x16x32_bf16 v[60:63], v[186:189], v[234:237], v[60:63]
	v_mfma_f32_16x16x32_bf16 v[128:131], v[152:155], v[214:217], v[128:131]
	v_mfma_f32_16x16x32_bf16 v[124:127], v[190:193], v[214:217], v[124:127]
	v_mfma_f32_16x16x32_bf16 v[120:123], v[152:155], v[222:225], v[120:123]
	v_mfma_f32_16x16x32_bf16 v[116:119], v[190:193], v[222:225], v[116:119]
	v_mfma_f32_16x16x32_bf16 v[80:83], v[152:155], v[230:233], v[80:83]
	v_mfma_f32_16x16x32_bf16 v[76:79], v[190:193], v[230:233], v[76:79]
	v_mfma_f32_16x16x32_bf16 v[72:75], v[152:155], v[238:241], v[72:75]
	v_mfma_f32_16x16x32_bf16 v[60:63], v[190:193], v[238:241], v[60:63]
	s_setprio 0
	s_setprio 1
	v_mfma_f32_16x16x32_bf16 v[108:111], v[194:197], v[210:213], v[108:111]
	v_mfma_f32_16x16x32_bf16 v[92:95], v[202:205], v[210:213], v[92:95]
	v_mfma_f32_16x16x32_bf16 v[112:115], v[194:197], v[218:221], v[112:115]
	v_mfma_f32_16x16x32_bf16 v[96:99], v[202:205], v[218:221], v[96:99]
	v_mfma_f32_16x16x32_bf16 v[56:59], v[194:197], v[226:229], v[56:59]
	v_mfma_f32_16x16x32_bf16 v[52:55], v[202:205], v[226:229], v[52:55]
	v_mfma_f32_16x16x32_bf16 v[48:51], v[194:197], v[234:237], v[48:51]
	v_mfma_f32_16x16x32_bf16 v[44:47], v[202:205], v[234:237], v[44:47]
	v_mfma_f32_16x16x32_bf16 v[108:111], v[198:201], v[214:217], v[108:111]
	v_mfma_f32_16x16x32_bf16 v[92:95], v[206:209], v[214:217], v[92:95]
	v_mfma_f32_16x16x32_bf16 v[112:115], v[198:201], v[222:225], v[112:115]
	v_mfma_f32_16x16x32_bf16 v[96:99], v[206:209], v[222:225], v[96:99]
	v_mfma_f32_16x16x32_bf16 v[56:59], v[198:201], v[230:233], v[56:59]
	v_mfma_f32_16x16x32_bf16 v[52:55], v[206:209], v[230:233], v[52:55]
	v_mfma_f32_16x16x32_bf16 v[48:51], v[198:201], v[238:241], v[48:51]
	v_mfma_f32_16x16x32_bf16 v[44:47], v[206:209], v[238:241], v[44:47]
	s_setprio 0
	s_barrier
	v_add_u32_e32 v157, s82, v146
	ds_read_b128 v[148:151], v157
	ds_read_b128 v[152:155], v157 offset:1024
	ds_read_b128 v[186:189], v157 offset:2048
	ds_read_b128 v[190:193], v157 offset:3072
	v_add_u32_e32 v157, s62, v146
	ds_read_b128 v[194:197], v157
	ds_read_b128 v[198:201], v157 offset:1024
	ds_read_b128 v[202:205], v157 offset:2048
	ds_read_b128 v[206:209], v157 offset:3072
	s_add_u32 s30, s60, 0x40000
	s_addc_u32 s31, s61, 0
	s_mov_b32 m0, s12
	v_lshl_add_u64 v[248:249], s[30:31], 0, v[2:3]
	ds_read_b128 v[210:213], v147 offset:32768
	ds_read_b128 v[214:217], v147 offset:33792
	ds_read_b128 v[218:221], v147 offset:34816
	ds_read_b128 v[222:225], v147 offset:35840
	ds_read_b128 v[226:229], v147 offset:36864
	ds_read_b128 v[230:233], v147 offset:37888
	ds_read_b128 v[234:237], v147 offset:38912
	ds_read_b128 v[238:241], v147 offset:39936
	global_load_lds_dwordx4 v[248:249], off
	v_lshl_add_u64 v[248:249], s[30:31], 0, v[0:1]
	s_mov_b32 m0, s13
	s_nop 0
	global_load_lds_dwordx4 v[248:249], off
	s_waitcnt vmcnt(8)
	s_waitcnt lgkmcnt(0)
	v_mfma_f32_16x16x32_bf16 v[36:39], v[148:151], v[210:213], v[36:39]
	v_mfma_f32_16x16x32_bf16 v[20:23], v[186:189], v[210:213], v[20:23]
	v_mfma_f32_16x16x32_bf16 v[40:43], v[148:151], v[218:221], v[40:43]
	v_mfma_f32_16x16x32_bf16 v[24:27], v[186:189], v[218:221], v[24:27]
	s_barrier
	s_setprio 1
	s_waitcnt lgkmcnt(0)
	v_mfma_f32_16x16x32_bf16 v[100:103], v[148:151], v[226:229], v[100:103]
	v_mfma_f32_16x16x32_bf16 v[84:87], v[186:189], v[226:229], v[84:87]
	v_mfma_f32_16x16x32_bf16 v[104:107], v[148:151], v[234:237], v[104:107]
	v_mfma_f32_16x16x32_bf16 v[88:91], v[186:189], v[234:237], v[88:91]
	v_mfma_f32_16x16x32_bf16 v[36:39], v[152:155], v[214:217], v[36:39]
	v_mfma_f32_16x16x32_bf16 v[20:23], v[190:193], v[214:217], v[20:23]
	v_mfma_f32_16x16x32_bf16 v[40:43], v[152:155], v[222:225], v[40:43]
	v_mfma_f32_16x16x32_bf16 v[24:27], v[190:193], v[222:225], v[24:27]
	v_mfma_f32_16x16x32_bf16 v[100:103], v[152:155], v[230:233], v[100:103]
	v_mfma_f32_16x16x32_bf16 v[84:87], v[190:193], v[230:233], v[84:87]
	v_mfma_f32_16x16x32_bf16 v[104:107], v[152:155], v[238:241], v[104:107]
	v_mfma_f32_16x16x32_bf16 v[88:91], v[190:193], v[238:241], v[88:91]
	s_setprio 0
	s_setprio 1
	v_mfma_f32_16x16x32_bf16 v[12:15], v[194:197], v[210:213], v[12:15]
	v_mfma_f32_16x16x32_bf16 v[4:7], v[202:205], v[210:213], v[4:7]
	v_mfma_f32_16x16x32_bf16 v[16:19], v[194:197], v[218:221], v[16:19]
	v_mfma_f32_16x16x32_bf16 v[8:11], v[202:205], v[218:221], v[8:11]
	v_mfma_f32_16x16x32_bf16 v[64:67], v[194:197], v[226:229], v[64:67]
	v_mfma_f32_16x16x32_bf16 v[32:35], v[202:205], v[226:229], v[32:35]
	v_mfma_f32_16x16x32_bf16 v[68:71], v[194:197], v[234:237], v[68:71]
	v_mfma_f32_16x16x32_bf16 v[28:31], v[202:205], v[234:237], v[28:31]
	v_mfma_f32_16x16x32_bf16 v[12:15], v[198:201], v[214:217], v[12:15]
	v_mfma_f32_16x16x32_bf16 v[4:7], v[206:209], v[214:217], v[4:7]
	v_mfma_f32_16x16x32_bf16 v[16:19], v[198:201], v[222:225], v[16:19]
	v_mfma_f32_16x16x32_bf16 v[8:11], v[206:209], v[222:225], v[8:11]
	v_mfma_f32_16x16x32_bf16 v[64:67], v[198:201], v[230:233], v[64:67]
	v_mfma_f32_16x16x32_bf16 v[32:35], v[206:209], v[230:233], v[32:35]
	v_mfma_f32_16x16x32_bf16 v[68:71], v[198:201], v[238:241], v[68:71]
	v_mfma_f32_16x16x32_bf16 v[28:31], v[206:209], v[238:241], v[28:31]
	s_setprio 0
	s_barrier
	s_add_i32 s28, s82, s9
	v_lshl_add_u64 v[168:169], v[168:169], 0, s[72:73]
	s_mov_b32 m0, s28
	ds_read_b128 v[210:213], v147 offset:49152
	ds_read_b128 v[214:217], v147 offset:50176
	ds_read_b128 v[218:221], v147 offset:51200
	ds_read_b128 v[222:225], v147 offset:52224
	ds_read_b128 v[226:229], v147 offset:53248
	ds_read_b128 v[230:233], v147 offset:54272
	ds_read_b128 v[234:237], v147 offset:55296
	ds_read_b128 v[238:241], v147 offset:56320
	global_load_lds_dwordx4 v[168:169], off
	v_lshl_add_u64 v[168:169], v[176:177], 0, s[72:73]
	s_add_i32 m0, s28, 0x2000
	s_add_i32 s28, s62, s9
	global_load_lds_dwordx4 v[168:169], off
	v_lshl_add_u64 v[168:169], v[178:179], 0, s[72:73]
	s_mov_b32 m0, s28
	s_nop 0
	global_load_lds_dwordx4 v[168:169], off
	v_lshl_add_u64 v[168:169], v[242:243], 0, s[72:73]
	s_add_i32 m0, s28, 0x2000
	s_nop 0
	global_load_lds_dwordx4 v[168:169], off
	v_lshl_add_u64 v[168:169], v[244:245], 0, s[72:73]
	s_mov_b32 m0, s15
	s_nop 0
	global_load_lds_dwordx4 v[168:169], off
	v_lshl_add_u64 v[168:169], v[246:247], 0, s[72:73]
	s_mov_b32 m0, s16
	s_nop 0
	global_load_lds_dwordx4 v[168:169], off
	s_waitcnt vmcnt(8)
	s_waitcnt lgkmcnt(0)
	v_mfma_f32_16x16x32_bf16 v[128:131], v[148:151], v[210:213], v[128:131]
	v_mfma_f32_16x16x32_bf16 v[124:127], v[186:189], v[210:213], v[124:127]
	v_mfma_f32_16x16x32_bf16 v[120:123], v[148:151], v[218:221], v[120:123]
	v_mfma_f32_16x16x32_bf16 v[116:119], v[186:189], v[218:221], v[116:119]
	s_barrier
	s_setprio 1
	s_waitcnt lgkmcnt(0)
	v_mfma_f32_16x16x32_bf16 v[80:83], v[148:151], v[226:229], v[80:83]
	v_mfma_f32_16x16x32_bf16 v[76:79], v[186:189], v[226:229], v[76:79]
	v_mfma_f32_16x16x32_bf16 v[72:75], v[148:151], v[234:237], v[72:75]
	v_mfma_f32_16x16x32_bf16 v[60:63], v[186:189], v[234:237], v[60:63]
	v_mfma_f32_16x16x32_bf16 v[128:131], v[152:155], v[214:217], v[128:131]
	v_mfma_f32_16x16x32_bf16 v[124:127], v[190:193], v[214:217], v[124:127]
	v_mfma_f32_16x16x32_bf16 v[120:123], v[152:155], v[222:225], v[120:123]
	v_mfma_f32_16x16x32_bf16 v[116:119], v[190:193], v[222:225], v[116:119]
	v_mfma_f32_16x16x32_bf16 v[80:83], v[152:155], v[230:233], v[80:83]
	v_mfma_f32_16x16x32_bf16 v[76:79], v[190:193], v[230:233], v[76:79]
	v_mfma_f32_16x16x32_bf16 v[72:75], v[152:155], v[238:241], v[72:75]
	v_mfma_f32_16x16x32_bf16 v[60:63], v[190:193], v[238:241], v[60:63]
	s_setprio 0
	s_setprio 1
	v_mfma_f32_16x16x32_bf16 v[108:111], v[194:197], v[210:213], v[108:111]
	v_mfma_f32_16x16x32_bf16 v[92:95], v[202:205], v[210:213], v[92:95]
	v_mfma_f32_16x16x32_bf16 v[112:115], v[194:197], v[218:221], v[112:115]
	v_mfma_f32_16x16x32_bf16 v[96:99], v[202:205], v[218:221], v[96:99]
	v_mfma_f32_16x16x32_bf16 v[56:59], v[194:197], v[226:229], v[56:59]
	v_mfma_f32_16x16x32_bf16 v[52:55], v[202:205], v[226:229], v[52:55]
	v_mfma_f32_16x16x32_bf16 v[48:51], v[194:197], v[234:237], v[48:51]
	v_mfma_f32_16x16x32_bf16 v[44:47], v[202:205], v[234:237], v[44:47]
	v_mfma_f32_16x16x32_bf16 v[108:111], v[198:201], v[214:217], v[108:111]
	v_mfma_f32_16x16x32_bf16 v[92:95], v[206:209], v[214:217], v[92:95]
	v_mfma_f32_16x16x32_bf16 v[112:115], v[198:201], v[222:225], v[112:115]
	v_mfma_f32_16x16x32_bf16 v[96:99], v[206:209], v[222:225], v[96:99]
	v_mfma_f32_16x16x32_bf16 v[56:59], v[198:201], v[230:233], v[56:59]
	v_mfma_f32_16x16x32_bf16 v[52:55], v[206:209], v[230:233], v[52:55]
	v_mfma_f32_16x16x32_bf16 v[48:51], v[198:201], v[238:241], v[48:51]
	v_mfma_f32_16x16x32_bf16 v[44:47], v[206:209], v[238:241], v[44:47]
	s_setprio 0
	s_barrier
	s_add_i32 s27, s27, 2
	s_add_u32 vcc_lo, vcc_lo, 0x100
	s_addc_u32 vcc_hi, vcc_hi, 0
	s_cmp_gt_u32 s27, 13
	s_cbranch_scc0 .LBB0_1145
	s_and_b64 vcc, exec, s[48:49]
	s_cbranch_vccz .LBB0_1148
	s_barrier

.LBB0_1201:
	v_add_u32_e32 v157, s67, v146
	ds_read_b128 v[148:151], v157
	ds_read_b128 v[152:155], v157 offset:1024
	ds_read_b128 v[186:189], v157 offset:2048
	ds_read_b128 v[190:193], v157 offset:3072
	v_add_u32_e32 v157, s68, v146
	s_add_u32 s28, s54, vcc_lo
	ds_read_b128 v[194:197], v157
	ds_read_b128 v[198:201], v157 offset:1024
	ds_read_b128 v[202:205], v157 offset:2048
	ds_read_b128 v[206:209], v157 offset:3072
	s_addc_u32 s29, s55, vcc_hi
	s_add_u32 s28, s28, 0x100
	s_addc_u32 s29, s29, 0
	s_add_u32 s30, s19, vcc_lo
	s_addc_u32 s31, s20, vcc_hi
	s_cmpk_eq_i32 vcc_lo, 0x700
	s_cselect_b32 s59, s21, s29
	s_cselect_b32 s58, s24, s28
	s_cselect_b32 s31, s25, s31
	s_cselect_b32 s30, s26, s30
	v_lshl_add_u64 v[168:169], v[140:141], 0, vcc
	s_add_i32 m0, s10, 0xc000
	ds_read_b128 v[210:213], v147
	ds_read_b128 v[214:217], v147 offset:1024
	ds_read_b128 v[218:221], v147 offset:2048
	ds_read_b128 v[222:225], v147 offset:3072
	ds_read_b128 v[226:229], v147 offset:4096
	ds_read_b128 v[230:233], v147 offset:5120
	ds_read_b128 v[234:237], v147 offset:6144
	ds_read_b128 v[238:241], v147 offset:7168
	global_load_lds_dwordx4 v[168:169], off
	v_lshl_add_u64 v[168:169], v[142:143], 0, vcc
	s_add_i32 m0, s10, 0xe000
	s_nop 0
	global_load_lds_dwordx4 v[168:169], off
	s_waitcnt vmcnt(8)
	s_waitcnt lgkmcnt(0)
	v_mfma_f32_16x16x32_bf16 v[36:39], v[148:151], v[210:213], v[36:39]
	v_mfma_f32_16x16x32_bf16 v[24:27], v[186:189], v[210:213], v[24:27]
	v_mfma_f32_16x16x32_bf16 v[40:43], v[148:151], v[218:221], v[40:43]
	v_mfma_f32_16x16x32_bf16 v[20:23], v[186:189], v[218:221], v[20:23]
	s_barrier
	s_setprio 1
	s_waitcnt lgkmcnt(0)
	v_mfma_f32_16x16x32_bf16 v[100:103], v[148:151], v[226:229], v[100:103]
	v_mfma_f32_16x16x32_bf16 v[88:91], v[186:189], v[226:229], v[88:91]
	v_mfma_f32_16x16x32_bf16 v[104:107], v[148:151], v[234:237], v[104:107]
	v_mfma_f32_16x16x32_bf16 v[84:87], v[186:189], v[234:237], v[84:87]
	v_mfma_f32_16x16x32_bf16 v[36:39], v[152:155], v[214:217], v[36:39]
	v_mfma_f32_16x16x32_bf16 v[24:27], v[190:193], v[214:217], v[24:27]
	v_mfma_f32_16x16x32_bf16 v[40:43], v[152:155], v[222:225], v[40:43]
	v_mfma_f32_16x16x32_bf16 v[20:23], v[190:193], v[222:225], v[20:23]
	v_mfma_f32_16x16x32_bf16 v[100:103], v[152:155], v[230:233], v[100:103]
	v_mfma_f32_16x16x32_bf16 v[88:91], v[190:193], v[230:233], v[88:91]
	v_mfma_f32_16x16x32_bf16 v[104:107], v[152:155], v[238:241], v[104:107]
	v_mfma_f32_16x16x32_bf16 v[84:87], v[190:193], v[238:241], v[84:87]
	s_setprio 0
	s_setprio 1
	v_mfma_f32_16x16x32_bf16 v[16:19], v[194:197], v[210:213], v[16:19]
	v_mfma_f32_16x16x32_bf16 v[8:11], v[202:205], v[210:213], v[8:11]
	v_mfma_f32_16x16x32_bf16 v[12:15], v[194:197], v[218:221], v[12:15]
	v_mfma_f32_16x16x32_bf16 v[4:7], v[202:205], v[218:221], v[4:7]
	v_mfma_f32_16x16x32_bf16 v[52:55], v[194:197], v[226:229], v[52:55]
	v_mfma_f32_16x16x32_bf16 v[32:35], v[202:205], v[226:229], v[32:35]
	v_mfma_f32_16x16x32_bf16 v[48:51], v[194:197], v[234:237], v[48:51]
	v_mfma_f32_16x16x32_bf16 v[28:31], v[202:205], v[234:237], v[28:31]
	v_mfma_f32_16x16x32_bf16 v[16:19], v[198:201], v[214:217], v[16:19]
	v_mfma_f32_16x16x32_bf16 v[8:11], v[206:209], v[214:217], v[8:11]
	v_mfma_f32_16x16x32_bf16 v[12:15], v[198:201], v[222:225], v[12:15]
	v_mfma_f32_16x16x32_bf16 v[4:7], v[206:209], v[222:225], v[4:7]
	v_mfma_f32_16x16x32_bf16 v[52:55], v[198:201], v[230:233], v[52:55]
	v_mfma_f32_16x16x32_bf16 v[32:35], v[206:209], v[230:233], v[32:35]
	v_mfma_f32_16x16x32_bf16 v[48:51], v[198:201], v[238:241], v[48:51]
	v_mfma_f32_16x16x32_bf16 v[28:31], v[206:209], v[238:241], v[28:31]
	s_setprio 0
	s_barrier
	s_add_i32 s28, s67, s9
	v_lshl_add_u64 v[168:169], s[30:31], 0, v[2:3]
	s_mov_b32 m0, s28
	ds_read_b128 v[210:213], v147 offset:16384
	ds_read_b128 v[214:217], v147 offset:17408
	ds_read_b128 v[218:221], v147 offset:18432
	ds_read_b128 v[222:225], v147 offset:19456
	ds_read_b128 v[226:229], v147 offset:20480
	ds_read_b128 v[230:233], v147 offset:21504
	ds_read_b128 v[234:237], v147 offset:22528
	ds_read_b128 v[238:241], v147 offset:23552
	global_load_lds_dwordx4 v[168:169], off
	v_lshl_add_u64 v[176:177], s[30:31], 0, v[132:133]
	s_add_i32 m0, s28, 0x2000
	s_add_i32 s28, s68, s9
	global_load_lds_dwordx4 v[176:177], off
	v_lshl_add_u64 v[178:179], s[30:31], 0, v[134:135]
	s_mov_b32 m0, s28
	v_lshl_add_u64 v[242:243], s[30:31], 0, v[0:1]
	global_load_lds_dwordx4 v[178:179], off
	s_add_i32 m0, s28, 0x2000
	v_lshl_add_u64 v[244:245], s[58:59], 0, v[2:3]
	global_load_lds_dwordx4 v[242:243], off
	s_mov_b32 m0, s10
	v_lshl_add_u64 v[246:247], s[58:59], 0, v[132:133]
	global_load_lds_dwordx4 v[244:245], off
	s_mov_b32 m0, s11
	s_nop 0
	global_load_lds_dwordx4 v[246:247], off
	s_waitcnt vmcnt(8)
	s_waitcnt lgkmcnt(0)
	v_mfma_f32_16x16x32_bf16 v[128:131], v[148:151], v[210:213], v[128:131]
	v_mfma_f32_16x16x32_bf16 v[124:127], v[186:189], v[210:213], v[124:127]
	v_mfma_f32_16x16x32_bf16 v[120:123], v[148:151], v[218:221], v[120:123]
	v_mfma_f32_16x16x32_bf16 v[116:119], v[186:189], v[218:221], v[116:119]
	s_barrier
	s_setprio 1
	s_waitcnt lgkmcnt(0)
	v_mfma_f32_16x16x32_bf16 v[80:83], v[148:151], v[226:229], v[80:83]
	v_mfma_f32_16x16x32_bf16 v[76:79], v[186:189], v[226:229], v[76:79]
	v_mfma_f32_16x16x32_bf16 v[72:75], v[148:151], v[234:237], v[72:75]
	v_mfma_f32_16x16x32_bf16 v[68:71], v[186:189], v[234:237], v[68:71]
	v_mfma_f32_16x16x32_bf16 v[128:131], v[152:155], v[214:217], v[128:131]
	v_mfma_f32_16x16x32_bf16 v[124:127], v[190:193], v[214:217], v[124:127]
	v_mfma_f32_16x16x32_bf16 v[120:123], v[152:155], v[222:225], v[120:123]
	v_mfma_f32_16x16x32_bf16 v[116:119], v[190:193], v[222:225], v[116:119]
	v_mfma_f32_16x16x32_bf16 v[80:83], v[152:155], v[230:233], v[80:83]
	v_mfma_f32_16x16x32_bf16 v[76:79], v[190:193], v[230:233], v[76:79]
	v_mfma_f32_16x16x32_bf16 v[72:75], v[152:155], v[238:241], v[72:75]
	v_mfma_f32_16x16x32_bf16 v[68:71], v[190:193], v[238:241], v[68:71]
	s_setprio 0
	s_setprio 1
	v_mfma_f32_16x16x32_bf16 v[112:115], v[194:197], v[210:213], v[112:115]
	v_mfma_f32_16x16x32_bf16 v[96:99], v[202:205], v[210:213], v[96:99]
	v_mfma_f32_16x16x32_bf16 v[108:111], v[194:197], v[218:221], v[108:111]
	v_mfma_f32_16x16x32_bf16 v[92:95], v[202:205], v[218:221], v[92:95]
	v_mfma_f32_16x16x32_bf16 v[64:67], v[194:197], v[226:229], v[64:67]
	v_mfma_f32_16x16x32_bf16 v[60:63], v[202:205], v[226:229], v[60:63]
	v_mfma_f32_16x16x32_bf16 v[56:59], v[194:197], v[234:237], v[56:59]
	v_mfma_f32_16x16x32_bf16 v[44:47], v[202:205], v[234:237], v[44:47]
	v_mfma_f32_16x16x32_bf16 v[112:115], v[198:201], v[214:217], v[112:115]
	v_mfma_f32_16x16x32_bf16 v[96:99], v[206:209], v[214:217], v[96:99]
	v_mfma_f32_16x16x32_bf16 v[108:111], v[198:201], v[222:225], v[108:111]
	v_mfma_f32_16x16x32_bf16 v[92:95], v[206:209], v[222:225], v[92:95]
	v_mfma_f32_16x16x32_bf16 v[64:67], v[198:201], v[230:233], v[64:67]
	v_mfma_f32_16x16x32_bf16 v[60:63], v[206:209], v[230:233], v[60:63]
	v_mfma_f32_16x16x32_bf16 v[56:59], v[198:201], v[238:241], v[56:59]
	v_mfma_f32_16x16x32_bf16 v[44:47], v[206:209], v[238:241], v[44:47]
	s_setprio 0
	s_barrier
	v_add_u32_e32 v157, s82, v146
	ds_read_b128 v[148:151], v157
	ds_read_b128 v[152:155], v157 offset:1024
	ds_read_b128 v[186:189], v157 offset:2048
	ds_read_b128 v[190:193], v157 offset:3072
	v_add_u32_e32 v157, s62, v146
	ds_read_b128 v[194:197], v157
	ds_read_b128 v[198:201], v157 offset:1024
	ds_read_b128 v[202:205], v157 offset:2048
	ds_read_b128 v[206:209], v157 offset:3072
	s_add_u32 s30, s58, 0x40000
	s_addc_u32 s31, s59, 0
	s_mov_b32 m0, s12
	v_lshl_add_u64 v[248:249], s[30:31], 0, v[2:3]
	ds_read_b128 v[210:213], v147 offset:32768
	ds_read_b128 v[214:217], v147 offset:33792
	ds_read_b128 v[218:221], v147 offset:34816
	ds_read_b128 v[222:225], v147 offset:35840
	ds_read_b128 v[226:229], v147 offset:36864
	ds_read_b128 v[230:233], v147 offset:37888
	ds_read_b128 v[234:237], v147 offset:38912
	ds_read_b128 v[238:241], v147 offset:39936
	global_load_lds_dwordx4 v[248:249], off
	v_lshl_add_u64 v[248:249], s[30:31], 0, v[132:133]
	s_mov_b32 m0, s13
	s_nop 0
	global_load_lds_dwordx4 v[248:249], off
	s_waitcnt vmcnt(8)
	s_waitcnt lgkmcnt(0)
	v_mfma_f32_16x16x32_bf16 v[36:39], v[148:151], v[210:213], v[36:39]
	v_mfma_f32_16x16x32_bf16 v[24:27], v[186:189], v[210:213], v[24:27]
	v_mfma_f32_16x16x32_bf16 v[40:43], v[148:151], v[218:221], v[40:43]
	v_mfma_f32_16x16x32_bf16 v[20:23], v[186:189], v[218:221], v[20:23]
	s_barrier
	s_setprio 1
	s_waitcnt lgkmcnt(0)
	v_mfma_f32_16x16x32_bf16 v[100:103], v[148:151], v[226:229], v[100:103]
	v_mfma_f32_16x16x32_bf16 v[88:91], v[186:189], v[226:229], v[88:91]
	v_mfma_f32_16x16x32_bf16 v[104:107], v[148:151], v[234:237], v[104:107]
	v_mfma_f32_16x16x32_bf16 v[84:87], v[186:189], v[234:237], v[84:87]
	v_mfma_f32_16x16x32_bf16 v[36:39], v[152:155], v[214:217], v[36:39]
	v_mfma_f32_16x16x32_bf16 v[24:27], v[190:193], v[214:217], v[24:27]
	v_mfma_f32_16x16x32_bf16 v[40:43], v[152:155], v[222:225], v[40:43]
	v_mfma_f32_16x16x32_bf16 v[20:23], v[190:193], v[222:225], v[20:23]
	v_mfma_f32_16x16x32_bf16 v[100:103], v[152:155], v[230:233], v[100:103]
	v_mfma_f32_16x16x32_bf16 v[88:91], v[190:193], v[230:233], v[88:91]
	v_mfma_f32_16x16x32_bf16 v[104:107], v[152:155], v[238:241], v[104:107]
	v_mfma_f32_16x16x32_bf16 v[84:87], v[190:193], v[238:241], v[84:87]
	s_setprio 0
	s_setprio 1
	v_mfma_f32_16x16x32_bf16 v[16:19], v[194:197], v[210:213], v[16:19]
	v_mfma_f32_16x16x32_bf16 v[8:11], v[202:205], v[210:213], v[8:11]
	v_mfma_f32_16x16x32_bf16 v[12:15], v[194:197], v[218:221], v[12:15]
	v_mfma_f32_16x16x32_bf16 v[4:7], v[202:205], v[218:221], v[4:7]
	v_mfma_f32_16x16x32_bf16 v[52:55], v[194:197], v[226:229], v[52:55]
	v_mfma_f32_16x16x32_bf16 v[32:35], v[202:205], v[226:229], v[32:35]
	v_mfma_f32_16x16x32_bf16 v[48:51], v[194:197], v[234:237], v[48:51]
	v_mfma_f32_16x16x32_bf16 v[28:31], v[202:205], v[234:237], v[28:31]
	v_mfma_f32_16x16x32_bf16 v[16:19], v[198:201], v[214:217], v[16:19]
	v_mfma_f32_16x16x32_bf16 v[8:11], v[206:209], v[214:217], v[8:11]
	v_mfma_f32_16x16x32_bf16 v[12:15], v[198:201], v[222:225], v[12:15]
	v_mfma_f32_16x16x32_bf16 v[4:7], v[206:209], v[222:225], v[4:7]
	v_mfma_f32_16x16x32_bf16 v[52:55], v[198:201], v[230:233], v[52:55]
	v_mfma_f32_16x16x32_bf16 v[32:35], v[206:209], v[230:233], v[32:35]
	v_mfma_f32_16x16x32_bf16 v[48:51], v[198:201], v[238:241], v[48:51]
	v_mfma_f32_16x16x32_bf16 v[28:31], v[206:209], v[238:241], v[28:31]
	s_setprio 0
	s_barrier
	s_add_i32 s28, s82, s9
	v_lshl_add_u64 v[168:169], v[168:169], 0, s[72:73]
	s_mov_b32 m0, s28
	ds_read_b128 v[210:213], v147 offset:49152
	ds_read_b128 v[214:217], v147 offset:50176
	ds_read_b128 v[218:221], v147 offset:51200
	ds_read_b128 v[222:225], v147 offset:52224
	ds_read_b128 v[226:229], v147 offset:53248
	ds_read_b128 v[230:233], v147 offset:54272
	ds_read_b128 v[234:237], v147 offset:55296
	ds_read_b128 v[238:241], v147 offset:56320
	global_load_lds_dwordx4 v[168:169], off
	v_lshl_add_u64 v[168:169], v[176:177], 0, s[72:73]
	s_add_i32 m0, s28, 0x2000
	s_add_i32 s28, s62, s9
	global_load_lds_dwordx4 v[168:169], off
	v_lshl_add_u64 v[168:169], v[178:179], 0, s[72:73]
	s_mov_b32 m0, s28
	s_nop 0
	global_load_lds_dwordx4 v[168:169], off
	v_lshl_add_u64 v[168:169], v[242:243], 0, s[72:73]
	s_add_i32 m0, s28, 0x2000
	s_nop 0
	global_load_lds_dwordx4 v[168:169], off
	v_lshl_add_u64 v[168:169], v[244:245], 0, s[72:73]
	s_mov_b32 m0, s15
	s_nop 0
	global_load_lds_dwordx4 v[168:169], off
	v_lshl_add_u64 v[168:169], v[246:247], 0, s[72:73]
	s_mov_b32 m0, s16
	s_nop 0
	global_load_lds_dwordx4 v[168:169], off
	s_waitcnt vmcnt(8)
	s_waitcnt lgkmcnt(0)
	v_mfma_f32_16x16x32_bf16 v[128:131], v[148:151], v[210:213], v[128:131]
	v_mfma_f32_16x16x32_bf16 v[124:127], v[186:189], v[210:213], v[124:127]
	v_mfma_f32_16x16x32_bf16 v[120:123], v[148:151], v[218:221], v[120:123]
	v_mfma_f32_16x16x32_bf16 v[116:119], v[186:189], v[218:221], v[116:119]
	s_barrier
	s_setprio 1
	s_waitcnt lgkmcnt(0)
	v_mfma_f32_16x16x32_bf16 v[80:83], v[148:151], v[226:229], v[80:83]
	v_mfma_f32_16x16x32_bf16 v[76:79], v[186:189], v[226:229], v[76:79]
	v_mfma_f32_16x16x32_bf16 v[72:75], v[148:151], v[234:237], v[72:75]
	v_mfma_f32_16x16x32_bf16 v[68:71], v[186:189], v[234:237], v[68:71]
	v_mfma_f32_16x16x32_bf16 v[128:131], v[152:155], v[214:217], v[128:131]
	v_mfma_f32_16x16x32_bf16 v[124:127], v[190:193], v[214:217], v[124:127]
	v_mfma_f32_16x16x32_bf16 v[120:123], v[152:155], v[222:225], v[120:123]
	v_mfma_f32_16x16x32_bf16 v[116:119], v[190:193], v[222:225], v[116:119]
	v_mfma_f32_16x16x32_bf16 v[80:83], v[152:155], v[230:233], v[80:83]
	v_mfma_f32_16x16x32_bf16 v[76:79], v[190:193], v[230:233], v[76:79]
	v_mfma_f32_16x16x32_bf16 v[72:75], v[152:155], v[238:241], v[72:75]
	v_mfma_f32_16x16x32_bf16 v[68:71], v[190:193], v[238:241], v[68:71]
	s_setprio 0
	s_setprio 1
	v_mfma_f32_16x16x32_bf16 v[112:115], v[194:197], v[210:213], v[112:115]
	v_mfma_f32_16x16x32_bf16 v[96:99], v[202:205], v[210:213], v[96:99]
	v_mfma_f32_16x16x32_bf16 v[108:111], v[194:197], v[218:221], v[108:111]
	v_mfma_f32_16x16x32_bf16 v[92:95], v[202:205], v[218:221], v[92:95]
	v_mfma_f32_16x16x32_bf16 v[64:67], v[194:197], v[226:229], v[64:67]
	v_mfma_f32_16x16x32_bf16 v[60:63], v[202:205], v[226:229], v[60:63]
	v_mfma_f32_16x16x32_bf16 v[56:59], v[194:197], v[234:237], v[56:59]
	v_mfma_f32_16x16x32_bf16 v[44:47], v[202:205], v[234:237], v[44:47]
	v_mfma_f32_16x16x32_bf16 v[112:115], v[198:201], v[214:217], v[112:115]
	v_mfma_f32_16x16x32_bf16 v[96:99], v[206:209], v[214:217], v[96:99]
	v_mfma_f32_16x16x32_bf16 v[108:111], v[198:201], v[222:225], v[108:111]
	v_mfma_f32_16x16x32_bf16 v[92:95], v[206:209], v[222:225], v[92:95]
	v_mfma_f32_16x16x32_bf16 v[64:67], v[198:201], v[230:233], v[64:67]
	v_mfma_f32_16x16x32_bf16 v[60:63], v[206:209], v[230:233], v[60:63]
	v_mfma_f32_16x16x32_bf16 v[56:59], v[198:201], v[238:241], v[56:59]
	v_mfma_f32_16x16x32_bf16 v[44:47], v[206:209], v[238:241], v[44:47]
	s_setprio 0
	s_barrier
	s_add_i32 s27, s27, 2
	s_add_u32 vcc_lo, vcc_lo, 0x100
	s_addc_u32 vcc_hi, vcc_hi, 0
	s_cmp_gt_u32 s27, 13
	s_cbranch_scc0 .LBB0_1201
	s_and_b64 vcc, exec, s[48:49]
	s_cbranch_vccz .LBB0_1204
	s_barrier
